# WS_GATE stored in MFMA-fragment order by P0 so each lru_m1 gate-weight fragment load is 1 KiB contiguous
# baseline (speedup 1.0000x reference)
; #define LAS __attribute__((address_space(3)))
; __device__ __forceinline__ void ld8bf(const bf16_t* p, float (&o)[8]) { unpack8(*(const u32x4*)p, o); }
; __device__ __forceinline__ const float* in_ptr(const Args& a, int i) { asm volatile("" : "+s"(i)); return a.in[i]; }
; __device__ __forceinline__ void w_lru_m1(const Args& a, int l, unsigned char* ws, const bf16_t* proj, bf16_t* y, LAS unsigned char* wl, int b, int ck_, int h, int lane) {
;     LAS float* xcf = (LAS float*)wl;
;     const int row0 = b * SEQ + 64 * ck_, lo = lane & 15, fq = lane >> 4;
;     const float* cw = in_ptr(a, I_LCW) + (size_t)l * 4 * 512; const float* cbias = in_ptr(a, I_LCB) + l * 512;
;     const bf16_t* gwt = (const bf16_t*)(ws + WS_GATE) + (size_t)l * 65536;
;     const bf16_t* waT = gwt + h * 4096; const bf16_t* wxT = gwt + 32768 + h * 4096;
;     const float* ba = in_ptr(a, I_BA) + l * 512 + 64 * h; const float* bx = in_ptr(a, I_BX) + l * 512 + 64 * h; const float* lam = in_ptr(a, I_LAM) + l * 512 + 64 * h;
;     bf16x8 nWa[2], nWx[2]; f32x4 nba, nbx, nlam;
; #pragma unroll
;     for (int kk = 0; kk < 2; ++kk) { nWa[kk] = *(const bf16x8*)(waT + lo * 64 + 32 * kk + 8 * fq); nWx[kk] = *(const bf16x8*)(wxT + lo * 64 + 32 * kk + 8 * fq); }
;     nba = *(const f32x4*)(ba + 4 * fq); nbx = *(const f32x4*)(bx + 4 * fq); nlam = *(const f32x4*)(lam + 4 * fq);
;     bf16x8 Xf[4][2];
; #pragma unroll
;     for (int kk = 0; kk < 2; ++kk) { const int ch0 = 64 * h + 32 * kk + 8 * fq; float w[4][8], bs[8];
; #pragma unroll
;         for (int j = 0; j < 8; ++j) { bs[j] = cbias[ch0 + j];
; #pragma unroll
;             for (int k = 0; k < 4; ++k) w[k][j] = cw[k * 512 + ch0 + j]; }
; #pragma unroll
;         for (int tb = 0; tb < 4; ++tb) { const int tok = 16 * tb + lo, t = 64 * ck_ + tok; float s[8];
; #pragma unroll
;             for (int j = 0; j < 8; ++j) s[j] = bs[j];
; #pragma unroll
;             for (int k = 0; k < 4; ++k) { const int tt = t - 3 + k; float x[8];
;                 ld8bf(proj + (size_t)(b * SEQ + (tt >= 0 ? tt : 0)) * NIN + C_LX + ch0, x);
.LBB0_520:
	s_lshr_b32 s20, s24, 8
	s_lshr_b32 s21, s24, 9
	s_add_i32 s20, s20, s24
	s_and_b32 s21, s21, 12
	s_add_i32 s20, s20, s21
	s_and_b32 s91, s20, 15
	s_cmp_gt_u32 s91, 7
	s_cbranch_scc1 .LBB0_519
	s_ashr_i32 s20, s24, 31
	s_ashr_i32 s90, s24, 4
	s_lshr_b32 s20, s20, 25
	s_add_i32 s27, s90, s20
	s_and_b32 s20, s27, 0xffffff80
	v_mov_b32_e32 v122, v144
	s_mov_b32 s34, 3
	s_sub_i32 s46, s90, s20
	s_ashr_i32 s35, s34, 31
	s_lshl_b32 s20, s46, 6
	s_lshl_b64 s[34:35], s[34:35], 3
	s_add_u32 s34, s0, s34
	s_addc_u32 s35, s1, s35
	s_load_dwordx2 s[40:41], s[34:35], 0x0
	s_mov_b32 s34, 4
	s_ashr_i32 s35, s34, 31
	s_lshl_b64 s[34:35], s[34:35], 3
	s_add_u32 s34, s0, s34
	s_addc_u32 s35, s1, s35
	s_lshl_b32 s21, s91, 13
	s_add_u32 s92, s2, s21
	s_addc_u32 s93, s3, 0
	s_load_dwordx2 s[42:43], s[34:35], 0x0
	s_add_u32 s34, s68, s21
	s_mov_b32 s44, 6
	s_addc_u32 s35, s70, 0
	s_ashr_i32 s45, s44, 31
	s_lshl_b64 s[44:45], s[44:45], 3
	s_add_u32 s44, s0, s44
	s_addc_u32 s45, s1, s45
	s_waitcnt lgkmcnt(0)
	s_mov_b32 s48, 8
	s_load_dwordx2 s[44:45], s[44:45], 0x0
	s_ashr_i32 s49, s48, 31
	s_lshl_b32 s21, s91, 6
	s_lshl_b64 s[48:49], s[48:49], 3
	s_add_u32 s48, s0, s48
	s_addc_u32 s49, s1, s49
	s_load_dwordx2 s[48:49], s[48:49], 0x0
	v_ashrrev_i32_e32 v8, 4, v122
	v_and_b32_e32 v136, 15, v122
	v_lshlrev_b32_e32 v4, 3, v8
	v_lshlrev_b32_e32 v2, 4, v136
	s_waitcnt lgkmcnt(0)
	s_add_u32 s47, s48, s88
	s_mov_b32 s48, 9
	s_addc_u32 s50, s49, s89
	s_ashr_i32 s49, s48, 31
	s_lshl_b64 s[48:49], s[48:49], 3
	s_add_u32 s48, s0, s48
	s_addc_u32 s49, s1, s49
	s_add_u32 s48, s78, 0x3b00000
	s_addc_u32 s49, s79, 0x0
	v_ashrrev_i32_e32 v5, 31, v4
	v_lshl_add_u64 v[0:1], s[92:93], 0, v[2:3]
	v_lshlrev_b64 v[100:101], 5, v[4:5]
	v_lshl_add_u64 v[0:1], v[0:1], 0, v[100:101]
	s_waitcnt lgkmcnt(0)
	s_add_u32 s51, s48, s88
	s_addc_u32 s52, s49, s89
	s_lshl_b32 s27, s27, 6
	s_and_b32 s27, s27, 0xffffe000
	s_add_u32 s48, s40, s96
	s_addc_u32 s49, s41, s97
	s_add_u32 s42, s42, s88
	s_addc_u32 s43, s43, s89
	s_add_u32 s40, s44, s88
	s_addc_u32 s41, s45, s89
	s_lshl_b32 s53, s91, 8
	s_add_u32 s40, s40, s53
	v_lshl_add_u64 v[6:7], s[34:35], 0, v[2:3]
	s_addc_u32 s41, s41, 0
	v_lshl_add_u64 v[6:7], v[6:7], 0, v[100:101]
	flat_load_dwordx4 v[52:55], v[0:1]
	flat_load_dwordx4 v[56:59], v[6:7]
	flat_load_dwordx4 v[60:63], v[0:1] offset:1024
	flat_load_dwordx4 v[64:67], v[6:7] offset:1024
	s_add_u32 s44, s47, s53
	v_lshlrev_b32_e32 v0, 2, v8
	s_addc_u32 s45, s50, 0
	v_ashrrev_i32_e32 v1, 31, v0
	s_add_u32 s50, s51, s53
	v_lshlrev_b64 v[6:7], 2, v[0:1]
	s_addc_u32 s51, s52, 0
	v_lshl_add_u64 v[108:109], s[40:41], 0, v[6:7]
	s_add_i32 s40, s20, -3
	v_add_u32_e32 v78, s21, v4
	v_lshl_add_u64 v[110:111], s[44:45], 0, v[6:7]
	v_lshl_add_u64 v[112:113], s[50:51], 0, v[6:7]
	v_ashrrev_i32_e32 v79, 31, v78
	v_add_u32_e32 v6, s40, v136
	v_lshlrev_b64 v[4:5], 2, v[78:79]
	v_cmp_lt_i32_e64 s[50:51], -1, v6
	v_lshl_add_u64 v[76:77], s[42:43], 0, v[4:5]
	v_lshl_add_u64 v[86:87], s[48:49], 0, v[4:5]
	s_mov_b64 s[42:43], 0x1000
	v_cndmask_b32_e64 v4, 0, v6, s[50:51]
	v_lshl_add_u64 v[36:37], v[86:87], 0, s[42:43]
	s_mov_b64 s[42:43], 0x1800
	v_lshl_add_u64 v[80:81], v[78:79], 1, s[8:9]
	v_add_u32_e32 v79, s27, v4
	v_lshl_add_u64 v[82:83], v[86:87], 0, s[42:43]
	v_max_i32_e32 v4, -1, v6
	s_or_b32 s80, s27, 1
	v_add_u32_e32 v92, s80, v4
	v_max_i32_e32 v4, -2, v6
	s_or_b32 s81, s27, 2
	v_add_u32_e32 v93, s81, v4
	s_cmp_gt_i32 s46, -1
	v_or_b32_e32 v4, s20, v136
	s_cselect_b64 s[42:43], -1, 0
	v_cndmask_b32_e64 v4, 0, v4, s[42:43]
	v_add_u32_e32 v94, s27, v4
	global_load_dwordx4 v[48:51], v[108:109], off
	global_load_dwordx4 v[44:47], v[110:111], off
	global_load_dwordx4 v[88:91], v[112:113], off
	v_lshl_add_u32 v95, v8, 5, s6
	v_cmp_lt_i32_e64 s[48:49], -2, v6
	v_cmp_lt_i32_e64 s[44:45], -3, v6
	global_load_dwordx4 v[20:23], v[76:77], off offset:16
	s_nop 0
	global_load_dwordx4 v[4:7], v[76:77], off
	global_load_dwordx4 v[24:27], v[86:87], off offset:16
	global_load_dwordx4 v[32:35], v[86:87], off
	global_load_dwordx4 v[28:31], v[86:87], off offset:2064
	global_load_dwordx4 v[40:43], v[86:87], off offset:2048
	v_add_co_u32_e32 v96, vcc, s73, v86
	v_mad_u32_u24 v121, v136, s76, v95
	s_nop 0
	v_addc_co_u32_e32 v97, vcc, 0, v87, vcc
	global_load_dwordx4 v[68:71], v[96:97], off
	s_nop 0
	global_load_dwordx4 v[36:39], v[36:37], off offset:16
	s_nop 0
	global_load_dwordx4 v[104:107], v[96:97], off offset:2048
	global_load_dwordx4 v[114:117], v[82:83], off offset:16
	v_add_u32_e32 v186, s20, v136
	v_add_u32_e32 v187, -16, v186
	v_max_i32_e32 v187, 0, v187
	v_add_u32_e32 v187, s27, v187
	v_add_u32_e32 v186, s27, v186
	v_mad_i64_i32 v[188:189], s[46:47], v187, s72, v[80:81]
	global_load_dwordx4 v[222:225], v[188:189], off
	global_load_dwordx4 v[242:245], v[188:189], off offset:64
	v_mad_i64_i32 v[188:189], s[46:47], v186, s72, v[80:81]
	global_load_dwordx4 v[226:229], v[188:189], off
	global_load_dwordx4 v[246:249], v[188:189], off offset:64
	v_add_u32_e32 v187, 16, v186
	v_mad_i64_i32 v[188:189], s[46:47], v187, s72, v[80:81]
	global_load_dwordx4 v[230:233], v[188:189], off
	global_load_dwordx4 v[250:253], v[188:189], off offset:64
	v_add_u32_e32 v187, 32, v186
	v_mad_i64_i32 v[188:189], s[46:47], v187, s72, v[80:81]
	global_load_dwordx4 v[234:237], v[188:189], off
	global_load_dwordx4 v[190:193], v[188:189], off offset:64
	v_add_u32_e32 v187, 48, v186
	v_mad_i64_i32 v[188:189], s[46:47], v187, s72, v[80:81]
	global_load_dwordx4 v[238:241], v[188:189], off
	global_load_dwordx4 v[194:197], v[188:189], off offset:64
	v_or_b32_e32 v140, 16, v136
	v_or_b32_e32 v139, 32, v136
	v_or_b32_e32 v137, 48, v136
	v_mov_b64_e32 v[102:103], s[8:9]
	s_waitcnt vmcnt(0) lgkmcnt(0)
; __device__ __forceinline__ void ld8bf(const bf16_t* p, float (&o)[8]) { unpack8(*(const u32x4*)p, o); }
; __device__ __forceinline__ bf16x8 pack_frag(const float (&v)[8]) { return __builtin_bit_cast(bf16x8, pack8(v)); }
; __device__ __forceinline__ void w_lru_m1(const Args& a, int l, unsigned char* ws, const bf16_t* proj, bf16_t* y, LAS unsigned char* wl, int b, int ck_, int h, int lane) {
;     ...
;     for (int kk = 0; kk < 2; ++kk) { const int ch0 = 64 * h + 32 * kk + 8 * fq; float w[4][8], bs[8];
; #pragma unroll
;         for (int j = 0; j < 8; ++j) { bs[j] = cbias[ch0 + j];
; #pragma unroll
;             for (int k = 0; k < 4; ++k) w[k][j] = cw[k * 512 + ch0 + j]; }
; #pragma unroll
;         for (int tb = 0; tb < 4; ++tb) { const int tok = 16 * tb + lo, t = 64 * ck_ + tok; float s[8];
; #pragma unroll
;             for (int j = 0; j < 8; ++j) s[j] = bs[j];
; #pragma unroll
;             for (int k = 0; k < 4; ++k) { const int tt = t - 3 + k; float x[8];
;                 ld8bf(proj + (size_t)(b * SEQ + (tt >= 0 ? tt : 0)) * NIN + C_LX + ch0, x);
; #pragma unroll
;                 for (int j = 0; j < 8; ++j) s[j] += (tt >= 0 ? w[k][j] : 0.f) * x[j]; }
;             Xf[tb][kk] = pack_frag(s);
; #pragma unroll
;             for (int j = 0; j < 8; ++j) xcf[tok * 65 + 32 * kk + 8 * fq + j] = s[j]; }
	v_mov_b32_dpp v72, v222 row_ror:3 row_mask:0xf bank_mask:0xf
	v_mov_b32_dpp v73, v223 row_ror:3 row_mask:0xf bank_mask:0xf
	v_mov_b32_dpp v74, v224 row_ror:3 row_mask:0xf bank_mask:0xf
	v_mov_b32_dpp v75, v225 row_ror:3 row_mask:0xf bank_mask:0xf
	v_mov_b32_dpp v72, v226 row_shr:3 row_mask:0xf bank_mask:0xf
	v_mov_b32_dpp v73, v227 row_shr:3 row_mask:0xf bank_mask:0xf
	v_mov_b32_dpp v74, v228 row_shr:3 row_mask:0xf bank_mask:0xf
	v_mov_b32_dpp v75, v229 row_shr:3 row_mask:0xf bank_mask:0xf
	v_mov_b32_dpp v16, v222 row_ror:2 row_mask:0xf bank_mask:0xf
	v_mov_b32_dpp v17, v223 row_ror:2 row_mask:0xf bank_mask:0xf
	v_mov_b32_dpp v18, v224 row_ror:2 row_mask:0xf bank_mask:0xf
	v_mov_b32_dpp v19, v225 row_ror:2 row_mask:0xf bank_mask:0xf
	v_mov_b32_dpp v16, v226 row_shr:2 row_mask:0xf bank_mask:0xf
	v_mov_b32_dpp v17, v227 row_shr:2 row_mask:0xf bank_mask:0xf
	v_mov_b32_dpp v18, v228 row_shr:2 row_mask:0xf bank_mask:0xf
	v_mov_b32_dpp v19, v229 row_shr:2 row_mask:0xf bank_mask:0xf
	v_mov_b32_dpp v12, v222 row_ror:1 row_mask:0xf bank_mask:0xf
	v_mov_b32_dpp v13, v223 row_ror:1 row_mask:0xf bank_mask:0xf
	v_mov_b32_dpp v14, v224 row_ror:1 row_mask:0xf bank_mask:0xf
	v_mov_b32_dpp v15, v225 row_ror:1 row_mask:0xf bank_mask:0xf
	v_mov_b32_dpp v12, v226 row_shr:1 row_mask:0xf bank_mask:0xf
	v_mov_b32_dpp v13, v227 row_shr:1 row_mask:0xf bank_mask:0xf
	v_mov_b32_dpp v14, v228 row_shr:1 row_mask:0xf bank_mask:0xf
	v_mov_b32_dpp v15, v229 row_shr:1 row_mask:0xf bank_mask:0xf
	v_mov_b64_e32 v[8:9], v[226:227]
	v_mov_b64_e32 v[10:11], v[228:229]
	v_lshlrev_b32_e32 v82, 16, v72
	v_lshlrev_b32_e32 v84, 16, v73
	v_and_b32_e32 v83, 0xffff0000, v72
	v_and_b32_e32 v85, 0xffff0000, v73
	v_cndmask_b32_e64 v73, 0, v33, s[50:51]
	v_cndmask_b32_e64 v72, 0, v32, s[50:51]
	v_cndmask_b32_e64 v99, 0, v35, s[50:51]
	v_cndmask_b32_e64 v98, 0, v34, s[50:51]
	v_pk_fma_f32 v[84:85], v[98:99], v[84:85], v[6:7]
	v_pk_fma_f32 v[72:73], v[72:73], v[82:83], v[4:5]
	v_lshlrev_b32_e32 v82, 16, v17
	v_lshlrev_b32_e32 v98, 16, v16
	v_and_b32_e32 v83, 0xffff0000, v17
	v_and_b32_e32 v99, 0xffff0000, v16
	v_cndmask_b32_e64 v17, 0, v43, s[48:49]
	v_cndmask_b32_e64 v16, 0, v42, s[48:49]
	v_cndmask_b32_e64 v119, 0, v41, s[48:49]
	v_cndmask_b32_e64 v118, 0, v40, s[48:49]
	v_pk_fma_f32 v[72:73], v[118:119], v[98:99], v[72:73]
	v_pk_fma_f32 v[16:17], v[16:17], v[82:83], v[84:85]
	v_lshlrev_b32_e32 v82, 16, v12
	v_lshlrev_b32_e32 v84, 16, v13
	v_and_b32_e32 v83, 0xffff0000, v12
	v_and_b32_e32 v85, 0xffff0000, v13
	v_cndmask_b32_e64 v13, 0, v69, s[44:45]
	v_cndmask_b32_e64 v12, 0, v68, s[44:45]
	v_cndmask_b32_e64 v99, 0, v71, s[44:45]
	v_cndmask_b32_e64 v98, 0, v70, s[44:45]
	v_pk_fma_f32 v[16:17], v[98:99], v[84:85], v[16:17]
	v_pk_fma_f32 v[12:13], v[12:13], v[82:83], v[72:73]
	v_lshlrev_b32_e32 v84, 16, v9
	v_lshlrev_b32_e32 v98, 16, v8
	v_and_b32_e32 v85, 0xffff0000, v9
	v_and_b32_e32 v99, 0xffff0000, v8
	v_cndmask_b32_e64 v73, 0, v107, s[42:43]
	v_cndmask_b32_e64 v72, 0, v106, s[42:43]
	v_cndmask_b32_e64 v83, 0, v105, s[42:43]
	v_cndmask_b32_e64 v82, 0, v104, s[42:43]
	v_pk_fma_f32 v[8:9], v[82:83], v[98:99], v[12:13]
	v_pk_fma_f32 v[12:13], v[72:73], v[84:85], v[16:17]
	v_cvt_pk_bf16_f32 v16, v8, v9
	v_cvt_pk_bf16_f32 v17, v12, v13
	ds_write2_b32 v121, v12, v13 offset0:2 offset1:3
	ds_write2_b32 v121, v8, v9 offset1:1
	v_lshlrev_b32_e32 v8, 16, v74
	v_lshlrev_b32_e32 v12, 16, v75
	v_and_b32_e32 v9, 0xffff0000, v74
	v_and_b32_e32 v13, 0xffff0000, v75
	v_cndmask_b32_e64 v75, 0, v25, s[50:51]
	v_cndmask_b32_e64 v74, 0, v24, s[50:51]
	v_cndmask_b32_e64 v85, 0, v27, s[50:51]
	v_cndmask_b32_e64 v84, 0, v26, s[50:51]
	v_pk_fma_f32 v[12:13], v[84:85], v[12:13], v[22:23]
	v_pk_fma_f32 v[8:9], v[74:75], v[8:9], v[20:21]
	v_lshlrev_b32_e32 v74, 16, v19
	v_lshlrev_b32_e32 v84, 16, v18
	v_and_b32_e32 v75, 0xffff0000, v19
	v_and_b32_e32 v85, 0xffff0000, v18
	v_cndmask_b32_e64 v19, 0, v31, s[48:49]
	v_cndmask_b32_e64 v18, 0, v30, s[48:49]
	v_cndmask_b32_e64 v99, 0, v29, s[48:49]
	v_cndmask_b32_e64 v98, 0, v28, s[48:49]
	v_pk_fma_f32 v[8:9], v[98:99], v[84:85], v[8:9]
	v_pk_fma_f32 v[12:13], v[18:19], v[74:75], v[12:13]
	v_lshlrev_b32_e32 v18, 16, v14
	v_lshlrev_b32_e32 v74, 16, v15
	v_and_b32_e32 v19, 0xffff0000, v14
	v_and_b32_e32 v75, 0xffff0000, v15
	v_cndmask_b32_e64 v15, 0, v37, s[44:45]
	v_cndmask_b32_e64 v14, 0, v36, s[44:45]
	v_cndmask_b32_e64 v85, 0, v39, s[44:45]
	v_cndmask_b32_e64 v84, 0, v38, s[44:45]
	v_pk_fma_f32 v[12:13], v[84:85], v[74:75], v[12:13]
	v_pk_fma_f32 v[8:9], v[14:15], v[18:19], v[8:9]
	v_lshlrev_b32_e32 v14, 16, v11
	v_lshlrev_b32_e32 v18, 16, v10
	v_and_b32_e32 v15, 0xffff0000, v11
	v_and_b32_e32 v19, 0xffff0000, v10
	v_cndmask_b32_e64 v75, 0, v117, s[42:43]
	v_cndmask_b32_e64 v74, 0, v116, s[42:43]
	v_cndmask_b32_e64 v85, 0, v115, s[42:43]
	v_cndmask_b32_e64 v84, 0, v114, s[42:43]
	v_add_u32_e32 v98, s40, v140
	v_pk_fma_f32 v[8:9], v[84:85], v[18:19], v[8:9]
	v_pk_fma_f32 v[10:11], v[74:75], v[14:15], v[12:13]
	v_cmp_lt_i32_e64 s[62:63], -1, v98
	v_cvt_pk_bf16_f32 v18, v8, v9
	ds_write2_b32 v121, v10, v11 offset0:6 offset1:7
	ds_write2_b32 v121, v8, v9 offset0:4 offset1:5
	v_cndmask_b32_e64 v8, 0, v98, s[62:63]
	v_cmp_lt_i32_e64 s[60:61], -2, v98
	v_max_i32_e32 v12, -1, v98
	v_cmp_lt_i32_e64 s[58:59], -3, v98
	v_max_i32_e32 v98, -2, v98
	v_add_u32_e32 v142, s81, v98
	v_add_u32_e32 v134, s27, v8
	v_add_u32_e32 v135, s80, v12
	v_mov_b32_dpp v104, v226 row_ror:1 row_mask:0xf bank_mask:0xf
	v_mov_b32_dpp v105, v227 row_ror:1 row_mask:0xf bank_mask:0xf
	v_mov_b32_dpp v106, v228 row_ror:1 row_mask:0xf bank_mask:0xf
	v_mov_b32_dpp v107, v229 row_ror:1 row_mask:0xf bank_mask:0xf
; __device__ __forceinline__ void ld8bf(const bf16_t* p, float (&o)[8]) { unpack8(*(const u32x4*)p, o); }
; __device__ __forceinline__ bf16x8 pack_frag(const float (&v)[8]) { return __builtin_bit_cast(bf16x8, pack8(v)); }
; __device__ __forceinline__ void w_lru_m1(const Args& a, int l, unsigned char* ws, const bf16_t* proj, bf16_t* y, LAS unsigned char* wl, int b, int ck_, int h, int lane) {
;     ...
;     for (int kk = 0; kk < 2; ++kk) { const int ch0 = 64 * h + 32 * kk + 8 * fq; float w[4][8], bs[8];
; #pragma unroll
;         for (int j = 0; j < 8; ++j) { bs[j] = cbias[ch0 + j];
; #pragma unroll
;             for (int k = 0; k < 4; ++k) w[k][j] = cw[k * 512 + ch0 + j]; }
; #pragma unroll
;         for (int tb = 0; tb < 4; ++tb) { const int tok = 16 * tb + lo, t = 64 * ck_ + tok; float s[8];
; #pragma unroll
;             for (int j = 0; j < 8; ++j) s[j] = bs[j];
; #pragma unroll
;             for (int k = 0; k < 4; ++k) { const int tt = t - 3 + k; float x[8];
;                 ld8bf(proj + (size_t)(b * SEQ + (tt >= 0 ? tt : 0)) * NIN + C_LX + ch0, x);
; #pragma unroll
;                 for (int j = 0; j < 8; ++j) s[j] += (tt >= 0 ? w[k][j] : 0.f) * x[j]; }
;             Xf[tb][kk] = pack_frag(s);
; #pragma unroll
;             for (int j = 0; j < 8; ++j) xcf[tok * 65 + 32 * kk + 8 * fq + j] = s[j]; }
	v_mov_b32_dpp v104, v230 row_shr:1 row_mask:0xf bank_mask:0xf
	v_mov_b32_dpp v105, v231 row_shr:1 row_mask:0xf bank_mask:0xf
	v_mov_b32_dpp v106, v232 row_shr:1 row_mask:0xf bank_mask:0xf
	v_mov_b32_dpp v107, v233 row_shr:1 row_mask:0xf bank_mask:0xf
	v_or_b32_e32 v98, s20, v140
	v_cvt_pk_bf16_f32 v19, v10, v11
	v_mov_b32_dpp v8, v226 row_ror:3 row_mask:0xf bank_mask:0xf
	v_mov_b32_dpp v9, v227 row_ror:3 row_mask:0xf bank_mask:0xf
	v_mov_b32_dpp v10, v228 row_ror:3 row_mask:0xf bank_mask:0xf
	v_mov_b32_dpp v11, v229 row_ror:3 row_mask:0xf bank_mask:0xf
	v_mov_b32_dpp v8, v230 row_shr:3 row_mask:0xf bank_mask:0xf
	v_mov_b32_dpp v9, v231 row_shr:3 row_mask:0xf bank_mask:0xf
	v_mov_b32_dpp v10, v232 row_shr:3 row_mask:0xf bank_mask:0xf
	v_mov_b32_dpp v11, v233 row_shr:3 row_mask:0xf bank_mask:0xf
	v_cndmask_b32_e64 v98, 0, v98, s[42:43]
	v_mov_b32_dpp v12, v226 row_ror:2 row_mask:0xf bank_mask:0xf
	v_mov_b32_dpp v13, v227 row_ror:2 row_mask:0xf bank_mask:0xf
	v_mov_b32_dpp v14, v228 row_ror:2 row_mask:0xf bank_mask:0xf
	v_mov_b32_dpp v15, v229 row_ror:2 row_mask:0xf bank_mask:0xf
	v_mov_b32_dpp v12, v230 row_shr:2 row_mask:0xf bank_mask:0xf
	v_mov_b32_dpp v13, v231 row_shr:2 row_mask:0xf bank_mask:0xf
	v_mov_b32_dpp v14, v232 row_shr:2 row_mask:0xf bank_mask:0xf
	v_mov_b32_dpp v15, v233 row_shr:2 row_mask:0xf bank_mask:0xf
	v_add_u32_e32 v143, s27, v98
	v_mov_b64_e32 v[114:115], v[230:231]
	v_mov_b64_e32 v[116:117], v[232:233]
	v_mov_b32_e32 v98, 0x1040
	v_mad_u32_u24 v123, v136, s76, v98
	v_cndmask_b32_e64 v127, 0, v35, s[62:63]
	v_cndmask_b32_e64 v126, 0, v34, s[62:63]
	v_cndmask_b32_e64 v129, 0, v41, s[60:61]
	v_cndmask_b32_e64 v128, 0, v40, s[60:61]
	v_add_u32_e32 v125, v95, v123
	s_waitcnt vmcnt(0) lgkmcnt(0)
	v_lshlrev_b32_e32 v98, 16, v8
	v_lshlrev_b32_e32 v118, 16, v9
	v_and_b32_e32 v99, 0xffff0000, v8
	v_and_b32_e32 v119, 0xffff0000, v9
	v_cndmask_b32_e64 v9, 0, v33, s[62:63]
	v_cndmask_b32_e64 v8, 0, v32, s[62:63]
	v_pk_fma_f32 v[118:119], v[126:127], v[118:119], v[6:7]
	v_pk_fma_f32 v[8:9], v[8:9], v[98:99], v[4:5]
	v_lshlrev_b32_e32 v98, 16, v13
	v_lshlrev_b32_e32 v126, 16, v12
	v_and_b32_e32 v99, 0xffff0000, v13
	v_and_b32_e32 v127, 0xffff0000, v12
	v_cndmask_b32_e64 v13, 0, v43, s[60:61]
	v_cndmask_b32_e64 v12, 0, v42, s[60:61]
	v_pk_fma_f32 v[8:9], v[128:129], v[126:127], v[8:9]
	v_pk_fma_f32 v[12:13], v[12:13], v[98:99], v[118:119]
	v_lshlrev_b32_e32 v98, 16, v104
	v_lshlrev_b32_e32 v118, 16, v105
	v_and_b32_e32 v99, 0xffff0000, v104
	v_and_b32_e32 v119, 0xffff0000, v105
	v_cndmask_b32_e64 v105, 0, v69, s[58:59]
	v_cndmask_b32_e64 v104, 0, v68, s[58:59]
	v_cndmask_b32_e64 v127, 0, v71, s[58:59]
	v_cndmask_b32_e64 v126, 0, v70, s[58:59]
	v_pk_fma_f32 v[12:13], v[126:127], v[118:119], v[12:13]
	v_pk_fma_f32 v[8:9], v[104:105], v[98:99], v[8:9]
	v_lshlrev_b32_e32 v98, 16, v115
	v_lshlrev_b32_e32 v104, 16, v114
	v_and_b32_e32 v99, 0xffff0000, v115
	v_and_b32_e32 v105, 0xffff0000, v114
	v_pk_fma_f32 v[8:9], v[82:83], v[104:105], v[8:9]
	v_pk_fma_f32 v[98:99], v[72:73], v[98:99], v[12:13]
	v_cvt_pk_bf16_f32 v12, v8, v9
	v_cvt_pk_bf16_f32 v13, v98, v99
	ds_write2_b32 v125, v98, v99 offset0:2 offset1:3
	ds_write2_b32 v125, v8, v9 offset1:1
	v_lshlrev_b32_e32 v8, 16, v10
	v_lshlrev_b32_e32 v98, 16, v11
	v_and_b32_e32 v9, 0xffff0000, v10
	v_and_b32_e32 v99, 0xffff0000, v11
	v_cndmask_b32_e64 v11, 0, v25, s[62:63]
	v_cndmask_b32_e64 v10, 0, v24, s[62:63]
	v_cndmask_b32_e64 v105, 0, v27, s[62:63]
	v_cndmask_b32_e64 v104, 0, v26, s[62:63]
	v_pk_fma_f32 v[98:99], v[104:105], v[98:99], v[22:23]
	v_pk_fma_f32 v[8:9], v[10:11], v[8:9], v[20:21]
	v_lshlrev_b32_e32 v10, 16, v15
	v_lshlrev_b32_e32 v104, 16, v14
	v_and_b32_e32 v11, 0xffff0000, v15
	v_and_b32_e32 v105, 0xffff0000, v14
	v_cndmask_b32_e64 v15, 0, v31, s[60:61]
	v_cndmask_b32_e64 v14, 0, v30, s[60:61]
	v_cndmask_b32_e64 v115, 0, v29, s[60:61]
	v_cndmask_b32_e64 v114, 0, v28, s[60:61]
	v_pk_fma_f32 v[8:9], v[114:115], v[104:105], v[8:9]
	v_pk_fma_f32 v[10:11], v[14:15], v[10:11], v[98:99]
	v_lshlrev_b32_e32 v14, 16, v106
	v_lshlrev_b32_e32 v98, 16, v107
	v_and_b32_e32 v15, 0xffff0000, v106
	v_and_b32_e32 v99, 0xffff0000, v107
	v_cndmask_b32_e64 v105, 0, v37, s[58:59]
	v_cndmask_b32_e64 v104, 0, v36, s[58:59]
	v_cndmask_b32_e64 v107, 0, v39, s[58:59]
	v_cndmask_b32_e64 v106, 0, v38, s[58:59]
	v_pk_fma_f32 v[10:11], v[106:107], v[98:99], v[10:11]
	v_pk_fma_f32 v[8:9], v[104:105], v[14:15], v[8:9]
	v_lshlrev_b32_e32 v14, 16, v117
	v_lshlrev_b32_e32 v98, 16, v116
	v_and_b32_e32 v15, 0xffff0000, v117
	v_and_b32_e32 v99, 0xffff0000, v116
	v_add_u32_e32 v114, s40, v139
	v_pk_fma_f32 v[8:9], v[84:85], v[98:99], v[8:9]
	v_pk_fma_f32 v[10:11], v[74:75], v[14:15], v[10:11]
	v_cmp_lt_i32_e64 s[56:57], -1, v114
	v_cvt_pk_bf16_f32 v14, v8, v9
	ds_write2_b32 v125, v10, v11 offset0:6 offset1:7
	ds_write2_b32 v125, v8, v9 offset0:4 offset1:5
	v_cndmask_b32_e64 v8, 0, v114, s[56:57]
	v_max_i32_e32 v98, -1, v114
	v_add_u32_e32 v130, s27, v8
	v_add_u32_e32 v131, s80, v98
	v_cvt_pk_bf16_f32 v15, v10, v11
	v_mov_b32_dpp v8, v230 row_ror:3 row_mask:0xf bank_mask:0xf
	v_mov_b32_dpp v9, v231 row_ror:3 row_mask:0xf bank_mask:0xf
	v_mov_b32_dpp v10, v232 row_ror:3 row_mask:0xf bank_mask:0xf
	v_mov_b32_dpp v11, v233 row_ror:3 row_mask:0xf bank_mask:0xf
	v_mov_b32_dpp v8, v234 row_shr:3 row_mask:0xf bank_mask:0xf
	v_mov_b32_dpp v9, v235 row_shr:3 row_mask:0xf bank_mask:0xf
	v_mov_b32_dpp v10, v236 row_shr:3 row_mask:0xf bank_mask:0xf
	v_mov_b32_dpp v11, v237 row_shr:3 row_mask:0xf bank_mask:0xf
	v_cmp_lt_i32_e64 s[54:55], -2, v114
	v_mov_b32_dpp v104, v230 row_ror:2 row_mask:0xf bank_mask:0xf
; __device__ __forceinline__ void ld8bf(const bf16_t* p, float (&o)[8]) { unpack8(*(const u32x4*)p, o); }
; __device__ __forceinline__ bf16x8 pack_frag(const float (&v)[8]) { return __builtin_bit_cast(bf16x8, pack8(v)); }
; __device__ __forceinline__ void w_lru_m1(const Args& a, int l, unsigned char* ws, const bf16_t* proj, bf16_t* y, LAS unsigned char* wl, int b, int ck_, int h, int lane) {
;     ...
;     for (int kk = 0; kk < 2; ++kk) { const int ch0 = 64 * h + 32 * kk + 8 * fq; float w[4][8], bs[8];
; #pragma unroll
;         for (int j = 0; j < 8; ++j) { bs[j] = cbias[ch0 + j];
; #pragma unroll
;             for (int k = 0; k < 4; ++k) w[k][j] = cw[k * 512 + ch0 + j]; }
; #pragma unroll
;         for (int tb = 0; tb < 4; ++tb) { const int tok = 16 * tb + lo, t = 64 * ck_ + tok; float s[8];
; #pragma unroll
;             for (int j = 0; j < 8; ++j) s[j] = bs[j];
; #pragma unroll
;             for (int k = 0; k < 4; ++k) { const int tt = t - 3 + k; float x[8];
;                 ld8bf(proj + (size_t)(b * SEQ + (tt >= 0 ? tt : 0)) * NIN + C_LX + ch0, x);
; #pragma unroll
;                 for (int j = 0; j < 8; ++j) s[j] += (tt >= 0 ? w[k][j] : 0.f) * x[j]; }
;             Xf[tb][kk] = pack_frag(s);
; #pragma unroll
;             for (int j = 0; j < 8; ++j) xcf[tok * 65 + 32 * kk + 8 * fq + j] = s[j]; }
	v_mov_b32_dpp v105, v231 row_ror:2 row_mask:0xf bank_mask:0xf
	v_mov_b32_dpp v106, v232 row_ror:2 row_mask:0xf bank_mask:0xf
	v_mov_b32_dpp v107, v233 row_ror:2 row_mask:0xf bank_mask:0xf
	v_mov_b32_dpp v104, v234 row_shr:2 row_mask:0xf bank_mask:0xf
	v_mov_b32_dpp v105, v235 row_shr:2 row_mask:0xf bank_mask:0xf
	v_mov_b32_dpp v106, v236 row_shr:2 row_mask:0xf bank_mask:0xf
	v_mov_b32_dpp v107, v237 row_shr:2 row_mask:0xf bank_mask:0xf
	v_max_i32_e32 v98, -2, v114
	v_add_u32_e32 v132, s81, v98
	v_cmp_lt_i32_e64 s[52:53], -3, v114
	v_mov_b32_dpp v114, v230 row_ror:1 row_mask:0xf bank_mask:0xf
	v_mov_b32_dpp v115, v231 row_ror:1 row_mask:0xf bank_mask:0xf
	v_mov_b32_dpp v116, v232 row_ror:1 row_mask:0xf bank_mask:0xf
	v_mov_b32_dpp v117, v233 row_ror:1 row_mask:0xf bank_mask:0xf
	v_mov_b32_dpp v114, v234 row_shr:1 row_mask:0xf bank_mask:0xf
	v_mov_b32_dpp v115, v235 row_shr:1 row_mask:0xf bank_mask:0xf
	v_mov_b32_dpp v116, v236 row_shr:1 row_mask:0xf bank_mask:0xf
	v_mov_b32_dpp v117, v237 row_shr:1 row_mask:0xf bank_mask:0xf
	v_or_b32_e32 v98, s20, v139
	v_cndmask_b32_e64 v98, 0, v98, s[42:43]
	v_add_u32_e32 v133, s27, v98
	v_mov_b64_e32 v[126:127], v[234:235]
	v_mov_b64_e32 v[128:129], v[236:237]
	v_mov_b32_e32 v98, 0x2080
	v_mad_u32_u24 v141, v136, s76, v98
	v_cndmask_b32_e64 v147, 0, v35, s[56:57]
	v_cndmask_b32_e64 v146, 0, v34, s[56:57]
	v_cndmask_b32_e64 v149, 0, v41, s[54:55]
	v_cndmask_b32_e64 v148, 0, v40, s[54:55]
	v_add_u32_e32 v124, v95, v141
	s_waitcnt vmcnt(0) lgkmcnt(0)
	v_lshlrev_b32_e32 v98, 16, v8
	v_lshlrev_b32_e32 v118, 16, v9
	v_and_b32_e32 v99, 0xffff0000, v8
	v_and_b32_e32 v119, 0xffff0000, v9
	v_cndmask_b32_e64 v9, 0, v33, s[56:57]
	v_cndmask_b32_e64 v8, 0, v32, s[56:57]
	v_pk_fma_f32 v[118:119], v[146:147], v[118:119], v[6:7]
	v_pk_fma_f32 v[8:9], v[8:9], v[98:99], v[4:5]
	v_lshlrev_b32_e32 v98, 16, v105
	v_lshlrev_b32_e32 v146, 16, v104
	v_and_b32_e32 v99, 0xffff0000, v105
	v_and_b32_e32 v147, 0xffff0000, v104
	v_cndmask_b32_e64 v105, 0, v43, s[54:55]
	v_cndmask_b32_e64 v104, 0, v42, s[54:55]
	v_pk_fma_f32 v[8:9], v[148:149], v[146:147], v[8:9]
	v_pk_fma_f32 v[98:99], v[104:105], v[98:99], v[118:119]
	v_lshlrev_b32_e32 v104, 16, v114
	v_lshlrev_b32_e32 v118, 16, v115
	v_and_b32_e32 v105, 0xffff0000, v114
	v_and_b32_e32 v119, 0xffff0000, v115
	v_cndmask_b32_e64 v115, 0, v69, s[52:53]
	v_cndmask_b32_e64 v114, 0, v68, s[52:53]
	v_cndmask_b32_e64 v147, 0, v71, s[52:53]
	v_cndmask_b32_e64 v146, 0, v70, s[52:53]
	v_pk_fma_f32 v[98:99], v[146:147], v[118:119], v[98:99]
	v_pk_fma_f32 v[8:9], v[114:115], v[104:105], v[8:9]
	v_lshlrev_b32_e32 v104, 16, v127
	v_lshlrev_b32_e32 v114, 16, v126
	v_and_b32_e32 v105, 0xffff0000, v127
	v_and_b32_e32 v115, 0xffff0000, v126
	v_pk_fma_f32 v[114:115], v[82:83], v[114:115], v[8:9]
	v_pk_fma_f32 v[98:99], v[72:73], v[104:105], v[98:99]
	v_cvt_pk_bf16_f32 v8, v114, v115
	v_cvt_pk_bf16_f32 v9, v98, v99
	ds_write2_b32 v124, v98, v99 offset0:2 offset1:3
	ds_write2_b32 v124, v114, v115 offset1:1
	v_lshlrev_b32_e32 v98, 16, v10
	v_lshlrev_b32_e32 v104, 16, v11
	v_and_b32_e32 v99, 0xffff0000, v10
	v_and_b32_e32 v105, 0xffff0000, v11
	v_cndmask_b32_e64 v11, 0, v25, s[56:57]
	v_cndmask_b32_e64 v10, 0, v24, s[56:57]
	v_cndmask_b32_e64 v115, 0, v27, s[56:57]
	v_cndmask_b32_e64 v114, 0, v26, s[56:57]
	v_pk_fma_f32 v[104:105], v[114:115], v[104:105], v[22:23]
	v_pk_fma_f32 v[10:11], v[10:11], v[98:99], v[20:21]
	v_lshlrev_b32_e32 v98, 16, v107
	v_lshlrev_b32_e32 v114, 16, v106
	v_and_b32_e32 v99, 0xffff0000, v107
	v_and_b32_e32 v115, 0xffff0000, v106
	v_cndmask_b32_e64 v107, 0, v31, s[54:55]
	v_cndmask_b32_e64 v106, 0, v30, s[54:55]
	v_cndmask_b32_e64 v119, 0, v29, s[54:55]
	v_cndmask_b32_e64 v118, 0, v28, s[54:55]
	v_pk_fma_f32 v[10:11], v[118:119], v[114:115], v[10:11]
	v_pk_fma_f32 v[98:99], v[106:107], v[98:99], v[104:105]
	v_lshlrev_b32_e32 v104, 16, v116
	v_lshlrev_b32_e32 v106, 16, v117
	v_and_b32_e32 v105, 0xffff0000, v116
	v_and_b32_e32 v107, 0xffff0000, v117
	v_cndmask_b32_e64 v115, 0, v37, s[52:53]
	v_cndmask_b32_e64 v114, 0, v36, s[52:53]
	v_cndmask_b32_e64 v117, 0, v39, s[52:53]
	v_cndmask_b32_e64 v116, 0, v38, s[52:53]
	v_pk_fma_f32 v[98:99], v[116:117], v[106:107], v[98:99]
	v_pk_fma_f32 v[10:11], v[114:115], v[104:105], v[10:11]
	v_lshlrev_b32_e32 v104, 16, v129
	v_and_b32_e32 v105, 0xffff0000, v129
	v_add_u32_e32 v118, s40, v137
	v_lshlrev_b32_e32 v106, 16, v128
	v_and_b32_e32 v107, 0xffff0000, v128
	v_pk_fma_f32 v[98:99], v[74:75], v[104:105], v[98:99]
	v_cmp_lt_i32_e64 s[46:47], -1, v118
	v_pk_fma_f32 v[106:107], v[84:85], v[106:107], v[10:11]
	v_cvt_pk_bf16_f32 v11, v98, v99
	ds_write2_b32 v124, v98, v99 offset0:6 offset1:7
	ds_write2_b32 v124, v106, v107 offset0:4 offset1:5
	v_cndmask_b32_e64 v98, 0, v118, s[46:47]
	v_add_u32_e32 v126, s27, v98
	v_cvt_pk_bf16_f32 v10, v106, v107
	v_mov_b32_dpp v104, v234 row_ror:3 row_mask:0xf bank_mask:0xf
	v_mov_b32_dpp v105, v235 row_ror:3 row_mask:0xf bank_mask:0xf
	v_mov_b32_dpp v106, v236 row_ror:3 row_mask:0xf bank_mask:0xf
	v_mov_b32_dpp v107, v237 row_ror:3 row_mask:0xf bank_mask:0xf
	v_mov_b32_dpp v104, v238 row_shr:3 row_mask:0xf bank_mask:0xf
	v_mov_b32_dpp v105, v239 row_shr:3 row_mask:0xf bank_mask:0xf
	v_mov_b32_dpp v106, v240 row_shr:3 row_mask:0xf bank_mask:0xf
	v_mov_b32_dpp v107, v241 row_shr:3 row_mask:0xf bank_mask:0xf
	v_max_i32_e32 v98, -1, v118
	v_add_u32_e32 v127, s80, v98
	v_mov_b32_dpp v114, v234 row_ror:2 row_mask:0xf bank_mask:0xf
	v_mov_b32_dpp v115, v235 row_ror:2 row_mask:0xf bank_mask:0xf
	v_mov_b32_dpp v116, v236 row_ror:2 row_mask:0xf bank_mask:0xf
	v_mov_b32_dpp v117, v237 row_ror:2 row_mask:0xf bank_mask:0xf
; __device__ __forceinline__ void ld8bf(const bf16_t* p, float (&o)[8]) { unpack8(*(const u32x4*)p, o); }
; __device__ __forceinline__ bf16x8 pack_frag(const float (&v)[8]) { return __builtin_bit_cast(bf16x8, pack8(v)); }
; __device__ __forceinline__ void w_lru_m1(const Args& a, int l, unsigned char* ws, const bf16_t* proj, bf16_t* y, LAS unsigned char* wl, int b, int ck_, int h, int lane) {
;     ...
;     for (int kk = 0; kk < 2; ++kk) { const int ch0 = 64 * h + 32 * kk + 8 * fq; float w[4][8], bs[8];
; #pragma unroll
;         for (int j = 0; j < 8; ++j) { bs[j] = cbias[ch0 + j];
; #pragma unroll
;             for (int k = 0; k < 4; ++k) w[k][j] = cw[k * 512 + ch0 + j]; }
; #pragma unroll
;         for (int tb = 0; tb < 4; ++tb) { const int tok = 16 * tb + lo, t = 64 * ck_ + tok; float s[8];
; #pragma unroll
;             for (int j = 0; j < 8; ++j) s[j] = bs[j];
; #pragma unroll
;             for (int k = 0; k < 4; ++k) { const int tt = t - 3 + k; float x[8];
;                 ld8bf(proj + (size_t)(b * SEQ + (tt >= 0 ? tt : 0)) * NIN + C_LX + ch0, x);
; #pragma unroll
;                 for (int j = 0; j < 8; ++j) s[j] += (tt >= 0 ? w[k][j] : 0.f) * x[j]; }
;             Xf[tb][kk] = pack_frag(s);
; #pragma unroll
;             for (int j = 0; j < 8; ++j) xcf[tok * 65 + 32 * kk + 8 * fq + j] = s[j]; }
	v_mov_b32_dpp v114, v238 row_shr:2 row_mask:0xf bank_mask:0xf
	v_mov_b32_dpp v115, v239 row_shr:2 row_mask:0xf bank_mask:0xf
	v_mov_b32_dpp v116, v240 row_shr:2 row_mask:0xf bank_mask:0xf
	v_mov_b32_dpp v117, v241 row_shr:2 row_mask:0xf bank_mask:0xf
	v_max_i32_e32 v98, -2, v118
	v_add_u32_e32 v128, s81, v98
	v_mov_b32_dpp v146, v234 row_ror:1 row_mask:0xf bank_mask:0xf
	v_mov_b32_dpp v147, v235 row_ror:1 row_mask:0xf bank_mask:0xf
	v_mov_b32_dpp v148, v236 row_ror:1 row_mask:0xf bank_mask:0xf
	v_mov_b32_dpp v149, v237 row_ror:1 row_mask:0xf bank_mask:0xf
	v_mov_b32_dpp v146, v238 row_shr:1 row_mask:0xf bank_mask:0xf
	v_mov_b32_dpp v147, v239 row_shr:1 row_mask:0xf bank_mask:0xf
	v_mov_b32_dpp v148, v240 row_shr:1 row_mask:0xf bank_mask:0xf
	v_mov_b32_dpp v149, v241 row_shr:1 row_mask:0xf bank_mask:0xf
	v_or_b32_e32 v98, s20, v137
	v_cndmask_b32_e64 v98, 0, v98, s[42:43]
	v_add_u32_e32 v129, s27, v98
	v_mov_b64_e32 v[150:151], v[238:239]
	v_mov_b64_e32 v[152:153], v[240:241]
	v_mov_b32_e32 v80, 0x30c0
	v_cmp_lt_i32_e64 s[40:41], -2, v118
	v_mad_u32_u24 v138, v136, s76, v80
	v_cndmask_b32_e64 v33, 0, v33, s[46:47]
	v_cndmask_b32_e64 v32, 0, v32, s[46:47]
	v_cndmask_b32_e64 v35, 0, v35, s[46:47]
	v_cndmask_b32_e64 v34, 0, v34, s[46:47]
	v_cmp_lt_i32_e32 vcc, -3, v118
	v_cndmask_b32_e64 v43, 0, v43, s[40:41]
	v_cndmask_b32_e64 v42, 0, v42, s[40:41]
	v_cndmask_b32_e64 v41, 0, v41, s[40:41]
	v_cndmask_b32_e64 v40, 0, v40, s[40:41]
	v_add_u32_e32 v120, v95, v138
	v_cndmask_b32_e64 v25, 0, v25, s[46:47]
	v_cndmask_b32_e64 v24, 0, v24, s[46:47]
	v_cndmask_b32_e64 v27, 0, v27, s[46:47]
	v_cndmask_b32_e64 v26, 0, v26, s[46:47]
	v_cndmask_b32_e64 v29, 0, v29, s[40:41]
	v_cndmask_b32_e64 v28, 0, v28, s[40:41]
	s_mov_b64 s[80:81], 0x1080
	s_waitcnt vmcnt(0) lgkmcnt(0)
	v_lshlrev_b32_e32 v80, 16, v104
	v_lshlrev_b32_e32 v98, 16, v105
	v_and_b32_e32 v81, 0xffff0000, v104
	v_and_b32_e32 v99, 0xffff0000, v105
	v_pk_fma_f32 v[6:7], v[34:35], v[98:99], v[6:7]
	v_pk_fma_f32 v[4:5], v[32:33], v[80:81], v[4:5]
	v_lshlrev_b32_e32 v32, 16, v115
	v_lshlrev_b32_e32 v34, 16, v114
	v_and_b32_e32 v33, 0xffff0000, v115
	v_and_b32_e32 v35, 0xffff0000, v114
	v_pk_fma_f32 v[4:5], v[40:41], v[34:35], v[4:5]
	v_pk_fma_f32 v[6:7], v[42:43], v[32:33], v[6:7]
	v_lshlrev_b32_e32 v32, 16, v146
	v_lshlrev_b32_e32 v34, 16, v147
	v_and_b32_e32 v33, 0xffff0000, v146
	v_and_b32_e32 v35, 0xffff0000, v147
	v_cndmask_b32_e32 v41, 0, v69, vcc
	v_cndmask_b32_e32 v40, 0, v68, vcc
	v_cndmask_b32_e32 v43, 0, v71, vcc
	v_cndmask_b32_e32 v42, 0, v70, vcc
	v_pk_fma_f32 v[6:7], v[42:43], v[34:35], v[6:7]
	v_pk_fma_f32 v[4:5], v[40:41], v[32:33], v[4:5]
	v_lshlrev_b32_e32 v32, 16, v151
	v_and_b32_e32 v33, 0xffff0000, v151
	v_lshlrev_b32_e32 v34, 16, v150
	v_and_b32_e32 v35, 0xffff0000, v150
	v_pk_fma_f32 v[6:7], v[72:73], v[32:33], v[6:7]
	v_pk_fma_f32 v[34:35], v[82:83], v[34:35], v[4:5]
	v_cvt_pk_bf16_f32 v5, v6, v7
	ds_write2_b32 v120, v6, v7 offset0:2 offset1:3
	ds_write2_b32 v120, v34, v35 offset1:1
	v_lshlrev_b32_e32 v6, 16, v106
	v_lshlrev_b32_e32 v32, 16, v107
	v_and_b32_e32 v7, 0xffff0000, v106
	v_and_b32_e32 v33, 0xffff0000, v107
	v_pk_fma_f32 v[22:23], v[26:27], v[32:33], v[22:23]
	v_pk_fma_f32 v[6:7], v[24:25], v[6:7], v[20:21]
	v_lshlrev_b32_e32 v20, 16, v117
	v_lshlrev_b32_e32 v24, 16, v116
	v_and_b32_e32 v21, 0xffff0000, v117
	v_and_b32_e32 v25, 0xffff0000, v116
	v_cndmask_b32_e64 v27, 0, v31, s[40:41]
	v_cndmask_b32_e64 v26, 0, v30, s[40:41]
	v_pk_fma_f32 v[6:7], v[28:29], v[24:25], v[6:7]
	v_pk_fma_f32 v[20:21], v[26:27], v[20:21], v[22:23]
	v_lshlrev_b32_e32 v22, 16, v148
	v_lshlrev_b32_e32 v24, 16, v149
	v_and_b32_e32 v23, 0xffff0000, v148
	v_and_b32_e32 v25, 0xffff0000, v149
	v_cndmask_b32_e32 v27, 0, v37, vcc
	v_cndmask_b32_e32 v26, 0, v36, vcc
	v_cndmask_b32_e32 v29, 0, v39, vcc
	v_cndmask_b32_e32 v28, 0, v38, vcc
	v_pk_fma_f32 v[20:21], v[28:29], v[24:25], v[20:21]
	v_pk_fma_f32 v[6:7], v[26:27], v[22:23], v[6:7]
	v_lshlrev_b32_e32 v22, 16, v153
	v_and_b32_e32 v23, 0xffff0000, v153
	v_lshlrev_b32_e32 v24, 16, v152
	v_and_b32_e32 v25, 0xffff0000, v152
	v_pk_fma_f32 v[20:21], v[74:75], v[22:23], v[20:21]
	v_pk_fma_f32 v[24:25], v[84:85], v[24:25], v[6:7]
	v_cvt_pk_bf16_f32 v7, v20, v21
	ds_write2_b32 v120, v20, v21 offset0:6 offset1:7
	ds_write2_b32 v120, v24, v25 offset0:4 offset1:5
	v_add_u32_e32 v20, 32, v78
	v_ashrrev_i32_e32 v21, 31, v20
	v_lshl_add_u64 v[84:85], v[86:87], 0, s[80:81]
	s_mov_b64 s[80:81], 0x1880
	v_lshl_add_u64 v[106:107], v[86:87], 0, s[80:81]
	v_lshlrev_b64 v[104:105], 1, v[20:21]
	v_mov_b32_dpp v80, v242 row_ror:3 row_mask:0xf bank_mask:0xf
	v_mov_b32_dpp v81, v243 row_ror:3 row_mask:0xf bank_mask:0xf
	v_mov_b32_dpp v82, v244 row_ror:3 row_mask:0xf bank_mask:0xf
	v_mov_b32_dpp v83, v245 row_ror:3 row_mask:0xf bank_mask:0xf
	v_mov_b32_dpp v80, v246 row_shr:3 row_mask:0xf bank_mask:0xf
	v_mov_b32_dpp v81, v247 row_shr:3 row_mask:0xf bank_mask:0xf
	v_mov_b32_dpp v82, v248 row_shr:3 row_mask:0xf bank_mask:0xf
	v_mov_b32_dpp v83, v249 row_shr:3 row_mask:0xf bank_mask:0xf
	v_cvt_pk_bf16_f32 v4, v34, v35
	v_mov_b32_dpp v32, v242 row_ror:2 row_mask:0xf bank_mask:0xf
	v_mov_b32_dpp v33, v243 row_ror:2 row_mask:0xf bank_mask:0xf
	v_mov_b32_dpp v34, v244 row_ror:2 row_mask:0xf bank_mask:0xf
	v_mov_b32_dpp v35, v245 row_ror:2 row_mask:0xf bank_mask:0xf
	v_mov_b32_dpp v32, v246 row_shr:2 row_mask:0xf bank_mask:0xf
	v_mov_b32_dpp v33, v247 row_shr:2 row_mask:0xf bank_mask:0xf
	v_mov_b32_dpp v34, v248 row_shr:2 row_mask:0xf bank_mask:0xf
	v_mov_b32_dpp v35, v249 row_shr:2 row_mask:0xf bank_mask:0xf
	v_mov_b32_dpp v28, v242 row_ror:1 row_mask:0xf bank_mask:0xf
	v_mov_b32_dpp v29, v243 row_ror:1 row_mask:0xf bank_mask:0xf
	v_mov_b32_dpp v30, v244 row_ror:1 row_mask:0xf bank_mask:0xf
	v_mov_b32_dpp v31, v245 row_ror:1 row_mask:0xf bank_mask:0xf
	v_mov_b32_dpp v28, v246 row_shr:1 row_mask:0xf bank_mask:0xf
	v_mov_b32_dpp v29, v247 row_shr:1 row_mask:0xf bank_mask:0xf
	v_mov_b32_dpp v30, v248 row_shr:1 row_mask:0xf bank_mask:0xf
	v_mov_b32_dpp v31, v249 row_shr:1 row_mask:0xf bank_mask:0xf
	v_cvt_pk_bf16_f32 v6, v24, v25
	v_mov_b64_e32 v[24:25], v[246:247]
	v_mov_b64_e32 v[26:27], v[248:249]
	global_load_dwordx4 v[40:43], v[76:77], off offset:144
	global_load_dwordx4 v[72:75], v[76:77], off offset:128
	global_load_dwordx4 v[68:71], v[86:87], off offset:144
	s_nop 0
	global_load_dwordx4 v[76:79], v[86:87], off offset:128
	global_load_dwordx4 v[36:39], v[86:87], off offset:2192
	global_load_dwordx4 v[20:23], v[86:87], off offset:2176
	global_load_dwordx4 v[92:95], v[96:97], off offset:128
	s_nop 0
	global_load_dwordx4 v[84:87], v[84:85], off offset:16
	s_nop 0
	global_load_dwordx4 v[96:99], v[96:97], off offset:2176
	s_nop 0
	global_load_dwordx4 v[146:149], v[106:107], off offset:16
	s_waitcnt vmcnt(0) lgkmcnt(0)
; __device__ __forceinline__ void ld8bf(const bf16_t* p, float (&o)[8]) { unpack8(*(const u32x4*)p, o); }
; __device__ __forceinline__ bf16x8 pack_frag(const float (&v)[8]) { return __builtin_bit_cast(bf16x8, pack8(v)); }
; __device__ __forceinline__ void w_lru_m1(const Args& a, int l, unsigned char* ws, const bf16_t* proj, bf16_t* y, LAS unsigned char* wl, int b, int ck_, int h, int lane) {
;     ...
;     for (int kk = 0; kk < 2; ++kk) { const int ch0 = 64 * h + 32 * kk + 8 * fq; float w[4][8], bs[8];
; #pragma unroll
;         for (int j = 0; j < 8; ++j) { bs[j] = cbias[ch0 + j];
; #pragma unroll
;             for (int k = 0; k < 4; ++k) w[k][j] = cw[k * 512 + ch0 + j]; }
; #pragma unroll
;         for (int tb = 0; tb < 4; ++tb) { const int tok = 16 * tb + lo, t = 64 * ck_ + tok; float s[8];
; #pragma unroll
;             for (int j = 0; j < 8; ++j) s[j] = bs[j];
; #pragma unroll
;             for (int k = 0; k < 4; ++k) { const int tt = t - 3 + k; float x[8];
;                 ld8bf(proj + (size_t)(b * SEQ + (tt >= 0 ? tt : 0)) * NIN + C_LX + ch0, x);
; #pragma unroll
;                 for (int j = 0; j < 8; ++j) s[j] += (tt >= 0 ? w[k][j] : 0.f) * x[j]; }
;             Xf[tb][kk] = pack_frag(s);
; #pragma unroll
;             for (int j = 0; j < 8; ++j) xcf[tok * 65 + 32 * kk + 8 * fq + j] = s[j]; }
	v_lshlrev_b32_e32 v106, 16, v80
	v_lshlrev_b32_e32 v114, 16, v81
	v_and_b32_e32 v107, 0xffff0000, v80
	v_and_b32_e32 v115, 0xffff0000, v81
	v_cndmask_b32_e64 v81, 0, v77, s[50:51]
	v_cndmask_b32_e64 v80, 0, v76, s[50:51]
	v_cndmask_b32_e64 v117, 0, v79, s[50:51]
	v_cndmask_b32_e64 v116, 0, v78, s[50:51]
	v_pk_fma_f32 v[114:115], v[116:117], v[114:115], v[74:75]
	v_pk_fma_f32 v[80:81], v[80:81], v[106:107], v[72:73]
	v_lshlrev_b32_e32 v106, 16, v33
	v_lshlrev_b32_e32 v116, 16, v32
	v_and_b32_e32 v107, 0xffff0000, v33
	v_and_b32_e32 v117, 0xffff0000, v32
	v_cndmask_b32_e64 v33, 0, v23, s[48:49]
	v_cndmask_b32_e64 v32, 0, v22, s[48:49]
	v_cndmask_b32_e64 v119, 0, v21, s[48:49]
	v_cndmask_b32_e64 v118, 0, v20, s[48:49]
	v_pk_fma_f32 v[80:81], v[118:119], v[116:117], v[80:81]
	v_pk_fma_f32 v[32:33], v[32:33], v[106:107], v[114:115]
	v_lshlrev_b32_e32 v106, 16, v28
	v_lshlrev_b32_e32 v114, 16, v29
	v_and_b32_e32 v107, 0xffff0000, v28
	v_and_b32_e32 v115, 0xffff0000, v29
	v_cndmask_b32_e64 v29, 0, v93, s[44:45]
	v_cndmask_b32_e64 v28, 0, v92, s[44:45]
	v_cndmask_b32_e64 v117, 0, v95, s[44:45]
	v_cndmask_b32_e64 v116, 0, v94, s[44:45]
	v_pk_fma_f32 v[32:33], v[116:117], v[114:115], v[32:33]
	v_pk_fma_f32 v[28:29], v[28:29], v[106:107], v[80:81]
	v_lshlrev_b32_e32 v80, 16, v25
	v_lshlrev_b32_e32 v116, 16, v24
	v_and_b32_e32 v81, 0xffff0000, v25
	v_and_b32_e32 v117, 0xffff0000, v24
	v_cndmask_b32_e64 v107, 0, v99, s[42:43]
	v_cndmask_b32_e64 v106, 0, v98, s[42:43]
	v_cndmask_b32_e64 v115, 0, v97, s[42:43]
	v_cndmask_b32_e64 v114, 0, v96, s[42:43]
	v_pk_fma_f32 v[24:25], v[114:115], v[116:117], v[28:29]
	v_pk_fma_f32 v[28:29], v[106:107], v[80:81], v[32:33]
	v_cvt_pk_bf16_f32 v32, v24, v25
	v_cvt_pk_bf16_f32 v33, v28, v29
	ds_write2_b32 v121, v28, v29 offset0:34 offset1:35
	ds_write2_b32 v121, v24, v25 offset0:32 offset1:33
	v_lshlrev_b32_e32 v24, 16, v82
	v_lshlrev_b32_e32 v28, 16, v83
	v_and_b32_e32 v25, 0xffff0000, v82
	v_and_b32_e32 v29, 0xffff0000, v83
	v_cndmask_b32_e64 v81, 0, v69, s[50:51]
	v_cndmask_b32_e64 v80, 0, v68, s[50:51]
	v_cndmask_b32_e64 v83, 0, v71, s[50:51]
	v_cndmask_b32_e64 v82, 0, v70, s[50:51]
	v_pk_fma_f32 v[28:29], v[82:83], v[28:29], v[42:43]
	v_pk_fma_f32 v[24:25], v[80:81], v[24:25], v[40:41]
	v_lshlrev_b32_e32 v80, 16, v35
	v_lshlrev_b32_e32 v82, 16, v34
	v_and_b32_e32 v81, 0xffff0000, v35
	v_and_b32_e32 v83, 0xffff0000, v34
	v_cndmask_b32_e64 v35, 0, v39, s[48:49]
	v_cndmask_b32_e64 v34, 0, v38, s[48:49]
	v_cndmask_b32_e64 v97, 0, v37, s[48:49]
	v_cndmask_b32_e64 v96, 0, v36, s[48:49]
	v_pk_fma_f32 v[24:25], v[96:97], v[82:83], v[24:25]
	v_pk_fma_f32 v[28:29], v[34:35], v[80:81], v[28:29]
	v_lshlrev_b32_e32 v34, 16, v30
	v_lshlrev_b32_e32 v80, 16, v31
	v_and_b32_e32 v35, 0xffff0000, v30
	v_and_b32_e32 v81, 0xffff0000, v31
	v_cndmask_b32_e64 v31, 0, v85, s[44:45]
	v_cndmask_b32_e64 v30, 0, v84, s[44:45]
	v_cndmask_b32_e64 v83, 0, v87, s[44:45]
	v_cndmask_b32_e64 v82, 0, v86, s[44:45]
	v_pk_fma_f32 v[28:29], v[82:83], v[80:81], v[28:29]
	v_pk_fma_f32 v[24:25], v[30:31], v[34:35], v[24:25]
	v_lshlrev_b32_e32 v30, 16, v27
	v_lshlrev_b32_e32 v34, 16, v26
	v_and_b32_e32 v31, 0xffff0000, v27
	v_and_b32_e32 v35, 0xffff0000, v26
	v_cndmask_b32_e64 v117, 0, v149, s[42:43]
	v_cndmask_b32_e64 v116, 0, v148, s[42:43]
	v_cndmask_b32_e64 v119, 0, v147, s[42:43]
	v_cndmask_b32_e64 v118, 0, v146, s[42:43]
	v_pk_fma_f32 v[24:25], v[118:119], v[34:35], v[24:25]
	v_pk_fma_f32 v[26:27], v[116:117], v[30:31], v[28:29]
	v_cvt_pk_bf16_f32 v34, v24, v25
	ds_write2_b32 v121, v26, v27 offset0:38 offset1:39
	ds_write2_b32 v121, v24, v25 offset0:36 offset1:37
	v_cvt_pk_bf16_f32 v35, v26, v27
	v_mov_b32_dpp v24, v246 row_ror:3 row_mask:0xf bank_mask:0xf
	v_mov_b32_dpp v25, v247 row_ror:3 row_mask:0xf bank_mask:0xf
	v_mov_b32_dpp v26, v248 row_ror:3 row_mask:0xf bank_mask:0xf
	v_mov_b32_dpp v27, v249 row_ror:3 row_mask:0xf bank_mask:0xf
	v_mov_b32_dpp v24, v250 row_shr:3 row_mask:0xf bank_mask:0xf
	v_mov_b32_dpp v25, v251 row_shr:3 row_mask:0xf bank_mask:0xf
	v_mov_b32_dpp v26, v252 row_shr:3 row_mask:0xf bank_mask:0xf
	v_mov_b32_dpp v27, v253 row_shr:3 row_mask:0xf bank_mask:0xf
	v_mov_b32_dpp v28, v246 row_ror:2 row_mask:0xf bank_mask:0xf
	v_mov_b32_dpp v29, v247 row_ror:2 row_mask:0xf bank_mask:0xf
	v_mov_b32_dpp v30, v248 row_ror:2 row_mask:0xf bank_mask:0xf
	v_mov_b32_dpp v31, v249 row_ror:2 row_mask:0xf bank_mask:0xf
	v_mov_b32_dpp v28, v250 row_shr:2 row_mask:0xf bank_mask:0xf
	v_mov_b32_dpp v29, v251 row_shr:2 row_mask:0xf bank_mask:0xf
	v_mov_b32_dpp v30, v252 row_shr:2 row_mask:0xf bank_mask:0xf
	v_mov_b32_dpp v31, v253 row_shr:2 row_mask:0xf bank_mask:0xf
	v_mov_b32_dpp v80, v246 row_ror:1 row_mask:0xf bank_mask:0xf
	v_mov_b32_dpp v81, v247 row_ror:1 row_mask:0xf bank_mask:0xf
	v_mov_b32_dpp v82, v248 row_ror:1 row_mask:0xf bank_mask:0xf
	v_mov_b32_dpp v83, v249 row_ror:1 row_mask:0xf bank_mask:0xf
	v_mov_b32_dpp v80, v250 row_shr:1 row_mask:0xf bank_mask:0xf
	v_mov_b32_dpp v81, v251 row_shr:1 row_mask:0xf bank_mask:0xf
	v_mov_b32_dpp v82, v252 row_shr:1 row_mask:0xf bank_mask:0xf
	v_mov_b32_dpp v83, v253 row_shr:1 row_mask:0xf bank_mask:0xf
	v_mov_b64_e32 v[96:97], v[250:251]
	v_mov_b64_e32 v[98:99], v[252:253]
	v_cndmask_b32_e64 v147, 0, v79, s[62:63]
	v_cndmask_b32_e64 v146, 0, v78, s[62:63]
	v_cndmask_b32_e64 v149, 0, v21, s[60:61]
	v_cndmask_b32_e64 v148, 0, v20, s[60:61]
	s_add_i32 s48, s20, s27
	s_lshl_b32 s20, s91, 7
	s_add_u32 s44, s10, s20
	s_addc_u32 s45, s11, 0
	s_waitcnt vmcnt(0) lgkmcnt(0)
; __device__ __forceinline__ void ld8bf(const bf16_t* p, float (&o)[8]) { unpack8(*(const u32x4*)p, o); }
; __device__ __forceinline__ bf16x8 pack_frag(const float (&v)[8]) { return __builtin_bit_cast(bf16x8, pack8(v)); }
; __device__ __forceinline__ void w_lru_m1(const Args& a, int l, unsigned char* ws, const bf16_t* proj, bf16_t* y, LAS unsigned char* wl, int b, int ck_, int h, int lane) {
;     ...
;     for (int kk = 0; kk < 2; ++kk) { const int ch0 = 64 * h + 32 * kk + 8 * fq; float w[4][8], bs[8];
; #pragma unroll
;         for (int j = 0; j < 8; ++j) { bs[j] = cbias[ch0 + j];
; #pragma unroll
;             for (int k = 0; k < 4; ++k) w[k][j] = cw[k * 512 + ch0 + j]; }
; #pragma unroll
;         for (int tb = 0; tb < 4; ++tb) { const int tok = 16 * tb + lo, t = 64 * ck_ + tok; float s[8];
; #pragma unroll
;             for (int j = 0; j < 8; ++j) s[j] = bs[j];
; #pragma unroll
;             for (int k = 0; k < 4; ++k) { const int tt = t - 3 + k; float x[8];
;                 ld8bf(proj + (size_t)(b * SEQ + (tt >= 0 ? tt : 0)) * NIN + C_LX + ch0, x);
; #pragma unroll
;                 for (int j = 0; j < 8; ++j) s[j] += (tt >= 0 ? w[k][j] : 0.f) * x[j]; }
;             Xf[tb][kk] = pack_frag(s);
; #pragma unroll
;             for (int j = 0; j < 8; ++j) xcf[tok * 65 + 32 * kk + 8 * fq + j] = s[j]; }
	v_lshlrev_b32_e32 v134, 16, v24
	v_lshlrev_b32_e32 v142, 16, v25
	v_and_b32_e32 v135, 0xffff0000, v24
	v_and_b32_e32 v143, 0xffff0000, v25
	v_cndmask_b32_e64 v25, 0, v77, s[62:63]
	v_cndmask_b32_e64 v24, 0, v76, s[62:63]
	v_pk_fma_f32 v[142:143], v[146:147], v[142:143], v[74:75]
	v_pk_fma_f32 v[24:25], v[24:25], v[134:135], v[72:73]
	v_lshlrev_b32_e32 v134, 16, v29
	v_lshlrev_b32_e32 v146, 16, v28
	v_and_b32_e32 v135, 0xffff0000, v29
	v_and_b32_e32 v147, 0xffff0000, v28
	v_cndmask_b32_e64 v29, 0, v23, s[60:61]
	v_cndmask_b32_e64 v28, 0, v22, s[60:61]
	v_pk_fma_f32 v[24:25], v[148:149], v[146:147], v[24:25]
	v_pk_fma_f32 v[28:29], v[28:29], v[134:135], v[142:143]
	v_lshlrev_b32_e32 v134, 16, v80
	v_lshlrev_b32_e32 v142, 16, v81
	v_and_b32_e32 v135, 0xffff0000, v80
	v_and_b32_e32 v143, 0xffff0000, v81
	v_cndmask_b32_e64 v81, 0, v93, s[58:59]
	v_cndmask_b32_e64 v80, 0, v92, s[58:59]
	v_cndmask_b32_e64 v147, 0, v95, s[58:59]
	v_cndmask_b32_e64 v146, 0, v94, s[58:59]
	v_pk_fma_f32 v[28:29], v[146:147], v[142:143], v[28:29]
	v_pk_fma_f32 v[24:25], v[80:81], v[134:135], v[24:25]
	v_lshlrev_b32_e32 v80, 16, v97
	v_lshlrev_b32_e32 v134, 16, v96
	v_and_b32_e32 v81, 0xffff0000, v97
	v_and_b32_e32 v135, 0xffff0000, v96
	v_pk_fma_f32 v[24:25], v[114:115], v[134:135], v[24:25]
	v_pk_fma_f32 v[80:81], v[106:107], v[80:81], v[28:29]
	v_cvt_pk_bf16_f32 v28, v24, v25
	v_cvt_pk_bf16_f32 v29, v80, v81
	ds_write2_b32 v125, v80, v81 offset0:34 offset1:35
	ds_write2_b32 v125, v24, v25 offset0:32 offset1:33
	v_lshlrev_b32_e32 v24, 16, v26
	v_lshlrev_b32_e32 v80, 16, v27
	v_and_b32_e32 v25, 0xffff0000, v26
	v_and_b32_e32 v81, 0xffff0000, v27
	v_cndmask_b32_e64 v27, 0, v69, s[62:63]
	v_cndmask_b32_e64 v26, 0, v68, s[62:63]
	v_cndmask_b32_e64 v97, 0, v71, s[62:63]
	v_cndmask_b32_e64 v96, 0, v70, s[62:63]
	v_pk_fma_f32 v[80:81], v[96:97], v[80:81], v[42:43]
	v_pk_fma_f32 v[24:25], v[26:27], v[24:25], v[40:41]
	v_lshlrev_b32_e32 v26, 16, v31
	v_lshlrev_b32_e32 v96, 16, v30
	v_and_b32_e32 v27, 0xffff0000, v31
	v_and_b32_e32 v97, 0xffff0000, v30
	v_cndmask_b32_e64 v31, 0, v39, s[60:61]
	v_cndmask_b32_e64 v30, 0, v38, s[60:61]
	v_cndmask_b32_e64 v135, 0, v37, s[60:61]
	v_cndmask_b32_e64 v134, 0, v36, s[60:61]
	v_pk_fma_f32 v[24:25], v[134:135], v[96:97], v[24:25]
	v_pk_fma_f32 v[26:27], v[30:31], v[26:27], v[80:81]
	v_lshlrev_b32_e32 v30, 16, v82
	v_lshlrev_b32_e32 v80, 16, v83
	v_and_b32_e32 v31, 0xffff0000, v82
	v_and_b32_e32 v81, 0xffff0000, v83
	v_cndmask_b32_e64 v83, 0, v85, s[58:59]
	v_cndmask_b32_e64 v82, 0, v84, s[58:59]
	v_cndmask_b32_e64 v97, 0, v87, s[58:59]
	v_cndmask_b32_e64 v96, 0, v86, s[58:59]
	v_pk_fma_f32 v[26:27], v[96:97], v[80:81], v[26:27]
	v_pk_fma_f32 v[24:25], v[82:83], v[30:31], v[24:25]
	v_lshlrev_b32_e32 v30, 16, v99
	v_lshlrev_b32_e32 v80, 16, v98
	v_and_b32_e32 v31, 0xffff0000, v99
	v_and_b32_e32 v81, 0xffff0000, v98
	v_pk_fma_f32 v[24:25], v[118:119], v[80:81], v[24:25]
	v_pk_fma_f32 v[26:27], v[116:117], v[30:31], v[26:27]
	v_cvt_pk_bf16_f32 v30, v24, v25
	ds_write2_b32 v125, v26, v27 offset0:38 offset1:39
	ds_write2_b32 v125, v24, v25 offset0:36 offset1:37
	v_cvt_pk_bf16_f32 v31, v26, v27
	v_mov_b32_dpp v24, v250 row_ror:3 row_mask:0xf bank_mask:0xf
	v_mov_b32_dpp v25, v251 row_ror:3 row_mask:0xf bank_mask:0xf
	v_mov_b32_dpp v26, v252 row_ror:3 row_mask:0xf bank_mask:0xf
	v_mov_b32_dpp v27, v253 row_ror:3 row_mask:0xf bank_mask:0xf
	v_mov_b32_dpp v24, v190 row_shr:3 row_mask:0xf bank_mask:0xf
	v_mov_b32_dpp v25, v191 row_shr:3 row_mask:0xf bank_mask:0xf
	v_mov_b32_dpp v26, v192 row_shr:3 row_mask:0xf bank_mask:0xf
	v_mov_b32_dpp v27, v193 row_shr:3 row_mask:0xf bank_mask:0xf
	v_mov_b32_dpp v80, v250 row_ror:2 row_mask:0xf bank_mask:0xf
	v_mov_b32_dpp v81, v251 row_ror:2 row_mask:0xf bank_mask:0xf
	v_mov_b32_dpp v82, v252 row_ror:2 row_mask:0xf bank_mask:0xf
	v_mov_b32_dpp v83, v253 row_ror:2 row_mask:0xf bank_mask:0xf
	v_mov_b32_dpp v80, v190 row_shr:2 row_mask:0xf bank_mask:0xf
	v_mov_b32_dpp v81, v191 row_shr:2 row_mask:0xf bank_mask:0xf
	v_mov_b32_dpp v82, v192 row_shr:2 row_mask:0xf bank_mask:0xf
	v_mov_b32_dpp v83, v193 row_shr:2 row_mask:0xf bank_mask:0xf
	v_mov_b32_dpp v96, v250 row_ror:1 row_mask:0xf bank_mask:0xf
	v_mov_b32_dpp v97, v251 row_ror:1 row_mask:0xf bank_mask:0xf
	v_mov_b32_dpp v98, v252 row_ror:1 row_mask:0xf bank_mask:0xf
	v_mov_b32_dpp v99, v253 row_ror:1 row_mask:0xf bank_mask:0xf
	v_mov_b32_dpp v96, v190 row_shr:1 row_mask:0xf bank_mask:0xf
	v_mov_b32_dpp v97, v191 row_shr:1 row_mask:0xf bank_mask:0xf
	v_mov_b32_dpp v98, v192 row_shr:1 row_mask:0xf bank_mask:0xf
	v_mov_b32_dpp v99, v193 row_shr:1 row_mask:0xf bank_mask:0xf
	v_mov_b64_e32 v[130:131], v[190:191]
	v_mov_b64_e32 v[132:133], v[192:193]
	v_cndmask_b32_e64 v147, 0, v79, s[56:57]
	v_cndmask_b32_e64 v146, 0, v78, s[56:57]
	v_cndmask_b32_e64 v149, 0, v21, s[54:55]
	v_cndmask_b32_e64 v148, 0, v20, s[54:55]
	v_cndmask_b32_e64 v79, 0, v79, s[46:47]
	v_cndmask_b32_e64 v78, 0, v78, s[46:47]
	v_cndmask_b32_e64 v21, 0, v21, s[40:41]
	v_cndmask_b32_e64 v20, 0, v20, s[40:41]
	s_waitcnt vmcnt(0) lgkmcnt(0)
; __device__ __forceinline__ void ld8bf(const bf16_t* p, float (&o)[8]) { unpack8(*(const u32x4*)p, o); }
; __device__ __forceinline__ bf16x8 pack_frag(const float (&v)[8]) { return __builtin_bit_cast(bf16x8, pack8(v)); }
; __device__ __forceinline__ void w_lru_m1(const Args& a, int l, unsigned char* ws, const bf16_t* proj, bf16_t* y, LAS unsigned char* wl, int b, int ck_, int h, int lane) {
;     ...
;     for (int kk = 0; kk < 2; ++kk) { const int ch0 = 64 * h + 32 * kk + 8 * fq; float w[4][8], bs[8];
; #pragma unroll
;         for (int j = 0; j < 8; ++j) { bs[j] = cbias[ch0 + j];
; #pragma unroll
;             for (int k = 0; k < 4; ++k) w[k][j] = cw[k * 512 + ch0 + j]; }
; #pragma unroll
;         for (int tb = 0; tb < 4; ++tb) { const int tok = 16 * tb + lo, t = 64 * ck_ + tok; float s[8];
; #pragma unroll
;             for (int j = 0; j < 8; ++j) s[j] = bs[j];
; #pragma unroll
;             for (int k = 0; k < 4; ++k) { const int tt = t - 3 + k; float x[8];
;                 ld8bf(proj + (size_t)(b * SEQ + (tt >= 0 ? tt : 0)) * NIN + C_LX + ch0, x);
; #pragma unroll
;                 for (int j = 0; j < 8; ++j) s[j] += (tt >= 0 ? w[k][j] : 0.f) * x[j]; }
;             Xf[tb][kk] = pack_frag(s);
; #pragma unroll
;             for (int j = 0; j < 8; ++j) xcf[tok * 65 + 32 * kk + 8 * fq + j] = s[j]; }
	v_lshlrev_b32_e32 v134, 16, v24
	v_lshlrev_b32_e32 v142, 16, v25
	v_and_b32_e32 v135, 0xffff0000, v24
	v_and_b32_e32 v143, 0xffff0000, v25
	v_cndmask_b32_e64 v25, 0, v77, s[56:57]
	v_cndmask_b32_e64 v24, 0, v76, s[56:57]
	v_pk_fma_f32 v[142:143], v[146:147], v[142:143], v[74:75]
	v_pk_fma_f32 v[24:25], v[24:25], v[134:135], v[72:73]
	v_lshlrev_b32_e32 v134, 16, v81
	v_lshlrev_b32_e32 v146, 16, v80
	v_and_b32_e32 v135, 0xffff0000, v81
	v_and_b32_e32 v147, 0xffff0000, v80
	v_cndmask_b32_e64 v81, 0, v23, s[54:55]
	v_cndmask_b32_e64 v80, 0, v22, s[54:55]
	v_pk_fma_f32 v[24:25], v[148:149], v[146:147], v[24:25]
	v_pk_fma_f32 v[80:81], v[80:81], v[134:135], v[142:143]
	v_lshlrev_b32_e32 v134, 16, v96
	v_lshlrev_b32_e32 v142, 16, v97
	v_and_b32_e32 v135, 0xffff0000, v96
	v_and_b32_e32 v143, 0xffff0000, v97
	v_cndmask_b32_e64 v97, 0, v93, s[52:53]
	v_cndmask_b32_e64 v96, 0, v92, s[52:53]
	v_cndmask_b32_e64 v147, 0, v95, s[52:53]
	v_cndmask_b32_e64 v146, 0, v94, s[52:53]
	v_pk_fma_f32 v[80:81], v[146:147], v[142:143], v[80:81]
	v_pk_fma_f32 v[24:25], v[96:97], v[134:135], v[24:25]
	v_lshlrev_b32_e32 v96, 16, v131
	v_lshlrev_b32_e32 v134, 16, v130
	v_and_b32_e32 v97, 0xffff0000, v131
	v_and_b32_e32 v135, 0xffff0000, v130
	v_pk_fma_f32 v[130:131], v[114:115], v[134:135], v[24:25]
	v_pk_fma_f32 v[80:81], v[106:107], v[96:97], v[80:81]
	v_cvt_pk_bf16_f32 v24, v130, v131
	v_cvt_pk_bf16_f32 v25, v80, v81
	ds_write2_b32 v124, v80, v81 offset0:34 offset1:35
	ds_write2_b32 v124, v130, v131 offset0:32 offset1:33
	v_lshlrev_b32_e32 v80, 16, v26
	v_lshlrev_b32_e32 v96, 16, v27
	v_and_b32_e32 v81, 0xffff0000, v26
	v_and_b32_e32 v97, 0xffff0000, v27
	v_cndmask_b32_e64 v27, 0, v69, s[56:57]
	v_cndmask_b32_e64 v26, 0, v68, s[56:57]
	v_cndmask_b32_e64 v131, 0, v71, s[56:57]
	v_cndmask_b32_e64 v130, 0, v70, s[56:57]
	v_pk_fma_f32 v[96:97], v[130:131], v[96:97], v[42:43]
	v_pk_fma_f32 v[26:27], v[26:27], v[80:81], v[40:41]
	v_lshlrev_b32_e32 v80, 16, v83
	v_lshlrev_b32_e32 v130, 16, v82
	v_and_b32_e32 v81, 0xffff0000, v83
	v_and_b32_e32 v131, 0xffff0000, v82
	v_cndmask_b32_e64 v83, 0, v39, s[54:55]
	v_cndmask_b32_e64 v82, 0, v38, s[54:55]
	v_cndmask_b32_e64 v135, 0, v37, s[54:55]
	v_cndmask_b32_e64 v134, 0, v36, s[54:55]
	v_pk_fma_f32 v[26:27], v[134:135], v[130:131], v[26:27]
	v_pk_fma_f32 v[80:81], v[82:83], v[80:81], v[96:97]
	v_lshlrev_b32_e32 v82, 16, v98
	v_lshlrev_b32_e32 v96, 16, v99
	v_and_b32_e32 v83, 0xffff0000, v98
	v_and_b32_e32 v97, 0xffff0000, v99
	v_cndmask_b32_e64 v99, 0, v85, s[52:53]
	v_cndmask_b32_e64 v98, 0, v84, s[52:53]
	v_cndmask_b32_e64 v131, 0, v87, s[52:53]
	v_cndmask_b32_e64 v130, 0, v86, s[52:53]
	v_pk_fma_f32 v[80:81], v[130:131], v[96:97], v[80:81]
	v_pk_fma_f32 v[26:27], v[98:99], v[82:83], v[26:27]
	v_lshlrev_b32_e32 v82, 16, v133
	v_and_b32_e32 v83, 0xffff0000, v133
	v_lshlrev_b32_e32 v96, 16, v132
	v_and_b32_e32 v97, 0xffff0000, v132
	v_pk_fma_f32 v[80:81], v[116:117], v[82:83], v[80:81]
	v_pk_fma_f32 v[96:97], v[118:119], v[96:97], v[26:27]
	v_cvt_pk_bf16_f32 v27, v80, v81
	ds_write2_b32 v124, v80, v81 offset0:38 offset1:39
	ds_write2_b32 v124, v96, v97 offset0:36 offset1:37
	v_mov_b32_dpp v130, v190 row_ror:3 row_mask:0xf bank_mask:0xf
	v_mov_b32_dpp v131, v191 row_ror:3 row_mask:0xf bank_mask:0xf
	v_mov_b32_dpp v132, v192 row_ror:3 row_mask:0xf bank_mask:0xf
	v_mov_b32_dpp v133, v193 row_ror:3 row_mask:0xf bank_mask:0xf
	v_mov_b32_dpp v130, v194 row_shr:3 row_mask:0xf bank_mask:0xf
	v_mov_b32_dpp v131, v195 row_shr:3 row_mask:0xf bank_mask:0xf
	v_mov_b32_dpp v132, v196 row_shr:3 row_mask:0xf bank_mask:0xf
	v_mov_b32_dpp v133, v197 row_shr:3 row_mask:0xf bank_mask:0xf
	v_mov_b32_dpp v124, v190 row_ror:2 row_mask:0xf bank_mask:0xf
	v_mov_b32_dpp v125, v191 row_ror:2 row_mask:0xf bank_mask:0xf
	v_mov_b32_dpp v126, v192 row_ror:2 row_mask:0xf bank_mask:0xf
	v_mov_b32_dpp v127, v193 row_ror:2 row_mask:0xf bank_mask:0xf
	v_mov_b32_dpp v124, v194 row_shr:2 row_mask:0xf bank_mask:0xf
	v_mov_b32_dpp v125, v195 row_shr:2 row_mask:0xf bank_mask:0xf
	v_mov_b32_dpp v126, v196 row_shr:2 row_mask:0xf bank_mask:0xf
	v_mov_b32_dpp v127, v197 row_shr:2 row_mask:0xf bank_mask:0xf
	v_cvt_pk_bf16_f32 v26, v96, v97
	v_mov_b32_dpp v96, v190 row_ror:1 row_mask:0xf bank_mask:0xf
	v_mov_b32_dpp v97, v191 row_ror:1 row_mask:0xf bank_mask:0xf
	v_mov_b32_dpp v98, v192 row_ror:1 row_mask:0xf bank_mask:0xf
	v_mov_b32_dpp v99, v193 row_ror:1 row_mask:0xf bank_mask:0xf
	v_mov_b32_dpp v96, v194 row_shr:1 row_mask:0xf bank_mask:0xf
	v_mov_b32_dpp v97, v195 row_shr:1 row_mask:0xf bank_mask:0xf
	v_mov_b32_dpp v98, v196 row_shr:1 row_mask:0xf bank_mask:0xf
	v_mov_b32_dpp v99, v197 row_shr:1 row_mask:0xf bank_mask:0xf
	v_mov_b64_e32 v[80:81], v[194:195]
	v_mov_b64_e32 v[82:83], v[196:197]
	v_cndmask_b32_e64 v77, 0, v77, s[46:47]
	v_cndmask_b32_e64 v76, 0, v76, s[46:47]
	v_cndmask_b32_e64 v23, 0, v23, s[40:41]
	v_cndmask_b32_e64 v22, 0, v22, s[40:41]
	v_cndmask_b32_e64 v69, 0, v69, s[46:47]
	v_cndmask_b32_e64 v68, 0, v68, s[46:47]
	v_cndmask_b32_e64 v71, 0, v71, s[46:47]
	v_cndmask_b32_e64 v70, 0, v70, s[46:47]
	v_cndmask_b32_e64 v39, 0, v39, s[40:41]
	v_cndmask_b32_e64 v38, 0, v38, s[40:41]
	v_cndmask_b32_e64 v37, 0, v37, s[40:41]
	v_cndmask_b32_e64 v36, 0, v36, s[40:41]
	s_add_u32 s46, s71, s20
	s_addc_u32 s47, s64, 0
	s_ashr_i32 s91, s90, 31
	s_lshl_b64 s[42:43], s[90:91], 9
	s_or_b32 s42, s42, s21
	s_waitcnt vmcnt(0) lgkmcnt(0)
; __device__ __forceinline__ void w_lru_m1(const Args& a, int l, unsigned char* ws, const bf16_t* proj, bf16_t* y, LAS unsigned char* wl, int b, int ck_, int h, int lane) {
;     ...
;         for (int tb = 0; tb < 4; ++tb) { const int tok = 16 * tb + lo, t = 64 * ck_ + tok; float s[8];
; #pragma unroll
;             for (int j = 0; j < 8; ++j) s[j] = bs[j];
; #pragma unroll
;             for (int k = 0; k < 4; ++k) { const int tt = t - 3 + k; float x[8];
;                 ld8bf(proj + (size_t)(b * SEQ + (tt >= 0 ? tt : 0)) * NIN + C_LX + ch0, x);
; #pragma unroll
;                 for (int j = 0; j < 8; ++j) s[j] += (tt >= 0 ? w[k][j] : 0.f) * x[j]; }
;             Xf[tb][kk] = pack_frag(s);
; #pragma unroll
;             for (int j = 0; j < 8; ++j) xcf[tok * 65 + 32 * kk + 8 * fq + j] = s[j]; }
;     ...
;     for (int jb = 0; jb < 4; ++jb) {
;         bf16x8 WaF[2], WxF[2]; f32x4 pba, pbx, plam;
; #pragma unroll
;         for (int kk = 0; kk < 2; ++kk) { WaF[kk] = nWa[kk]; WxF[kk] = nWx[kk]; }
;         pba = nba; pbx = nbx; plam = nlam;
;         if (jb < 3) {
; #pragma unroll
;             for (int kk = 0; kk < 2; ++kk) { nWa[kk] = *(const bf16x8*)(waT + (16 * (jb + 1) + lo) * 64 + 32 * kk + 8 * fq); nWx[kk] = *(const bf16x8*)(wxT + (16 * (jb + 1) + lo) * 64 + 32 * kk + 8 * fq); }
;             nba = *(const f32x4*)(ba + 16 * (jb + 1) + 4 * fq); nbx = *(const f32x4*)(bx + 16 * (jb + 1) + 4 * fq); nlam = *(const f32x4*)(lam + 16 * (jb + 1) + 4 * fq);
;         }
;         const int j0 = 16 * jb + 4 * fq;
;         float bav[4], bxv[4], sp[4], hc[4], Pc[4];
; #pragma unroll
;         for (int r = 0; r < 4; ++r) { bav[r] = pba[r]; bxv[r] = pbx[r]; sp[r] = log1pf(__expf(-plam[r])); hc[r] = 0.f; Pc[r] = 1.f; }
; #pragma unroll
;         for (int tb = 0; tb < 4; ++tb) { const int tok = 16 * tb + lo;
;             f32x4 ga = {0.f, 0.f, 0.f, 0.f}, gx = {0.f, 0.f, 0.f, 0.f};
; #pragma unroll
;             for (int kk = 0; kk < 2; ++kk) { ga = __builtin_amdgcn_mfma_f32_16x16x32_bf16(WaF[kk], Xf[tb][kk], ga, 0, 0, 0); gx = __builtin_amdgcn_mfma_f32_16x16x32_bf16(WxF[kk], Xf[tb][kk], gx, 0, 0, 0); }
;             float hv[4], pv[4];
; #pragma unroll
;             for (int r = 0; r < 4; ++r) {
;                 const float rg = sigmoidf_(ga[r] + bav[r]), ig = sigmoidf_(gx[r] + bxv[r]);
;                 const float la = -8.0f * rg * sp[r]; float A = __expf(la);
	v_lshlrev_b32_e32 v102, 16, v130
	v_lshlrev_b32_e32 v104, 16, v131
	v_and_b32_e32 v103, 0xffff0000, v130
	v_and_b32_e32 v105, 0xffff0000, v131
	v_pk_fma_f32 v[74:75], v[78:79], v[104:105], v[74:75]
	v_pk_fma_f32 v[72:73], v[76:77], v[102:103], v[72:73]
	v_lshlrev_b32_e32 v76, 16, v125
	v_lshlrev_b32_e32 v78, 16, v124
	v_and_b32_e32 v77, 0xffff0000, v125
	v_and_b32_e32 v79, 0xffff0000, v124
	v_pk_fma_f32 v[20:21], v[20:21], v[78:79], v[72:73]
	v_pk_fma_f32 v[22:23], v[22:23], v[76:77], v[74:75]
	v_lshlrev_b32_e32 v72, 16, v96
	v_lshlrev_b32_e32 v74, 16, v97
	v_and_b32_e32 v73, 0xffff0000, v96
	v_and_b32_e32 v75, 0xffff0000, v97
	v_cndmask_b32_e32 v77, 0, v93, vcc
	v_cndmask_b32_e32 v76, 0, v92, vcc
	v_cndmask_b32_e32 v79, 0, v95, vcc
	v_cndmask_b32_e32 v78, 0, v94, vcc
	v_pk_fma_f32 v[22:23], v[78:79], v[74:75], v[22:23]
	v_pk_fma_f32 v[20:21], v[76:77], v[72:73], v[20:21]
	v_lshlrev_b32_e32 v72, 16, v81
	v_and_b32_e32 v73, 0xffff0000, v81
	v_lshlrev_b32_e32 v74, 16, v80
	v_and_b32_e32 v75, 0xffff0000, v80
	v_pk_fma_f32 v[22:23], v[106:107], v[72:73], v[22:23]
	v_pk_fma_f32 v[74:75], v[114:115], v[74:75], v[20:21]
	v_cvt_pk_bf16_f32 v21, v22, v23
	ds_write2_b32 v120, v22, v23 offset0:34 offset1:35
	ds_write2_b32 v120, v74, v75 offset0:32 offset1:33
	v_lshlrev_b32_e32 v22, 16, v132
	v_lshlrev_b32_e32 v72, 16, v133
	v_and_b32_e32 v23, 0xffff0000, v132
	v_and_b32_e32 v73, 0xffff0000, v133
	v_pk_fma_f32 v[42:43], v[70:71], v[72:73], v[42:43]
	v_pk_fma_f32 v[22:23], v[68:69], v[22:23], v[40:41]
	v_lshlrev_b32_e32 v40, 16, v127
	v_lshlrev_b32_e32 v68, 16, v126
	v_and_b32_e32 v41, 0xffff0000, v127
	v_and_b32_e32 v69, 0xffff0000, v126
	v_pk_fma_f32 v[22:23], v[36:37], v[68:69], v[22:23]
	v_pk_fma_f32 v[36:37], v[38:39], v[40:41], v[42:43]
	v_lshlrev_b32_e32 v38, 16, v98
	v_lshlrev_b32_e32 v40, 16, v99
	v_and_b32_e32 v39, 0xffff0000, v98
	v_and_b32_e32 v41, 0xffff0000, v99
	v_cndmask_b32_e32 v43, 0, v85, vcc
	v_cndmask_b32_e32 v42, 0, v84, vcc
	v_cndmask_b32_e32 v69, 0, v87, vcc
	v_cndmask_b32_e32 v68, 0, v86, vcc
	v_pk_fma_f32 v[36:37], v[68:69], v[40:41], v[36:37]
	v_pk_fma_f32 v[22:23], v[42:43], v[38:39], v[22:23]
	v_lshlrev_b32_e32 v38, 16, v83
	v_and_b32_e32 v39, 0xffff0000, v83
	v_lshlrev_b32_e32 v40, 16, v82
	v_and_b32_e32 v41, 0xffff0000, v82
	v_pk_fma_f32 v[36:37], v[116:117], v[38:39], v[36:37]
	v_pk_fma_f32 v[40:41], v[118:119], v[40:41], v[22:23]
	v_cvt_pk_bf16_f32 v23, v36, v37
	ds_write2_b32 v120, v36, v37 offset0:38 offset1:39
	ds_write2_b32 v120, v40, v41 offset0:36 offset1:37
	v_lshlrev_b32_e32 v36, 2, v122
	v_lshl_add_u64 v[118:119], s[92:93], 0, v[100:101]
	v_lshl_add_u64 v[120:121], s[34:35], 0, v[100:101]
	v_and_b32_e32 v143, 0xc0, v36
	v_lshl_add_u64 v[36:37], v[118:119], 0, v[2:3]
	v_lshl_add_u64 v[38:39], v[120:121], 0, v[2:3]
	s_nop 7
	s_waitcnt lgkmcnt(0)
	v_cvt_pk_bf16_f32 v20, v74, v75
	v_cvt_pk_bf16_f32 v22, v40, v41
	s_nop 7
	global_load_dwordx4 v[68:71], v[36:37], off offset:2048
	global_load_dwordx4 v[72:75], v[38:39], off offset:2048
	global_load_dwordx4 v[76:79], v[36:37], off offset:3072
	global_load_dwordx4 v[80:83], v[38:39], off offset:3072
	global_load_dwordx4 v[40:43], v[108:109], off offset:64
	s_nop 0
	global_load_dwordx4 v[36:39], v[110:111], off offset:64
	global_load_dwordx4 v[84:87], v[112:113], off offset:64
	s_nop 7
	v_mov_b32_e32 v104, 1.0
	s_nop 7
	v_mov_b32_e32 v105, 1.0
	s_nop 7
	v_cmp_eq_u32_e32 vcc, 0, v136
	s_nop 0
	s_nop 7
	s_nop 1
	s_nop 7
	s_nop 1
	s_nop 7
	v_mov_b32_e32 v145, v88
	s_nop 7
	s_nop 0
	s_nop 7
	s_nop 0
	s_nop 7
	s_nop 0
	s_nop 7
	s_nop 0
	s_nop 7
	s_nop 0
	s_nop 7
	s_nop 0
	s_nop 7
	s_nop 1
	s_nop 7
	s_nop 1
	s_nop 7
	s_nop 1
	s_nop 7
	v_mov_b32_e32 v147, v89
	s_nop 7
	s_nop 0
	s_nop 7
	s_nop 0
	s_nop 7
	v_mov_b32_e32 v103, 1.0
	s_nop 7
	s_nop 0
	s_nop 7
	s_nop 1
	s_nop 7
	s_nop 1
	s_nop 7
	s_nop 1
	s_nop 7
	v_mov_b32_e32 v2, v90
	s_nop 7
	s_nop 0
	s_nop 7
	s_nop 0
	s_nop 7
	s_nop 0
	s_nop 7
	s_nop 0
	s_nop 7
	v_mov_b32_e32 v100, 1.0
	s_nop 7
	v_mov_b32_e32 v101, 1.0
	s_nop 7
	v_mfma_f32_16x16x32_bf16 v[92:95], v[56:59], v[16:19], 0
	v_mov_b32_e32 v98, 1.0
	s_nop 7
	v_mfma_f32_16x16x32_bf16 v[92:95], v[64:67], v[32:35], v[92:95]
	v_mov_b32_e32 v99, 1.0
	s_nop 7
	s_nop 1
	s_nop 7
	v_mov_b32_e32 v146, v91
	v_and_b32_e32 v88, -16, v122
	v_add_u32_e32 v142, s6, v88
	v_lshlrev_b64 v[88:89], 1, v[0:1]
	v_lshl_add_u64 v[114:115], s[44:45], 0, v[88:89]
	v_lshl_add_u64 v[116:117], s[46:47], 0, v[88:89]
	v_and_b32_e32 v198, 16, v144
	v_lshrrev_b32_e32 v199, 1, v198
	v_add_u32_e32 v198, v198, v199
	v_mov_b32_e32 v199, 0
	v_lshl_add_u64 v[114:115], v[114:115], 0, v[198:199]
	v_lshl_add_u64 v[116:117], v[116:117], 0, v[198:199]
	v_mfma_f32_16x16x32_bf16 v[88:91], v[52:55], v[16:19], 0
	v_mad_u32_u24 v122, v136, s76, v142
	ds_read2_b32 v[124:125], v122 offset1:1
	ds_read2_b32 v[128:129], v122 offset0:2 offset1:3
	v_mfma_f32_16x16x32_bf16 v[88:91], v[60:63], v[32:35], v[88:91]
	v_mov_b32_e32 v102, 1.0
	v_add_u32_e32 v148, v142, v123
	v_add_u32_e32 v150, v142, v141
	s_nop 4
	v_add_f32_e32 v88, v48, v88
	v_add_f32_e32 v89, v49, v89
	v_mul_f32_e32 v88, 0xbfb8aa3b, v88
	v_mul_f32_e32 v89, 0xbfb8aa3b, v89
	v_exp_f32_e32 v88, v88
	v_exp_f32_e32 v89, v89
	v_add_f32_e32 v90, v50, v90
	v_mul_f32_e32 v90, 0xbfb8aa3b, v90
	v_add_f32_e32 v88, 1.0, v88
	v_add_f32_e32 v89, 1.0, v89
	v_rcp_f32_e32 v96, v88
	v_rcp_f32_e32 v97, v89
	v_add_f32_e32 v88, v44, v92
	v_add_f32_e32 v89, v45, v93
	v_mul_f32_e32 v92, 0xc1000000, v96
	v_mul_f32_e32 v93, 0xc1000000, v97
	v_mul_f32_e32 v88, 0xbfb8aa3b, v88
	v_mul_f32_e32 v92, v145, v92
	v_mul_f32_e32 v89, 0xbfb8aa3b, v89
	v_mul_f32_e32 v93, v147, v93
	v_exp_f32_e32 v88, v88
	v_mul_f32_e32 v92, 0x3fb8aa3b, v92
	v_exp_f32_e32 v89, v89
	v_mul_f32_e32 v93, 0x3fb8aa3b, v93
	v_exp_f32_e32 v92, v92
	v_exp_f32_e32 v93, v93
	v_add_f32_e32 v88, 1.0, v88
	v_add_f32_e32 v89, 1.0, v89
	v_rcp_f32_e32 v88, v88
	v_fma_f32 v96, -v92, v92, 1.0
	v_rcp_f32_e32 v89, v89
	v_fma_f32 v97, -v93, v93, 1.0
	v_sqrt_f32_e32 v96, v96
	v_sqrt_f32_e32 v97, v97
	s_waitcnt lgkmcnt(0)
; __device__ __forceinline__ unsigned pk2(float lo, float hi) { const f32x2_t v = {lo, hi}; const bf16x2_t b = __builtin_convertvector(v, bf16x2_t); return __builtin_bit_cast(unsigned, b); }
; __device__ __forceinline__ float sigmoidf_(float x) { return __builtin_amdgcn_rcpf(1.0f + __expf(-x)); }
; __device__ __forceinline__ float bcast15(float v, int lane) { return bperm_f((lane & 48) | 15, v); }
; __device__ __forceinline__ void w_lru_m1(const Args& a, int l, unsigned char* ws, const bf16_t* proj, bf16_t* y, LAS unsigned char* wl, int b, int ck_, int h, int lane) {
;     ...
;         for (int tb = 0; tb < 4; ++tb) { const int tok = 16 * tb + lo;
;             f32x4 ga = {0.f, 0.f, 0.f, 0.f}, gx = {0.f, 0.f, 0.f, 0.f};
; #pragma unroll
;             for (int kk = 0; kk < 2; ++kk) { ga = __builtin_amdgcn_mfma_f32_16x16x32_bf16(WaF[kk], Xf[tb][kk], ga, 0, 0, 0); gx = __builtin_amdgcn_mfma_f32_16x16x32_bf16(WxF[kk], Xf[tb][kk], gx, 0, 0, 0); }
;             float hv[4], pv[4];
; #pragma unroll
;             for (int r = 0; r < 4; ++r) {
;                 const float rg = sigmoidf_(ga[r] + bav[r]), ig = sigmoidf_(gx[r] + bxv[r]);
;                 const float la = -8.0f * rg * sp[r]; float A = __expf(la);
;                 float U = __builtin_amdgcn_sqrtf(1.0f - A * A) * (ig * xcf[tok * 65 + j0 + r]);
;                 { const float As = dpp_shr1<1>(A), Us = dpp_shr0<1>(U); U = A * Us + U; A = A * As; }
;                 { const float As = dpp_shr1<2>(A), Us = dpp_shr0<2>(U); U = A * Us + U; A = A * As; }
;                 { const float As = dpp_shr1<4>(A), Us = dpp_shr0<4>(U); U = A * Us + U; A = A * As; }
;                 { const float As = dpp_shr1<8>(A), Us = dpp_shr0<8>(U); U = A * Us + U; A = A * As; }
;                 const float hh = U + A * hc[r], PP = A * Pc[r];
;                 hc[r] = bcast15(hh, lane); Pc[r] = bcast15(PP, lane); hv[r] = hh; pv[r] = PP; }
;             *(unsigned long long*)(y + (size_t)(row0 + tok) * DM + 64 * h + j0) = (unsigned long long)pk2(hv[0], hv[1]) | ((unsigned long long)pk2(hv[2], hv[3]) << 32);
;             *(unsigned long long*)((bf16_t*)(ws + WS_P) + (size_t)(row0 + tok) * 512 + 64 * h + j0) = (unsigned long long)pk2(pv[0], pv[1]) | ((unsigned long long)pk2(pv[2], pv[3]) << 32);
;         }
	v_pk_mul_f32 v[88:89], v[124:125], v[88:89]
	v_mov_b32_dpp v98, v92 row_shr:1 row_mask:0xf bank_mask:0xf
	v_mov_b32_dpp v99, v93 row_shr:1 row_mask:0xf bank_mask:0xf
	v_pk_mul_f32 v[88:89], v[88:89], v[96:97]
	v_pk_mul_f32 v[98:99], v[92:93], v[98:99]
	v_exp_f32_e32 v90, v90
	v_mov_b32_dpp v96, v88 row_shr:1 row_mask:0xf bank_mask:0xf bound_ctrl:1
	v_mov_b32_dpp v97, v89 row_shr:1 row_mask:0xf bank_mask:0xf bound_ctrl:1
	v_pk_fma_f32 v[88:89], v[92:93], v[96:97], v[88:89]
	v_mov_b32_dpp v100, v98 row_shr:2 row_mask:0xf bank_mask:0xf
	v_mov_b32_dpp v101, v99 row_shr:2 row_mask:0xf bank_mask:0xf
	v_mov_b32_dpp v92, v88 row_shr:2 row_mask:0xf bank_mask:0xf bound_ctrl:1
	v_mov_b32_dpp v93, v89 row_shr:2 row_mask:0xf bank_mask:0xf bound_ctrl:1
	v_pk_fma_f32 v[88:89], v[98:99], v[92:93], v[88:89]
	v_pk_mul_f32 v[100:101], v[98:99], v[100:101]
	v_add_f32_e32 v90, 1.0, v90
	v_mov_b32_dpp v92, v88 row_shr:4 row_mask:0xf bank_mask:0xf bound_ctrl:1
	v_mov_b32_dpp v93, v89 row_shr:4 row_mask:0xf bank_mask:0xf bound_ctrl:1
	v_mov_b32_dpp v102, v100 row_shr:4 row_mask:0xf bank_mask:0xf
	v_mov_b32_dpp v103, v101 row_shr:4 row_mask:0xf bank_mask:0xf
	v_pk_fma_f32 v[88:89], v[100:101], v[92:93], v[88:89]
	v_pk_mul_f32 v[102:103], v[100:101], v[102:103]
	v_add_f32_e32 v91, v51, v91
	v_mov_b32_dpp v92, v88 row_shr:8 row_mask:0xf bank_mask:0xf bound_ctrl:1
	v_mov_b32_dpp v93, v89 row_shr:8 row_mask:0xf bank_mask:0xf bound_ctrl:1
	v_pk_fma_f32 v[88:89], v[102:103], v[92:93], v[88:89]
	v_rcp_f32_e32 v92, v90
	v_mul_f32_e32 v91, 0xbfb8aa3b, v91
	v_exp_f32_e32 v91, v91
	v_add_f32_e32 v90, v46, v94
	v_mul_f32_e32 v92, 0xc1000000, v92
	v_mul_f32_e32 v92, v2, v92
	v_mul_f32_e32 v92, 0x3fb8aa3b, v92
	v_exp_f32_e32 v92, v92
	v_add_f32_e32 v91, 1.0, v91
	v_mul_f32_e32 v90, 0xbfb8aa3b, v90
	v_exp_f32_e32 v90, v90
	v_fma_f32 v93, -v92, v92, 1.0
	v_sqrt_f32_e32 v94, v93
	v_rcp_f32_e32 v93, v91
	v_add_f32_e32 v91, v47, v95
	v_mul_f32_e32 v91, 0xbfb8aa3b, v91
	v_exp_f32_e32 v91, v91
	v_mul_f32_e32 v93, 0xc1000000, v93
	v_mul_f32_e32 v93, v146, v93
	v_mul_f32_e32 v93, 0x3fb8aa3b, v93
	v_exp_f32_e32 v93, v93
	v_add_f32_e32 v90, 1.0, v90
	v_add_f32_e32 v91, 1.0, v91
	v_rcp_f32_e32 v90, v90
	v_rcp_f32_e32 v91, v91
	v_fma_f32 v95, -v93, v93, 1.0
	v_sqrt_f32_e32 v95, v95
	v_mov_b32_e32 v96, 1.0
	v_pk_mul_f32 v[90:91], v[90:91], v[128:129]
	v_mov_b32_e32 v97, 1.0
	v_pk_mul_f32 v[90:91], v[94:95], v[90:91]
	v_mov_b32_dpp v96, v92 row_shr:1 row_mask:0xf bank_mask:0xf
	v_mov_b32_dpp v97, v93 row_shr:1 row_mask:0xf bank_mask:0xf
	v_mov_b32_dpp v94, v90 row_shr:1 row_mask:0xf bank_mask:0xf bound_ctrl:1
	v_mov_b32_dpp v95, v91 row_shr:1 row_mask:0xf bank_mask:0xf bound_ctrl:1
	v_pk_mul_f32 v[96:97], v[92:93], v[96:97]
	v_mov_b32_e32 v100, 1.0
	v_mov_b32_e32 v101, 1.0
	v_pk_fma_f32 v[90:91], v[92:93], v[94:95], v[90:91]
	v_mov_b32_dpp v104, v102 row_shr:8 row_mask:0xf bank_mask:0xf
	v_mov_b32_dpp v105, v103 row_shr:8 row_mask:0xf bank_mask:0xf
	v_mov_b32_dpp v100, v96 row_shr:2 row_mask:0xf bank_mask:0xf
	v_mov_b32_dpp v101, v97 row_shr:2 row_mask:0xf bank_mask:0xf
	v_mov_b32_dpp v92, v90 row_shr:2 row_mask:0xf bank_mask:0xf bound_ctrl:1
	v_mov_b32_dpp v93, v91 row_shr:2 row_mask:0xf bank_mask:0xf bound_ctrl:1
	v_pk_mul_f32 v[106:107], v[102:103], v[104:105]
	v_pk_mul_f32 v[100:101], v[96:97], v[100:101]
	v_mov_b32_e32 v102, 1.0
	v_mov_b32_e32 v103, 1.0
	v_pk_fma_f32 v[90:91], v[96:97], v[92:93], v[90:91]
	v_mov_b32_dpp v102, v100 row_shr:4 row_mask:0xf bank_mask:0xf
	v_mov_b32_dpp v103, v101 row_shr:4 row_mask:0xf bank_mask:0xf
	v_mov_b32_dpp v92, v90 row_shr:4 row_mask:0xf bank_mask:0xf bound_ctrl:1
	v_mov_b32_dpp v93, v91 row_shr:4 row_mask:0xf bank_mask:0xf bound_ctrl:1
	v_pk_mul_f32 v[102:103], v[100:101], v[102:103]
	v_mov_b32_e32 v124, 1.0
	v_mov_b32_e32 v125, 1.0
	v_pk_fma_f32 v[90:91], v[100:101], v[92:93], v[90:91]
	v_mov_b32_dpp v124, v102 row_shr:8 row_mask:0xf bank_mask:0xf
	v_mov_b32_dpp v125, v103 row_shr:8 row_mask:0xf bank_mask:0xf
	v_mov_b32_dpp v92, v90 row_shr:8 row_mask:0xf bank_mask:0xf bound_ctrl:1
	v_mov_b32_dpp v93, v91 row_shr:8 row_mask:0xf bank_mask:0xf bound_ctrl:1
	v_pk_mul_f32 v[126:127], v[102:103], v[124:125]
	v_pk_fma_f32 v[90:91], v[102:103], v[92:93], v[90:91]
	v_pk_fma_f32 v[88:89], v[106:107], 0, v[88:89] op_sel_hi:[1,0,1]
	v_pk_fma_f32 v[90:91], v[126:127], 0, v[90:91] op_sel_hi:[1,0,1]
	ds_bpermute_b32 v98, v143, v88 offset:60
	ds_bpermute_b32 v99, v143, v89 offset:60
	ds_bpermute_b32 v96, v143, v90 offset:60
	v_cvt_pk_bf16_f32 v88, v88, v89
	v_cvt_pk_bf16_f32 v89, v90, v91
	v_or_b32_e32 v90, s48, v136
	ds_bpermute_b32 v97, v143, v91 offset:60
	v_ashrrev_i32_e32 v91, 31, v90
	v_lshlrev_b64 v[92:93], 11, v[90:91]
	v_lshl_add_u64 v[100:101], v[114:115], 0, v[92:93]
	v_lshlrev_b64 v[90:91], 10, v[90:91]
	v_mov_b64_e32 v[222:223], v[88:89]
	v_cvt_pk_bf16_f32 v88, v106, v107
	v_cvt_pk_bf16_f32 v89, v126, v127
	v_lshl_add_u64 v[102:103], v[116:117], 0, v[90:91]
	v_mov_b64_e32 v[226:227], v[88:89]
	v_mfma_f32_16x16x32_bf16 v[88:91], v[52:55], v[12:15], 0
	ds_bpermute_b32 v124, v143, v126 offset:60
	ds_bpermute_b32 v125, v143, v127 offset:60
	ds_bpermute_b32 v104, v143, v106 offset:60
	v_mfma_f32_16x16x32_bf16 v[126:129], v[56:59], v[12:15], 0
	ds_bpermute_b32 v105, v143, v107 offset:60
	v_mfma_f32_16x16x32_bf16 v[92:95], v[60:63], v[28:31], v[88:91]
	v_mfma_f32_16x16x32_bf16 v[88:91], v[64:67], v[28:31], v[126:129]
	s_nop 6
	v_add_f32_e32 v92, v48, v92
	v_mul_f32_e32 v92, 0xbfb8aa3b, v92
	v_exp_f32_e32 v92, v92
	v_add_f32_e32 v88, v44, v88
	v_mul_f32_e32 v88, 0xbfb8aa3b, v88
	v_exp_f32_e32 v88, v88
	v_add_f32_e32 v92, 1.0, v92
	v_rcp_f32_e32 v92, v92
; __device__ __forceinline__ unsigned pk2(float lo, float hi) { const f32x2_t v = {lo, hi}; const bf16x2_t b = __builtin_convertvector(v, bf16x2_t); return __builtin_bit_cast(unsigned, b); }
; __device__ __forceinline__ float sigmoidf_(float x) { return __builtin_amdgcn_rcpf(1.0f + __expf(-x)); }
; __device__ __forceinline__ float bcast15(float v, int lane) { return bperm_f((lane & 48) | 15, v); }
; __device__ __forceinline__ void w_lru_m1(const Args& a, int l, unsigned char* ws, const bf16_t* proj, bf16_t* y, LAS unsigned char* wl, int b, int ck_, int h, int lane) {
;     ...
;         for (int tb = 0; tb < 4; ++tb) { const int tok = 16 * tb + lo;
;             f32x4 ga = {0.f, 0.f, 0.f, 0.f}, gx = {0.f, 0.f, 0.f, 0.f};
; #pragma unroll
;             for (int kk = 0; kk < 2; ++kk) { ga = __builtin_amdgcn_mfma_f32_16x16x32_bf16(WaF[kk], Xf[tb][kk], ga, 0, 0, 0); gx = __builtin_amdgcn_mfma_f32_16x16x32_bf16(WxF[kk], Xf[tb][kk], gx, 0, 0, 0); }
;             float hv[4], pv[4];
; #pragma unroll
;             for (int r = 0; r < 4; ++r) {
;                 const float rg = sigmoidf_(ga[r] + bav[r]), ig = sigmoidf_(gx[r] + bxv[r]);
;                 const float la = -8.0f * rg * sp[r]; float A = __expf(la);
;                 float U = __builtin_amdgcn_sqrtf(1.0f - A * A) * (ig * xcf[tok * 65 + j0 + r]);
;                 { const float As = dpp_shr1<1>(A), Us = dpp_shr0<1>(U); U = A * Us + U; A = A * As; }
;                 { const float As = dpp_shr1<2>(A), Us = dpp_shr0<2>(U); U = A * Us + U; A = A * As; }
;                 { const float As = dpp_shr1<4>(A), Us = dpp_shr0<4>(U); U = A * Us + U; A = A * As; }
;                 { const float As = dpp_shr1<8>(A), Us = dpp_shr0<8>(U); U = A * Us + U; A = A * As; }
;                 const float hh = U + A * hc[r], PP = A * Pc[r];
;                 hc[r] = bcast15(hh, lane); Pc[r] = bcast15(PP, lane); hv[r] = hh; pv[r] = PP; }
;             *(unsigned long long*)(y + (size_t)(row0 + tok) * DM + 64 * h + j0) = (unsigned long long)pk2(hv[0], hv[1]) | ((unsigned long long)pk2(hv[2], hv[3]) << 32);
;             *(unsigned long long*)((bf16_t*)(ws + WS_P) + (size_t)(row0 + tok) * 512 + 64 * h + j0) = (unsigned long long)pk2(pv[0], pv[1]) | ((unsigned long long)pk2(pv[2], pv[3]) << 32);
;         }
	v_add_f32_e32 v89, v45, v89
	v_add_f32_e32 v88, 1.0, v88
	v_rcp_f32_e32 v106, v88
	v_mul_f32_e32 v88, 0xc1000000, v92
	v_add_f32_e32 v92, v49, v93
	v_mul_f32_e32 v92, 0xbfb8aa3b, v92
	v_exp_f32_e32 v92, v92
	v_mul_f32_e32 v89, 0xbfb8aa3b, v89
	v_exp_f32_e32 v89, v89
	v_mul_f32_e32 v88, v145, v88
	v_add_f32_e32 v92, 1.0, v92
	v_rcp_f32_e32 v92, v92
	v_add_f32_e32 v89, 1.0, v89
	v_rcp_f32_e32 v107, v89
	v_mul_f32_e32 v88, 0x3fb8aa3b, v88
	v_mul_f32_e32 v89, 0xc1000000, v92
	v_mul_f32_e32 v89, v147, v89
	v_mul_f32_e32 v89, 0x3fb8aa3b, v89
	v_exp_f32_e32 v122, v88
	v_exp_f32_e32 v123, v89
	v_add_f32_e32 v94, v50, v94
	v_add_f32_e32 v95, v51, v95
	v_fma_f32 v88, -v122, v122, 1.0
	v_fma_f32 v89, -v123, v123, 1.0
	v_sqrt_f32_e32 v126, v88
	v_mov_b32_e32 v88, 1.0
	v_sqrt_f32_e32 v127, v89
	v_mov_b32_e32 v89, 1.0
	v_mov_b32_dpp v88, v122 row_shr:1 row_mask:0xf bank_mask:0xf
	v_mul_f32_e32 v94, 0xbfb8aa3b, v94
	v_mov_b32_dpp v89, v123 row_shr:1 row_mask:0xf bank_mask:0xf
	v_pk_mul_f32 v[128:129], v[122:123], v[88:89]
	v_mov_b32_e32 v88, 1.0
	v_mov_b32_e32 v89, 1.0
	v_mul_f32_e32 v95, 0xbfb8aa3b, v95
	v_mov_b32_dpp v88, v128 row_shr:2 row_mask:0xf bank_mask:0xf
	v_mov_b32_dpp v89, v129 row_shr:2 row_mask:0xf bank_mask:0xf
	v_pk_mul_f32 v[130:131], v[128:129], v[88:89]
	v_mov_b32_e32 v88, 1.0
	v_mov_b32_e32 v89, 1.0
	v_exp_f32_e32 v94, v94
	v_mov_b32_dpp v88, v130 row_shr:4 row_mask:0xf bank_mask:0xf
	v_mov_b32_dpp v89, v131 row_shr:4 row_mask:0xf bank_mask:0xf
	v_pk_mul_f32 v[132:133], v[130:131], v[88:89]
	v_mov_b32_e32 v88, 1.0
	v_mov_b32_e32 v89, 1.0
	v_exp_f32_e32 v95, v95
	v_mov_b32_dpp v88, v132 row_shr:8 row_mask:0xf bank_mask:0xf
	v_mov_b32_dpp v89, v133 row_shr:8 row_mask:0xf bank_mask:0xf
	v_pk_mul_f32 v[134:135], v[132:133], v[88:89]
	v_add_f32_e32 v90, v46, v90
	s_waitcnt lgkmcnt(0)
	v_pk_mul_f32 v[92:93], v[134:135], v[104:105]
	ds_read2_b32 v[104:105], v148 offset1:1
	v_add_f32_e32 v91, v47, v91
	v_mul_f32_e32 v90, 0xbfb8aa3b, v90
	v_mul_f32_e32 v91, 0xbfb8aa3b, v91
	v_add_f32_e32 v94, 1.0, v94
	s_waitcnt lgkmcnt(0)
	v_pk_mul_f32 v[104:105], v[104:105], v[106:107]
	v_exp_f32_e32 v90, v90
	v_pk_mul_f32 v[104:105], v[104:105], v[126:127]
	v_add_f32_e32 v95, 1.0, v95
	v_exp_f32_e32 v91, v91
	v_mov_b32_dpp v106, v104 row_shr:1 row_mask:0xf bank_mask:0xf bound_ctrl:1
	v_mov_b32_dpp v107, v105 row_shr:1 row_mask:0xf bank_mask:0xf bound_ctrl:1
	v_pk_fma_f32 v[104:105], v[122:123], v[106:107], v[104:105]
	v_rcp_f32_e32 v94, v94
	v_rcp_f32_e32 v95, v95
	v_mov_b32_dpp v106, v104 row_shr:2 row_mask:0xf bank_mask:0xf bound_ctrl:1
	v_mov_b32_dpp v107, v105 row_shr:2 row_mask:0xf bank_mask:0xf bound_ctrl:1
	v_pk_fma_f32 v[104:105], v[128:129], v[106:107], v[104:105]
	v_add_f32_e32 v90, 1.0, v90
	v_add_f32_e32 v91, 1.0, v91
	v_mov_b32_dpp v106, v104 row_shr:4 row_mask:0xf bank_mask:0xf bound_ctrl:1
	v_mov_b32_dpp v107, v105 row_shr:4 row_mask:0xf bank_mask:0xf bound_ctrl:1
	v_pk_fma_f32 v[104:105], v[130:131], v[106:107], v[104:105]
	ds_bpermute_b32 v88, v143, v92 offset:60
	ds_bpermute_b32 v89, v143, v93 offset:60
	v_mov_b32_dpp v106, v104 row_shr:8 row_mask:0xf bank_mask:0xf bound_ctrl:1
	v_mov_b32_dpp v107, v105 row_shr:8 row_mask:0xf bank_mask:0xf bound_ctrl:1
	v_pk_fma_f32 v[104:105], v[132:133], v[106:107], v[104:105]
	v_rcp_f32_e32 v106, v90
	v_mul_f32_e32 v90, 0xc1000000, v94
	v_rcp_f32_e32 v107, v91
	v_mul_f32_e32 v91, 0xc1000000, v95
	v_mul_f32_e32 v90, v2, v90
	v_mul_f32_e32 v91, v146, v91
	v_mul_f32_e32 v90, 0x3fb8aa3b, v90
	v_mul_f32_e32 v91, 0x3fb8aa3b, v91
	v_exp_f32_e32 v94, v90
	v_exp_f32_e32 v95, v91
	v_pk_fma_f32 v[104:105], v[134:135], v[98:99], v[104:105]
	ds_read2_b32 v[134:135], v148 offset0:2 offset1:3
	v_fma_f32 v90, -v94, v94, 1.0
	v_fma_f32 v91, -v95, v95, 1.0
	v_sqrt_f32_e32 v122, v90
	v_sqrt_f32_e32 v123, v91
	s_waitcnt lgkmcnt(0)
	v_pk_mul_f32 v[106:107], v[106:107], v[134:135]
	v_mov_b32_e32 v90, 1.0
	v_mov_b32_e32 v91, 1.0
	v_pk_mul_f32 v[106:107], v[122:123], v[106:107]
	v_mov_b32_dpp v90, v94 row_shr:1 row_mask:0xf bank_mask:0xf
	v_mov_b32_dpp v91, v95 row_shr:1 row_mask:0xf bank_mask:0xf
	v_mov_b32_dpp v122, v106 row_shr:1 row_mask:0xf bank_mask:0xf bound_ctrl:1
	v_mov_b32_dpp v123, v107 row_shr:1 row_mask:0xf bank_mask:0xf bound_ctrl:1
	v_pk_mul_f32 v[126:127], v[94:95], v[90:91]
	v_mov_b32_e32 v90, 1.0
	v_mov_b32_e32 v91, 1.0
	v_pk_fma_f32 v[94:95], v[94:95], v[122:123], v[106:107]
	v_mov_b32_dpp v90, v126 row_shr:2 row_mask:0xf bank_mask:0xf
	v_mov_b32_dpp v91, v127 row_shr:2 row_mask:0xf bank_mask:0xf
	v_mov_b32_dpp v106, v94 row_shr:2 row_mask:0xf bank_mask:0xf bound_ctrl:1
	v_mov_b32_dpp v107, v95 row_shr:2 row_mask:0xf bank_mask:0xf bound_ctrl:1
	v_pk_mul_f32 v[128:129], v[126:127], v[90:91]
	v_mov_b32_e32 v90, 1.0
	v_mov_b32_e32 v91, 1.0
	v_pk_fma_f32 v[94:95], v[126:127], v[106:107], v[94:95]
	v_mov_b32_dpp v90, v128 row_shr:4 row_mask:0xf bank_mask:0xf
	v_mov_b32_dpp v91, v129 row_shr:4 row_mask:0xf bank_mask:0xf
	v_mov_b32_dpp v106, v94 row_shr:4 row_mask:0xf bank_mask:0xf bound_ctrl:1
	v_mov_b32_dpp v107, v95 row_shr:4 row_mask:0xf bank_mask:0xf bound_ctrl:1
	v_pk_mul_f32 v[130:131], v[128:129], v[90:91]
	v_mov_b32_e32 v90, 1.0
	v_mov_b32_e32 v91, 1.0
	v_pk_fma_f32 v[94:95], v[128:129], v[106:107], v[94:95]
	v_mov_b32_dpp v90, v130 row_shr:8 row_mask:0xf bank_mask:0xf
	v_mov_b32_dpp v91, v131 row_shr:8 row_mask:0xf bank_mask:0xf
	v_mov_b32_dpp v106, v94 row_shr:8 row_mask:0xf bank_mask:0xf bound_ctrl:1
	v_mov_b32_dpp v107, v95 row_shr:8 row_mask:0xf bank_mask:0xf bound_ctrl:1
	v_pk_mul_f32 v[132:133], v[130:131], v[90:91]
	v_pk_fma_f32 v[94:95], v[130:131], v[106:107], v[94:95]
; __device__ __forceinline__ unsigned pk2(float lo, float hi) { const f32x2_t v = {lo, hi}; const bf16x2_t b = __builtin_convertvector(v, bf16x2_t); return __builtin_bit_cast(unsigned, b); }
; __device__ __forceinline__ float sigmoidf_(float x) { return __builtin_amdgcn_rcpf(1.0f + __expf(-x)); }
; __device__ __forceinline__ float bcast15(float v, int lane) { return bperm_f((lane & 48) | 15, v); }
; __device__ __forceinline__ void w_lru_m1(const Args& a, int l, unsigned char* ws, const bf16_t* proj, bf16_t* y, LAS unsigned char* wl, int b, int ck_, int h, int lane) {
;     ...
;         for (int tb = 0; tb < 4; ++tb) { const int tok = 16 * tb + lo;
;             f32x4 ga = {0.f, 0.f, 0.f, 0.f}, gx = {0.f, 0.f, 0.f, 0.f};
; #pragma unroll
;             for (int kk = 0; kk < 2; ++kk) { ga = __builtin_amdgcn_mfma_f32_16x16x32_bf16(WaF[kk], Xf[tb][kk], ga, 0, 0, 0); gx = __builtin_amdgcn_mfma_f32_16x16x32_bf16(WxF[kk], Xf[tb][kk], gx, 0, 0, 0); }
;             float hv[4], pv[4];
; #pragma unroll
;             for (int r = 0; r < 4; ++r) {
;                 const float rg = sigmoidf_(ga[r] + bav[r]), ig = sigmoidf_(gx[r] + bxv[r]);
;                 const float la = -8.0f * rg * sp[r]; float A = __expf(la);
;                 float U = __builtin_amdgcn_sqrtf(1.0f - A * A) * (ig * xcf[tok * 65 + j0 + r]);
;                 { const float As = dpp_shr1<1>(A), Us = dpp_shr0<1>(U); U = A * Us + U; A = A * As; }
;                 { const float As = dpp_shr1<2>(A), Us = dpp_shr0<2>(U); U = A * Us + U; A = A * As; }
;                 { const float As = dpp_shr1<4>(A), Us = dpp_shr0<4>(U); U = A * Us + U; A = A * As; }
;                 { const float As = dpp_shr1<8>(A), Us = dpp_shr0<8>(U); U = A * Us + U; A = A * As; }
;                 const float hh = U + A * hc[r], PP = A * Pc[r];
;                 hc[r] = bcast15(hh, lane); Pc[r] = bcast15(PP, lane); hv[r] = hh; pv[r] = PP; }
;             *(unsigned long long*)(y + (size_t)(row0 + tok) * DM + 64 * h + j0) = (unsigned long long)pk2(hv[0], hv[1]) | ((unsigned long long)pk2(hv[2], hv[3]) << 32);
;             *(unsigned long long*)((bf16_t*)(ws + WS_P) + (size_t)(row0 + tok) * 512 + 64 * h + j0) = (unsigned long long)pk2(pv[0], pv[1]) | ((unsigned long long)pk2(pv[2], pv[3]) << 32);
;         }
	ds_bpermute_b32 v98, v143, v104 offset:60
	v_pk_fma_f32 v[94:95], v[132:133], v[96:97], v[94:95]
	ds_bpermute_b32 v96, v143, v94 offset:60
	v_cvt_pk_bf16_f32 v107, v94, v95
	v_or_b32_e32 v94, s48, v140
	ds_bpermute_b32 v97, v143, v95 offset:60
	v_ashrrev_i32_e32 v95, 31, v94
	ds_bpermute_b32 v99, v143, v105 offset:60
	v_cvt_pk_bf16_f32 v106, v104, v105
	v_lshlrev_b64 v[104:105], 11, v[94:95]
	v_pk_mul_f32 v[124:125], v[132:133], v[124:125]
	v_lshl_add_u64 v[104:105], v[114:115], 0, v[104:105]
	v_lshlrev_b64 v[94:95], 10, v[94:95]
	v_mov_b64_e32 v[230:231], v[106:107]
	v_cvt_pk_bf16_f32 v92, v92, v93
	v_cvt_pk_bf16_f32 v93, v124, v125
	v_lshl_add_u64 v[106:107], v[116:117], 0, v[94:95]
	v_mov_b64_e32 v[234:235], v[92:93]
	v_mfma_f32_16x16x32_bf16 v[92:95], v[52:55], v[8:11], 0
	ds_bpermute_b32 v90, v143, v124 offset:60
	ds_bpermute_b32 v91, v143, v125 offset:60
	v_mfma_f32_16x16x32_bf16 v[126:129], v[60:63], v[24:27], v[92:95]
	v_mfma_f32_16x16x32_bf16 v[122:125], v[56:59], v[8:11], 0
	v_mfma_f32_16x16x32_bf16 v[122:125], v[64:67], v[24:27], v[122:125]
	s_nop 5
	v_add_f32_e32 v92, v48, v126
	v_mul_f32_e32 v92, 0xbfb8aa3b, v92
	v_exp_f32_e32 v92, v92
	v_mfma_f32_16x16x32_bf16 v[52:55], v[52:55], v[4:7], 0
	v_add_f32_e32 v92, 1.0, v92
	v_rcp_f32_e32 v93, v92
	v_add_f32_e32 v92, v44, v122
	v_mov_b32_e32 v122, 1.0
	v_mul_f32_e32 v92, 0xbfb8aa3b, v92
	v_mul_f32_e32 v93, 0xc1000000, v93
	v_mul_f32_e32 v93, v145, v93
	v_mul_f32_e32 v93, 0x3fb8aa3b, v93
	v_exp_f32_e32 v94, v93
	v_exp_f32_e32 v92, v92
	v_fma_f32 v93, -v94, v94, 1.0
	v_sqrt_f32_e32 v126, v93
	v_add_f32_e32 v93, v49, v127
	v_mul_f32_e32 v93, 0xbfb8aa3b, v93
	v_exp_f32_e32 v93, v93
	v_mov_b32_dpp v122, v94 row_shr:1 row_mask:0xf bank_mask:0xf
	v_add_f32_e32 v92, 1.0, v92
	v_rcp_f32_e32 v92, v92
	v_add_f32_e32 v93, 1.0, v93
	v_rcp_f32_e32 v95, v93
	v_add_f32_e32 v93, v45, v123
	v_mul_f32_e32 v93, 0xbfb8aa3b, v93
	v_exp_f32_e32 v93, v93
	v_mul_f32_e32 v95, 0xc1000000, v95
	v_mul_f32_e32 v95, v147, v95
	v_mul_f32_e32 v95, 0x3fb8aa3b, v95
	v_exp_f32_e32 v95, v95
	v_add_f32_e32 v93, 1.0, v93
	v_rcp_f32_e32 v93, v93
	v_fma_f32 v123, -v95, v95, 1.0
	v_sqrt_f32_e32 v127, v123
	v_mov_b32_e32 v123, 1.0
	s_nop 1
	v_mov_b32_dpp v123, v95 row_shr:1 row_mask:0xf bank_mask:0xf
	v_pk_mul_f32 v[130:131], v[94:95], v[122:123]
	v_mov_b32_e32 v122, 1.0
	v_mov_b32_e32 v123, 1.0
	s_nop 0
	v_mov_b32_dpp v122, v130 row_shr:2 row_mask:0xf bank_mask:0xf
	v_mov_b32_dpp v123, v131 row_shr:2 row_mask:0xf bank_mask:0xf
	v_pk_mul_f32 v[132:133], v[130:131], v[122:123]
	v_mov_b32_e32 v122, 1.0
	v_mov_b32_e32 v123, 1.0
	s_nop 0
	v_mov_b32_dpp v122, v132 row_shr:4 row_mask:0xf bank_mask:0xf
	v_mov_b32_dpp v123, v133 row_shr:4 row_mask:0xf bank_mask:0xf
	v_pk_mul_f32 v[134:135], v[132:133], v[122:123]
	v_mov_b32_e32 v122, 1.0
	v_mov_b32_e32 v123, 1.0
	s_nop 0
	v_mov_b32_dpp v122, v134 row_shr:8 row_mask:0xf bank_mask:0xf
	v_mov_b32_dpp v123, v135 row_shr:8 row_mask:0xf bank_mask:0xf
	v_pk_mul_f32 v[140:141], v[134:135], v[122:123]
	s_nop 0
	v_pk_mul_f32 v[148:149], v[140:141], v[88:89]
	ds_read2_b32 v[88:89], v150 offset1:1
	ds_bpermute_b32 v122, v143, v148 offset:60
	ds_bpermute_b32 v123, v143, v149 offset:60
	s_waitcnt lgkmcnt(0)
	v_pk_mul_f32 v[88:89], v[88:89], v[92:93]
	s_nop 0
	v_pk_mul_f32 v[88:89], v[88:89], v[126:127]
	s_nop 1
	v_mov_b32_dpp v92, v88 row_shr:1 row_mask:0xf bank_mask:0xf bound_ctrl:1
	v_mov_b32_dpp v93, v89 row_shr:1 row_mask:0xf bank_mask:0xf bound_ctrl:1
	v_pk_fma_f32 v[88:89], v[94:95], v[92:93], v[88:89]
	s_nop 1
	v_mov_b32_dpp v92, v88 row_shr:2 row_mask:0xf bank_mask:0xf bound_ctrl:1
	v_mov_b32_dpp v93, v89 row_shr:2 row_mask:0xf bank_mask:0xf bound_ctrl:1
	v_pk_fma_f32 v[88:89], v[130:131], v[92:93], v[88:89]
	s_nop 1
	v_mov_b32_dpp v92, v88 row_shr:4 row_mask:0xf bank_mask:0xf bound_ctrl:1
	v_mov_b32_dpp v93, v89 row_shr:4 row_mask:0xf bank_mask:0xf bound_ctrl:1
	v_pk_fma_f32 v[88:89], v[132:133], v[92:93], v[88:89]
	s_nop 1
	v_mov_b32_dpp v92, v88 row_shr:8 row_mask:0xf bank_mask:0xf bound_ctrl:1
	v_mov_b32_dpp v93, v89 row_shr:8 row_mask:0xf bank_mask:0xf bound_ctrl:1
	v_pk_fma_f32 v[88:89], v[134:135], v[92:93], v[88:89]
	v_mov_b32_e32 v92, 1.0
	v_pk_fma_f32 v[98:99], v[140:141], v[98:99], v[88:89]
	v_add_f32_e32 v88, v50, v128
	v_mul_f32_e32 v88, 0xbfb8aa3b, v88
	v_exp_f32_e32 v88, v88
	ds_read2_b32 v[140:141], v150 offset0:2 offset1:3
	ds_bpermute_b32 v94, v143, v98 offset:60
	ds_bpermute_b32 v95, v143, v99 offset:60
	v_add_f32_e32 v88, 1.0, v88
	v_rcp_f32_e32 v89, v88
	v_add_f32_e32 v88, v46, v124
	v_mul_f32_e32 v88, 0xbfb8aa3b, v88
	v_exp_f32_e32 v88, v88
	v_mul_f32_e32 v89, 0xc1000000, v89
	v_mul_f32_e32 v89, v2, v89
	v_mul_f32_e32 v89, 0x3fb8aa3b, v89
	v_exp_f32_e32 v124, v89
	v_add_f32_e32 v88, 1.0, v88
	v_rcp_f32_e32 v88, v88
	v_cvt_pk_bf16_f32 v98, v98, v99
	v_fma_f32 v89, -v124, v124, 1.0
	v_sqrt_f32_e32 v126, v89
	v_add_f32_e32 v89, v51, v129
	v_mul_f32_e32 v89, 0xbfb8aa3b, v89
	v_exp_f32_e32 v89, v89
	v_mov_b32_dpp v92, v124 row_shr:1 row_mask:0xf bank_mask:0xf
	v_add_f32_e32 v89, 1.0, v89
	v_rcp_f32_e32 v93, v89
	v_add_f32_e32 v89, v47, v125
	v_mul_f32_e32 v89, 0xbfb8aa3b, v89
	v_exp_f32_e32 v89, v89
	v_mul_f32_e32 v93, 0xc1000000, v93
	v_mul_f32_e32 v93, v146, v93
	v_mul_f32_e32 v93, 0x3fb8aa3b, v93
	v_exp_f32_e32 v125, v93
	v_add_f32_e32 v89, 1.0, v89
	v_rcp_f32_e32 v89, v89
	v_fma_f32 v93, -v125, v125, 1.0
	v_sqrt_f32_e32 v127, v93
	s_waitcnt lgkmcnt(0)
; __device__ __forceinline__ unsigned pk2(float lo, float hi) { const f32x2_t v = {lo, hi}; const bf16x2_t b = __builtin_convertvector(v, bf16x2_t); return __builtin_bit_cast(unsigned, b); }
; __device__ __forceinline__ float sigmoidf_(float x) { return __builtin_amdgcn_rcpf(1.0f + __expf(-x)); }
; __device__ __forceinline__ float bcast15(float v, int lane) { return bperm_f((lane & 48) | 15, v); }
; __device__ __forceinline__ void w_lru_m1(const Args& a, int l, unsigned char* ws, const bf16_t* proj, bf16_t* y, LAS unsigned char* wl, int b, int ck_, int h, int lane) {
;     ...
;         for (int tb = 0; tb < 4; ++tb) { const int tok = 16 * tb + lo;
;             f32x4 ga = {0.f, 0.f, 0.f, 0.f}, gx = {0.f, 0.f, 0.f, 0.f};
; #pragma unroll
;             for (int kk = 0; kk < 2; ++kk) { ga = __builtin_amdgcn_mfma_f32_16x16x32_bf16(WaF[kk], Xf[tb][kk], ga, 0, 0, 0); gx = __builtin_amdgcn_mfma_f32_16x16x32_bf16(WxF[kk], Xf[tb][kk], gx, 0, 0, 0); }
;             float hv[4], pv[4];
; #pragma unroll
;             for (int r = 0; r < 4; ++r) {
;                 const float rg = sigmoidf_(ga[r] + bav[r]), ig = sigmoidf_(gx[r] + bxv[r]);
;                 const float la = -8.0f * rg * sp[r]; float A = __expf(la);
;                 float U = __builtin_amdgcn_sqrtf(1.0f - A * A) * (ig * xcf[tok * 65 + j0 + r]);
;                 { const float As = dpp_shr1<1>(A), Us = dpp_shr0<1>(U); U = A * Us + U; A = A * As; }
;                 { const float As = dpp_shr1<2>(A), Us = dpp_shr0<2>(U); U = A * Us + U; A = A * As; }
;                 { const float As = dpp_shr1<4>(A), Us = dpp_shr0<4>(U); U = A * Us + U; A = A * As; }
;                 { const float As = dpp_shr1<8>(A), Us = dpp_shr0<8>(U); U = A * Us + U; A = A * As; }
;                 const float hh = U + A * hc[r], PP = A * Pc[r];
;                 hc[r] = bcast15(hh, lane); Pc[r] = bcast15(PP, lane); hv[r] = hh; pv[r] = PP; }
;             *(unsigned long long*)(y + (size_t)(row0 + tok) * DM + 64 * h + j0) = (unsigned long long)pk2(hv[0], hv[1]) | ((unsigned long long)pk2(hv[2], hv[3]) << 32);
;             *(unsigned long long*)((bf16_t*)(ws + WS_P) + (size_t)(row0 + tok) * 512 + 64 * h + j0) = (unsigned long long)pk2(pv[0], pv[1]) | ((unsigned long long)pk2(pv[2], pv[3]) << 32);
;         }
	v_pk_mul_f32 v[88:89], v[88:89], v[140:141]
	v_mov_b32_e32 v93, 1.0
	v_pk_mul_f32 v[88:89], v[126:127], v[88:89]
	s_nop 0
	v_mov_b32_dpp v93, v125 row_shr:1 row_mask:0xf bank_mask:0xf
	v_mov_b32_dpp v126, v88 row_shr:1 row_mask:0xf bank_mask:0xf bound_ctrl:1
	v_mov_b32_dpp v127, v89 row_shr:1 row_mask:0xf bank_mask:0xf bound_ctrl:1
	v_pk_mul_f32 v[128:129], v[124:125], v[92:93]
	v_mov_b32_e32 v92, 1.0
	v_mov_b32_e32 v93, 1.0
	v_pk_fma_f32 v[88:89], v[124:125], v[126:127], v[88:89]
	v_mov_b32_dpp v92, v128 row_shr:2 row_mask:0xf bank_mask:0xf
	v_mov_b32_dpp v93, v129 row_shr:2 row_mask:0xf bank_mask:0xf
	v_mov_b32_dpp v124, v88 row_shr:2 row_mask:0xf bank_mask:0xf bound_ctrl:1
	v_mov_b32_dpp v125, v89 row_shr:2 row_mask:0xf bank_mask:0xf bound_ctrl:1
	v_pk_mul_f32 v[130:131], v[128:129], v[92:93]
	v_mov_b32_e32 v92, 1.0
	v_mov_b32_e32 v93, 1.0
	v_pk_fma_f32 v[88:89], v[128:129], v[124:125], v[88:89]
	v_mov_b32_dpp v92, v130 row_shr:4 row_mask:0xf bank_mask:0xf
	v_mov_b32_dpp v93, v131 row_shr:4 row_mask:0xf bank_mask:0xf
	v_mov_b32_dpp v124, v88 row_shr:4 row_mask:0xf bank_mask:0xf bound_ctrl:1
	v_mov_b32_dpp v125, v89 row_shr:4 row_mask:0xf bank_mask:0xf bound_ctrl:1
	v_pk_mul_f32 v[132:133], v[130:131], v[92:93]
	v_mov_b32_e32 v92, 1.0
	v_mov_b32_e32 v93, 1.0
	v_pk_fma_f32 v[88:89], v[130:131], v[124:125], v[88:89]
	v_mov_b32_dpp v92, v132 row_shr:8 row_mask:0xf bank_mask:0xf
	v_mov_b32_dpp v93, v133 row_shr:8 row_mask:0xf bank_mask:0xf
	v_mov_b32_dpp v124, v88 row_shr:8 row_mask:0xf bank_mask:0xf bound_ctrl:1
	v_mov_b32_dpp v125, v89 row_shr:8 row_mask:0xf bank_mask:0xf bound_ctrl:1
	v_pk_mul_f32 v[134:135], v[132:133], v[92:93]
	v_pk_fma_f32 v[88:89], v[132:133], v[124:125], v[88:89]
	v_or_b32_e32 v124, s48, v139
	v_pk_fma_f32 v[96:97], v[134:135], v[96:97], v[88:89]
	v_ashrrev_i32_e32 v125, 31, v124
	v_pk_mul_f32 v[90:91], v[134:135], v[90:91]
	ds_bpermute_b32 v88, v143, v96 offset:60
	ds_bpermute_b32 v89, v143, v97 offset:60
	v_cvt_pk_bf16_f32 v99, v96, v97
	v_lshlrev_b64 v[96:97], 11, v[124:125]
	ds_bpermute_b32 v92, v143, v90 offset:60
	ds_bpermute_b32 v93, v143, v91 offset:60
	v_lshl_add_u64 v[96:97], v[114:115], 0, v[96:97]
	v_cvt_pk_bf16_f32 v127, v90, v91
	v_lshlrev_b64 v[90:91], 10, v[124:125]
	v_mov_b64_e32 v[238:239], v[98:99]
	v_cvt_pk_bf16_f32 v126, v148, v149
	v_lshl_add_u64 v[98:99], v[116:117], 0, v[90:91]
	v_mov_b64_e32 v[242:243], v[126:127]
	v_mfma_f32_16x16x32_bf16 v[124:127], v[56:59], v[4:7], 0
	v_mfma_f32_16x16x32_bf16 v[56:59], v[60:63], v[20:23], v[52:55]
	v_mfma_f32_16x16x32_bf16 v[52:55], v[64:67], v[20:23], v[124:127]
	s_nop 5
	v_add_u32_e32 v124, v142, v138
	v_add_f32_e32 v48, v48, v56
	v_add_f32_e32 v49, v49, v57
	v_mul_f32_e32 v48, 0xbfb8aa3b, v48
	v_mul_f32_e32 v49, 0xbfb8aa3b, v49
	v_exp_f32_e32 v48, v48
	v_exp_f32_e32 v49, v49
	v_add_f32_e32 v44, v44, v52
	v_add_f32_e32 v45, v45, v53
	v_mul_f32_e32 v44, 0xbfb8aa3b, v44
	v_mul_f32_e32 v45, 0xbfb8aa3b, v45
	v_add_f32_e32 v48, 1.0, v48
	v_exp_f32_e32 v44, v44
	v_add_f32_e32 v49, 1.0, v49
	v_exp_f32_e32 v45, v45
	v_rcp_f32_e32 v56, v48
	v_rcp_f32_e32 v52, v49
	v_add_f32_e32 v44, 1.0, v44
	v_add_f32_e32 v45, 1.0, v45
	v_rcp_f32_e32 v48, v44
	v_mul_f32_e32 v44, 0xc1000000, v56
	v_rcp_f32_e32 v49, v45
	v_mul_f32_e32 v45, 0xc1000000, v52
	v_mul_f32_e32 v44, v145, v44
	v_mul_f32_e32 v45, v147, v45
	v_mul_f32_e32 v44, 0x3fb8aa3b, v44
	v_mul_f32_e32 v45, 0x3fb8aa3b, v45
	v_exp_f32_e32 v56, v44
	v_exp_f32_e32 v57, v45
	v_add_f32_e32 v50, v50, v58
	v_mul_f32_e32 v50, 0xbfb8aa3b, v50
	v_fma_f32 v44, -v56, v56, 1.0
	v_fma_f32 v45, -v57, v57, 1.0
	v_sqrt_f32_e32 v60, v44
	v_mov_b32_e32 v44, 1.0
	v_sqrt_f32_e32 v61, v45
	v_mov_b32_e32 v45, 1.0
	v_exp_f32_e32 v50, v50
	v_mov_b32_dpp v44, v56 row_shr:1 row_mask:0xf bank_mask:0xf
	v_mov_b32_dpp v45, v57 row_shr:1 row_mask:0xf bank_mask:0xf
	v_pk_mul_f32 v[62:63], v[56:57], v[44:45]
	v_mov_b32_e32 v44, 1.0
	v_mov_b32_e32 v45, 1.0
	v_add_f32_e32 v46, v46, v54
	v_mov_b32_dpp v44, v62 row_shr:2 row_mask:0xf bank_mask:0xf
	v_mov_b32_dpp v45, v63 row_shr:2 row_mask:0xf bank_mask:0xf
	v_mul_f32_e32 v46, 0xbfb8aa3b, v46
	v_pk_mul_f32 v[64:65], v[62:63], v[44:45]
	v_mov_b32_e32 v44, 1.0
	v_mov_b32_e32 v45, 1.0
	v_add_f32_e32 v50, 1.0, v50
	v_exp_f32_e32 v46, v46
	v_mov_b32_dpp v44, v64 row_shr:4 row_mask:0xf bank_mask:0xf
	v_mov_b32_dpp v45, v65 row_shr:4 row_mask:0xf bank_mask:0xf
	v_rcp_f32_e32 v50, v50
	v_pk_mul_f32 v[66:67], v[64:65], v[44:45]
	v_mov_b32_e32 v44, 1.0
	v_mov_b32_e32 v45, 1.0
	v_add_f32_e32 v46, 1.0, v46
	v_mov_b32_dpp v44, v66 row_shr:8 row_mask:0xf bank_mask:0xf
	v_mov_b32_dpp v45, v67 row_shr:8 row_mask:0xf bank_mask:0xf
	v_pk_mul_f32 v[90:91], v[66:67], v[44:45]
	v_rcp_f32_e32 v54, v46
	v_pk_mul_f32 v[52:53], v[90:91], v[122:123]
	ds_read2_b32 v[122:123], v124 offset1:1
	v_mul_f32_e32 v46, 0xc1000000, v50
	v_mul_f32_e32 v2, v2, v46
	v_mul_f32_e32 v2, 0x3fb8aa3b, v2
	v_exp_f32_e32 v50, v2
	s_waitcnt lgkmcnt(0)
; __device__ __forceinline__ unsigned pk2(float lo, float hi) { const f32x2_t v = {lo, hi}; const bf16x2_t b = __builtin_convertvector(v, bf16x2_t); return __builtin_bit_cast(unsigned, b); }
; __device__ __forceinline__ float sigmoidf_(float x) { return __builtin_amdgcn_rcpf(1.0f + __expf(-x)); }
; __device__ __forceinline__ void w_lru_m1(const Args& a, int l, unsigned char* ws, const bf16_t* proj, bf16_t* y, LAS unsigned char* wl, int b, int ck_, int h, int lane) {
;     ...
;         for (int tb = 0; tb < 4; ++tb) { const int tok = 16 * tb + lo;
;             f32x4 ga = {0.f, 0.f, 0.f, 0.f}, gx = {0.f, 0.f, 0.f, 0.f};
; #pragma unroll
;             for (int kk = 0; kk < 2; ++kk) { ga = __builtin_amdgcn_mfma_f32_16x16x32_bf16(WaF[kk], Xf[tb][kk], ga, 0, 0, 0); gx = __builtin_amdgcn_mfma_f32_16x16x32_bf16(WxF[kk], Xf[tb][kk], gx, 0, 0, 0); }
;             float hv[4], pv[4];
; #pragma unroll
;             for (int r = 0; r < 4; ++r) {
;                 const float rg = sigmoidf_(ga[r] + bav[r]), ig = sigmoidf_(gx[r] + bxv[r]);
;                 const float la = -8.0f * rg * sp[r]; float A = __expf(la);
;                 float U = __builtin_amdgcn_sqrtf(1.0f - A * A) * (ig * xcf[tok * 65 + j0 + r]);
;                 { const float As = dpp_shr1<1>(A), Us = dpp_shr0<1>(U); U = A * Us + U; A = A * As; }
;                 { const float As = dpp_shr1<2>(A), Us = dpp_shr0<2>(U); U = A * Us + U; A = A * As; }
;                 { const float As = dpp_shr1<4>(A), Us = dpp_shr0<4>(U); U = A * Us + U; A = A * As; }
;                 { const float As = dpp_shr1<8>(A), Us = dpp_shr0<8>(U); U = A * Us + U; A = A * As; }
;                 const float hh = U + A * hc[r], PP = A * Pc[r];
;                 hc[r] = bcast15(hh, lane); Pc[r] = bcast15(PP, lane); hv[r] = hh; pv[r] = PP; }
;             *(unsigned long long*)(y + (size_t)(row0 + tok) * DM + 64 * h + j0) = (unsigned long long)pk2(hv[0], hv[1]) | ((unsigned long long)pk2(hv[2], hv[3]) << 32);
;             *(unsigned long long*)((bf16_t*)(ws + WS_P) + (size_t)(row0 + tok) * 512 + 64 * h + j0) = (unsigned long long)pk2(pv[0], pv[1]) | ((unsigned long long)pk2(pv[2], pv[3]) << 32);
;         }
;         if (lo == 0) { const size_t so = (size_t)(b * NCH + ck_) * 512 + 64 * h + j0;
; #pragma unroll
;             for (int r = 0; r < 4; ++r) { ((float*)(ws + WS_LRUA))[so + r] = Pc[r]; ((float*)(ws + WS_LRUH))[so + r] = hc[r]; } }
	v_pk_mul_f32 v[48:49], v[122:123], v[48:49]
	v_add_f32_e32 v47, v47, v55
	v_pk_mul_f32 v[48:49], v[48:49], v[60:61]
	v_fma_f32 v2, -v50, v50, 1.0
	v_mul_f32_e32 v47, 0xbfb8aa3b, v47
	v_mov_b32_dpp v60, v48 row_shr:1 row_mask:0xf bank_mask:0xf bound_ctrl:1
	v_mov_b32_dpp v61, v49 row_shr:1 row_mask:0xf bank_mask:0xf bound_ctrl:1
	v_pk_fma_f32 v[48:49], v[56:57], v[60:61], v[48:49]
	v_sqrt_f32_e32 v60, v2
	v_add_f32_e32 v2, v51, v59
	v_mul_f32_e32 v2, 0xbfb8aa3b, v2
	v_exp_f32_e32 v2, v2
	v_exp_f32_e32 v47, v47
	v_mov_b32_e32 v46, 1.0
	v_mov_b32_dpp v56, v48 row_shr:2 row_mask:0xf bank_mask:0xf bound_ctrl:1
	v_add_f32_e32 v2, 1.0, v2
	v_rcp_f32_e32 v2, v2
	v_add_f32_e32 v47, 1.0, v47
	v_rcp_f32_e32 v55, v47
	v_mov_b32_e32 v47, 1.0
	v_mul_f32_e32 v2, 0xc1000000, v2
	v_mul_f32_e32 v2, v146, v2
	v_mul_f32_e32 v2, 0x3fb8aa3b, v2
	v_exp_f32_e32 v51, v2
	v_mov_b32_dpp v57, v49 row_shr:2 row_mask:0xf bank_mask:0xf bound_ctrl:1
	v_mov_b32_dpp v46, v50 row_shr:1 row_mask:0xf bank_mask:0xf
	v_pk_fma_f32 v[48:49], v[62:63], v[56:57], v[48:49]
	v_mov_b32_dpp v47, v51 row_shr:1 row_mask:0xf bank_mask:0xf
	v_pk_mul_f32 v[62:63], v[50:51], v[46:47]
	v_mov_b32_e32 v46, 1.0
	v_mov_b32_e32 v47, 1.0
	v_mov_b32_dpp v56, v48 row_shr:4 row_mask:0xf bank_mask:0xf bound_ctrl:1
	v_mov_b32_dpp v57, v49 row_shr:4 row_mask:0xf bank_mask:0xf bound_ctrl:1
	v_mov_b32_dpp v46, v62 row_shr:2 row_mask:0xf bank_mask:0xf
	v_mov_b32_dpp v47, v63 row_shr:2 row_mask:0xf bank_mask:0xf
	v_pk_fma_f32 v[48:49], v[64:65], v[56:57], v[48:49]
	v_pk_mul_f32 v[64:65], v[62:63], v[46:47]
	v_mov_b32_e32 v46, 1.0
	v_mov_b32_e32 v47, 1.0
	v_mov_b32_dpp v56, v48 row_shr:8 row_mask:0xf bank_mask:0xf bound_ctrl:1
	v_mov_b32_dpp v57, v49 row_shr:8 row_mask:0xf bank_mask:0xf bound_ctrl:1
	v_mov_b32_dpp v46, v64 row_shr:4 row_mask:0xf bank_mask:0xf
	v_mov_b32_dpp v47, v65 row_shr:4 row_mask:0xf bank_mask:0xf
	v_pk_fma_f32 v[48:49], v[66:67], v[56:57], v[48:49]
	v_pk_mul_f32 v[66:67], v[64:65], v[46:47]
	v_mov_b32_e32 v46, 1.0
	v_mov_b32_e32 v47, 1.0
	v_pk_fma_f32 v[56:57], v[90:91], v[94:95], v[48:49]
	v_mov_b32_dpp v46, v66 row_shr:8 row_mask:0xf bank_mask:0xf
	v_mov_b32_dpp v47, v67 row_shr:8 row_mask:0xf bank_mask:0xf
	v_pk_mul_f32 v[90:91], v[66:67], v[46:47]
	v_fma_f32 v2, -v51, v51, 1.0
	v_pk_mul_f32 v[58:59], v[90:91], v[92:93]
	ds_read2_b32 v[92:93], v124 offset0:2 offset1:3
	v_sqrt_f32_e32 v61, v2
	ds_bpermute_b32 v44, v143, v52 offset:60
	ds_bpermute_b32 v48, v143, v56 offset:60
	ds_bpermute_b32 v49, v143, v57 offset:60
	s_waitcnt lgkmcnt(0)
	v_pk_mul_f32 v[54:55], v[54:55], v[92:93]
	ds_bpermute_b32 v45, v143, v53 offset:60
	v_pk_mul_f32 v[54:55], v[60:61], v[54:55]
	ds_bpermute_b32 v46, v143, v58 offset:60
	ds_bpermute_b32 v47, v143, v59 offset:60
	v_mov_b32_dpp v60, v54 row_shr:1 row_mask:0xf bank_mask:0xf bound_ctrl:1
	v_mov_b32_dpp v61, v55 row_shr:1 row_mask:0xf bank_mask:0xf bound_ctrl:1
	v_pk_fma_f32 v[50:51], v[50:51], v[60:61], v[54:55]
	v_cvt_pk_bf16_f32 v56, v56, v57
	v_cvt_pk_bf16_f32 v52, v52, v53
	v_mov_b32_dpp v54, v50 row_shr:2 row_mask:0xf bank_mask:0xf bound_ctrl:1
	v_mov_b32_dpp v55, v51 row_shr:2 row_mask:0xf bank_mask:0xf bound_ctrl:1
	v_pk_fma_f32 v[50:51], v[62:63], v[54:55], v[50:51]
	v_cvt_pk_bf16_f32 v53, v58, v59
	s_nop 0
	v_mov_b32_dpp v54, v50 row_shr:4 row_mask:0xf bank_mask:0xf bound_ctrl:1
	v_mov_b32_dpp v55, v51 row_shr:4 row_mask:0xf bank_mask:0xf bound_ctrl:1
	v_pk_fma_f32 v[50:51], v[64:65], v[54:55], v[50:51]
	s_nop 1
	v_mov_b32_dpp v54, v50 row_shr:8 row_mask:0xf bank_mask:0xf bound_ctrl:1
	v_mov_b32_dpp v55, v51 row_shr:8 row_mask:0xf bank_mask:0xf bound_ctrl:1
	v_pk_fma_f32 v[50:51], v[66:67], v[54:55], v[50:51]
	s_nop 0
	v_pk_fma_f32 v[54:55], v[90:91], v[88:89], v[50:51]
	ds_bpermute_b32 v50, v143, v54 offset:60
	ds_bpermute_b32 v51, v143, v55 offset:60
	v_cvt_pk_bf16_f32 v57, v54, v55
	v_or_b32_e32 v54, s48, v137
	v_ashrrev_i32_e32 v55, 31, v54
	v_lshlrev_b64 v[60:61], 11, v[54:55]
	v_lshlrev_b64 v[54:55], 10, v[54:55]
	v_lshl_add_u64 v[114:115], v[114:115], 0, v[60:61]
	v_lshl_add_u64 v[116:117], v[116:117], 0, v[54:55]
	v_mov_b64_e32 v[246:247], v[56:57]
	v_mov_b64_e32 v[250:251], v[52:53]
	s_and_saveexec_b64 s[34:35], vcc
	s_cbranch_execz .LBB0_523
	v_lshl_add_u64 v[52:53], s[42:43], 0, v[0:1]
	v_lshlrev_b64 v[52:53], 2, v[52:53]
	v_lshl_add_u64 v[54:55], s[84:85], 0, v[52:53]
	v_lshl_add_u64 v[52:53], s[86:87], 0, v[52:53]
	s_waitcnt lgkmcnt(0)
	global_store_dwordx4 v[54:55], v[44:47], off
	global_store_dwordx4 v[52:53], v[48:51], off
; __device__ __forceinline__ float sigmoidf_(float x) { return __builtin_amdgcn_rcpf(1.0f + __expf(-x)); }
; __device__ __forceinline__ float bcast15(float v, int lane) { return bperm_f((lane & 48) | 15, v); }
; __device__ __forceinline__ void w_lru_m1(const Args& a, int l, unsigned char* ws, const bf16_t* proj, bf16_t* y, LAS unsigned char* wl, int b, int ck_, int h, int lane) {
;     ...
;         if (jb < 3) {
; #pragma unroll
;             for (int kk = 0; kk < 2; ++kk) { nWa[kk] = *(const bf16x8*)(waT + (16 * (jb + 1) + lo) * 64 + 32 * kk + 8 * fq); nWx[kk] = *(const bf16x8*)(wxT + (16 * (jb + 1) + lo) * 64 + 32 * kk + 8 * fq); }
;             nba = *(const f32x4*)(ba + 16 * (jb + 1) + 4 * fq); nbx = *(const f32x4*)(bx + 16 * (jb + 1) + 4 * fq); nlam = *(const f32x4*)(lam + 16 * (jb + 1) + 4 * fq);
;         }
;         const int j0 = 16 * jb + 4 * fq;
;         float bav[4], bxv[4], sp[4], hc[4], Pc[4];
; #pragma unroll
;         for (int r = 0; r < 4; ++r) { bav[r] = pba[r]; bxv[r] = pbx[r]; sp[r] = log1pf(__expf(-plam[r])); hc[r] = 0.f; Pc[r] = 1.f; }
; #pragma unroll
;         for (int tb = 0; tb < 4; ++tb) { const int tok = 16 * tb + lo;
;             f32x4 ga = {0.f, 0.f, 0.f, 0.f}, gx = {0.f, 0.f, 0.f, 0.f};
; #pragma unroll
;             for (int kk = 0; kk < 2; ++kk) { ga = __builtin_amdgcn_mfma_f32_16x16x32_bf16(WaF[kk], Xf[tb][kk], ga, 0, 0, 0); gx = __builtin_amdgcn_mfma_f32_16x16x32_bf16(WxF[kk], Xf[tb][kk], gx, 0, 0, 0); }
;             float hv[4], pv[4];
; #pragma unroll
;             for (int r = 0; r < 4; ++r) {
;                 const float rg = sigmoidf_(ga[r] + bav[r]), ig = sigmoidf_(gx[r] + bxv[r]);
;                 const float la = -8.0f * rg * sp[r]; float A = __expf(la);
;                 float U = __builtin_amdgcn_sqrtf(1.0f - A * A) * (ig * xcf[tok * 65 + j0 + r]);
;                 { const float As = dpp_shr1<1>(A), Us = dpp_shr0<1>(U); U = A * Us + U; A = A * As; }
;                 { const float As = dpp_shr1<2>(A), Us = dpp_shr0<2>(U); U = A * Us + U; A = A * As; }
;                 { const float As = dpp_shr1<4>(A), Us = dpp_shr0<4>(U); U = A * Us + U; A = A * As; }
;                 { const float As = dpp_shr1<8>(A), Us = dpp_shr0<8>(U); U = A * Us + U; A = A * As; }
;                 const float hh = U + A * hc[r], PP = A * Pc[r];
;                 hc[r] = bcast15(hh, lane); Pc[r] = bcast15(PP, lane); hv[r] = hh; pv[r] = PP; }
.LBB0_523:
	s_or_b64 exec, exec, s[34:35]
	v_lshlrev_b32_e32 v146, 3, v136
	v_lshl_or_b32 v2, v146, 1, v209
	s_waitcnt lgkmcnt(0)
	v_lshl_add_u64 v[44:45], v[118:119], 0, v[2:3]
	v_lshl_add_u64 v[46:47], v[120:121], 0, v[2:3]
	s_waitcnt vmcnt(2)
	s_nop 7
	v_mul_u32_u24_e32 v92, 0x104, v136
	v_add_u32_e32 v145, v142, v92
	global_load_dwordx4 v[64:67], v[44:45], off
	global_load_dwordx4 v[60:63], v[46:47], off
	global_load_dwordx4 v[56:59], v[44:45], off offset:1024
	global_load_dwordx4 v[52:55], v[46:47], off offset:1024
	global_load_dwordx4 v[48:51], v[108:109], off offset:128
	s_nop 0
	global_load_dwordx4 v[44:47], v[110:111], off offset:128
	global_load_dwordx4 v[88:91], v[112:113], off offset:128
	s_nop 7
	v_mov_b32_e32 v132, 1.0
	s_nop 7
	v_mov_b32_e32 v133, 1.0
	s_nop 7
	v_or_b32_e32 v1, 60, v143
	ds_read2_b32 v[136:137], v145 offset0:18 offset1:19
	s_nop 7
	s_nop 1
	s_nop 7
	s_nop 1
	s_nop 7
	v_mov_b32_e32 v147, v84
	s_nop 7
	s_nop 0
	s_nop 7
	s_nop 0
	s_nop 7
	s_nop 0
	s_nop 7
	s_nop 0
	s_nop 7
	s_nop 1
	s_nop 7
	s_nop 1
	s_nop 7
	s_nop 1
	s_nop 7
	v_mov_b32_e32 v149, v85
	s_nop 7
	s_nop 0
	s_nop 7
	s_nop 0
	s_nop 7
	v_mov_b32_e32 v130, 1.0
	s_nop 7
	v_mov_b32_e32 v131, 1.0
	s_nop 7
	s_nop 1
	s_nop 7
	s_nop 1
	s_nop 7
	s_nop 1
	s_nop 7
	v_mov_b32_e32 v2, v86
	s_nop 7
	s_nop 0
	s_nop 7
	s_nop 0
	s_nop 7
	s_nop 0
	s_nop 7
	s_nop 0
	s_nop 7
	v_mov_b32_e32 v128, 1.0
	s_nop 7
	v_mov_b32_e32 v129, 1.0
	s_nop 7
	v_mfma_f32_16x16x32_bf16 v[122:125], v[72:75], v[16:19], 0
	s_nop 0
	s_nop 7
	v_mfma_f32_16x16x32_bf16 v[124:127], v[80:83], v[32:35], v[122:125]
	s_nop 0
	s_nop 7
	s_nop 1
	s_nop 7
	v_mov_b32_e32 v148, v87
	v_mfma_f32_16x16x32_bf16 v[84:87], v[68:71], v[16:19], 0
	v_mfma_f32_16x16x32_bf16 v[84:87], v[76:79], v[32:35], v[84:87]
	s_nop 7
	v_add_f32_e32 v84, v40, v84
	v_mul_f32_e32 v84, 0xbfb8aa3b, v84
	v_exp_f32_e32 v84, v84
	v_add_f32_e32 v85, v41, v85
	v_mul_f32_e32 v85, 0xbfb8aa3b, v85
	v_exp_f32_e32 v85, v85
	v_add_f32_e32 v84, 1.0, v84
	v_rcp_f32_e32 v93, v84
	v_add_f32_e32 v84, v36, v124
	v_add_f32_e32 v85, 1.0, v85
	v_mul_f32_e32 v84, 0xbfb8aa3b, v84
	v_mul_f32_e32 v93, 0xc1000000, v93
	v_mul_f32_e32 v93, v147, v93
	v_mul_f32_e32 v93, 0x3fb8aa3b, v93
	v_exp_f32_e32 v94, v93
	v_exp_f32_e32 v84, v84
	v_mov_b32_e32 v124, 1.0
	v_add_f32_e32 v86, v42, v86
	v_fma_f32 v93, -v94, v94, 1.0
	v_sqrt_f32_e32 v122, v93
	v_rcp_f32_e32 v93, v85
	v_add_f32_e32 v85, v37, v125
	v_mul_f32_e32 v85, 0xbfb8aa3b, v85
	v_exp_f32_e32 v85, v85
	v_mul_f32_e32 v93, 0xc1000000, v93
	v_mul_f32_e32 v93, v149, v93
	v_mul_f32_e32 v93, 0x3fb8aa3b, v93
	v_exp_f32_e32 v95, v93
	v_add_f32_e32 v84, 1.0, v84
	v_add_f32_e32 v85, 1.0, v85
	v_rcp_f32_e32 v84, v84
	v_fma_f32 v93, -v95, v95, 1.0
	v_sqrt_f32_e32 v123, v93
	ds_read2_b32 v[92:93], v145 offset0:16 offset1:17
	v_rcp_f32_e32 v85, v85
	v_mov_b32_e32 v125, 1.0
	v_mov_b32_dpp v124, v94 row_shr:1 row_mask:0xf bank_mask:0xf
	v_mul_f32_e32 v86, 0xbfb8aa3b, v86
	s_waitcnt lgkmcnt(0)
	v_pk_mul_f32 v[84:85], v[92:93], v[84:85]
	v_mov_b32_dpp v125, v95 row_shr:1 row_mask:0xf bank_mask:0xf
	v_pk_mul_f32 v[84:85], v[84:85], v[122:123]
	v_pk_mul_f32 v[124:125], v[94:95], v[124:125]
	v_exp_f32_e32 v86, v86
	v_mov_b32_dpp v92, v84 row_shr:1 row_mask:0xf bank_mask:0xf bound_ctrl:1
	v_mov_b32_dpp v93, v85 row_shr:1 row_mask:0xf bank_mask:0xf bound_ctrl:1
	v_pk_fma_f32 v[84:85], v[94:95], v[92:93], v[84:85]
	v_mov_b32_dpp v128, v124 row_shr:2 row_mask:0xf bank_mask:0xf
	v_mov_b32_dpp v129, v125 row_shr:2 row_mask:0xf bank_mask:0xf
	v_mov_b32_dpp v92, v84 row_shr:2 row_mask:0xf bank_mask:0xf bound_ctrl:1
	v_mov_b32_dpp v93, v85 row_shr:2 row_mask:0xf bank_mask:0xf bound_ctrl:1
	v_pk_fma_f32 v[84:85], v[124:125], v[92:93], v[84:85]
	v_pk_mul_f32 v[128:129], v[124:125], v[128:129]
	v_add_f32_e32 v86, 1.0, v86
	v_mov_b32_dpp v92, v84 row_shr:4 row_mask:0xf bank_mask:0xf bound_ctrl:1
	v_mov_b32_dpp v93, v85 row_shr:4 row_mask:0xf bank_mask:0xf bound_ctrl:1
	v_mov_b32_dpp v130, v128 row_shr:4 row_mask:0xf bank_mask:0xf
	v_mov_b32_dpp v131, v129 row_shr:4 row_mask:0xf bank_mask:0xf
	v_pk_fma_f32 v[84:85], v[128:129], v[92:93], v[84:85]
	v_pk_mul_f32 v[130:131], v[128:129], v[130:131]
	v_add_f32_e32 v87, v43, v87
	v_mov_b32_dpp v92, v84 row_shr:8 row_mask:0xf bank_mask:0xf bound_ctrl:1
	v_mov_b32_dpp v93, v85 row_shr:8 row_mask:0xf bank_mask:0xf bound_ctrl:1
	v_pk_fma_f32 v[84:85], v[130:131], v[92:93], v[84:85]
	v_rcp_f32_e32 v92, v86
	v_mul_f32_e32 v87, 0xbfb8aa3b, v87
	v_exp_f32_e32 v87, v87
	v_add_f32_e32 v86, v38, v126
	v_mul_f32_e32 v92, 0xc1000000, v92
	v_mul_f32_e32 v92, v2, v92
	v_mul_f32_e32 v92, 0x3fb8aa3b, v92
	v_exp_f32_e32 v92, v92
	v_add_f32_e32 v87, 1.0, v87
	v_mul_f32_e32 v86, 0xbfb8aa3b, v86
	v_exp_f32_e32 v86, v86
	v_fma_f32 v93, -v92, v92, 1.0
	v_sqrt_f32_e32 v94, v93
	v_rcp_f32_e32 v93, v87
	v_add_f32_e32 v87, v39, v127
	v_mul_f32_e32 v87, 0xbfb8aa3b, v87
	v_exp_f32_e32 v87, v87
	v_mul_f32_e32 v93, 0xc1000000, v93
	v_mul_f32_e32 v93, v148, v93
	v_mul_f32_e32 v93, 0x3fb8aa3b, v93
	v_exp_f32_e32 v93, v93
	v_add_f32_e32 v86, 1.0, v86
	v_add_f32_e32 v87, 1.0, v87
	v_rcp_f32_e32 v86, v86
	v_rcp_f32_e32 v87, v87
	v_fma_f32 v95, -v93, v93, 1.0
	v_sqrt_f32_e32 v95, v95
	v_mov_b32_e32 v122, 1.0
	v_pk_mul_f32 v[86:87], v[86:87], v[136:137]
	v_mov_b32_e32 v123, 1.0
	v_pk_mul_f32 v[86:87], v[94:95], v[86:87]
	v_mov_b32_dpp v122, v92 row_shr:1 row_mask:0xf bank_mask:0xf
	v_mov_b32_dpp v123, v93 row_shr:1 row_mask:0xf bank_mask:0xf
	v_mov_b32_dpp v94, v86 row_shr:1 row_mask:0xf bank_mask:0xf bound_ctrl:1
	v_mov_b32_dpp v95, v87 row_shr:1 row_mask:0xf bank_mask:0xf bound_ctrl:1
	v_pk_mul_f32 v[122:123], v[92:93], v[122:123]
; __device__ __forceinline__ unsigned pk2(float lo, float hi) { const f32x2_t v = {lo, hi}; const bf16x2_t b = __builtin_convertvector(v, bf16x2_t); return __builtin_bit_cast(unsigned, b); }
; __device__ __forceinline__ float sigmoidf_(float x) { return __builtin_amdgcn_rcpf(1.0f + __expf(-x)); }
; __device__ __forceinline__ float bcast15(float v, int lane) { return bperm_f((lane & 48) | 15, v); }
; __device__ __forceinline__ void w_lru_m1(const Args& a, int l, unsigned char* ws, const bf16_t* proj, bf16_t* y, LAS unsigned char* wl, int b, int ck_, int h, int lane) {
;     ...
;         for (int tb = 0; tb < 4; ++tb) { const int tok = 16 * tb + lo;
;             f32x4 ga = {0.f, 0.f, 0.f, 0.f}, gx = {0.f, 0.f, 0.f, 0.f};
; #pragma unroll
;             for (int kk = 0; kk < 2; ++kk) { ga = __builtin_amdgcn_mfma_f32_16x16x32_bf16(WaF[kk], Xf[tb][kk], ga, 0, 0, 0); gx = __builtin_amdgcn_mfma_f32_16x16x32_bf16(WxF[kk], Xf[tb][kk], gx, 0, 0, 0); }
;             float hv[4], pv[4];
; #pragma unroll
;             for (int r = 0; r < 4; ++r) {
;                 const float rg = sigmoidf_(ga[r] + bav[r]), ig = sigmoidf_(gx[r] + bxv[r]);
;                 const float la = -8.0f * rg * sp[r]; float A = __expf(la);
;                 float U = __builtin_amdgcn_sqrtf(1.0f - A * A) * (ig * xcf[tok * 65 + j0 + r]);
;                 { const float As = dpp_shr1<1>(A), Us = dpp_shr0<1>(U); U = A * Us + U; A = A * As; }
;                 { const float As = dpp_shr1<2>(A), Us = dpp_shr0<2>(U); U = A * Us + U; A = A * As; }
;                 { const float As = dpp_shr1<4>(A), Us = dpp_shr0<4>(U); U = A * Us + U; A = A * As; }
;                 { const float As = dpp_shr1<8>(A), Us = dpp_shr0<8>(U); U = A * Us + U; A = A * As; }
;                 const float hh = U + A * hc[r], PP = A * Pc[r];
;                 hc[r] = bcast15(hh, lane); Pc[r] = bcast15(PP, lane); hv[r] = hh; pv[r] = PP; }
;             *(unsigned long long*)(y + (size_t)(row0 + tok) * DM + 64 * h + j0) = (unsigned long long)pk2(hv[0], hv[1]) | ((unsigned long long)pk2(hv[2], hv[3]) << 32);
;             *(unsigned long long*)((bf16_t*)(ws + WS_P) + (size_t)(row0 + tok) * 512 + 64 * h + j0) = (unsigned long long)pk2(pv[0], pv[1]) | ((unsigned long long)pk2(pv[2], pv[3]) << 32);
;         }
	v_mov_b32_e32 v126, 1.0
	v_mov_b32_e32 v127, 1.0
	v_pk_fma_f32 v[86:87], v[92:93], v[94:95], v[86:87]
	v_mov_b32_dpp v126, v122 row_shr:2 row_mask:0xf bank_mask:0xf
	v_mov_b32_dpp v127, v123 row_shr:2 row_mask:0xf bank_mask:0xf
	v_mov_b32_dpp v92, v86 row_shr:2 row_mask:0xf bank_mask:0xf bound_ctrl:1
	v_mov_b32_dpp v93, v87 row_shr:2 row_mask:0xf bank_mask:0xf bound_ctrl:1
	v_pk_mul_f32 v[126:127], v[122:123], v[126:127]
	v_mov_b32_e32 v128, 1.0
	v_mov_b32_e32 v129, 1.0
	v_pk_fma_f32 v[86:87], v[122:123], v[92:93], v[86:87]
	v_mov_b32_dpp v132, v130 row_shr:8 row_mask:0xf bank_mask:0xf
	v_mov_b32_dpp v133, v131 row_shr:8 row_mask:0xf bank_mask:0xf
	v_mov_b32_dpp v128, v126 row_shr:4 row_mask:0xf bank_mask:0xf
	v_mov_b32_dpp v129, v127 row_shr:4 row_mask:0xf bank_mask:0xf
	v_mov_b32_dpp v92, v86 row_shr:4 row_mask:0xf bank_mask:0xf bound_ctrl:1
	v_mov_b32_dpp v93, v87 row_shr:4 row_mask:0xf bank_mask:0xf bound_ctrl:1
	v_pk_mul_f32 v[134:135], v[130:131], v[132:133]
	v_pk_mul_f32 v[128:129], v[126:127], v[128:129]
	v_mov_b32_e32 v130, 1.0
	v_mov_b32_e32 v131, 1.0
	v_pk_fma_f32 v[86:87], v[126:127], v[92:93], v[86:87]
	v_mov_b32_dpp v130, v128 row_shr:8 row_mask:0xf bank_mask:0xf
	v_mov_b32_dpp v131, v129 row_shr:8 row_mask:0xf bank_mask:0xf
	v_mov_b32_dpp v92, v86 row_shr:8 row_mask:0xf bank_mask:0xf bound_ctrl:1
	v_mov_b32_dpp v93, v87 row_shr:8 row_mask:0xf bank_mask:0xf bound_ctrl:1
	v_pk_mul_f32 v[130:131], v[128:129], v[130:131]
	v_pk_fma_f32 v[86:87], v[128:129], v[92:93], v[86:87]
	v_pk_fma_f32 v[84:85], v[134:135], 0, v[84:85] op_sel_hi:[1,0,1]
	v_pk_fma_f32 v[86:87], v[130:131], 0, v[86:87] op_sel_hi:[1,0,1]
	ds_bpermute_b32 v124, v1, v84
	ds_bpermute_b32 v125, v1, v85
	v_cvt_pk_bf16_f32 v84, v84, v85
	v_cvt_pk_bf16_f32 v85, v86, v87
	v_mov_b64_e32 v[224:225], v[84:85]
	s_nop 1
	v_permlane16_swap_b32_e32 v222, v224
	v_permlane16_swap_b32_e32 v223, v225
	global_store_dwordx4 v[100:101], v[222:225], off
	v_cvt_pk_bf16_f32 v84, v134, v135
	v_cvt_pk_bf16_f32 v85, v130, v131
	ds_bpermute_b32 v122, v1, v86
	ds_bpermute_b32 v123, v1, v87
	v_mov_b64_e32 v[228:229], v[84:85]
	s_nop 1
	v_permlane16_swap_b32_e32 v226, v228
	v_permlane16_swap_b32_e32 v227, v229
	global_store_dwordx4 v[102:103], v[226:229], off
	v_mfma_f32_16x16x32_bf16 v[84:87], v[68:71], v[12:15], 0
	ds_bpermute_b32 v132, v1, v130
	ds_bpermute_b32 v133, v1, v131
	ds_bpermute_b32 v150, v1, v134
	v_mfma_f32_16x16x32_bf16 v[126:129], v[72:75], v[12:15], 0
	ds_bpermute_b32 v151, v1, v135
	v_mfma_f32_16x16x32_bf16 v[92:95], v[76:79], v[28:31], v[84:87]
	v_mfma_f32_16x16x32_bf16 v[84:87], v[80:83], v[28:31], v[126:129]
	s_nop 6
	v_add_f32_e32 v92, v40, v92
	v_mul_f32_e32 v92, 0xbfb8aa3b, v92
	v_exp_f32_e32 v92, v92
	v_add_f32_e32 v84, v36, v84
	v_mul_f32_e32 v84, 0xbfb8aa3b, v84
	v_exp_f32_e32 v84, v84
	v_add_f32_e32 v92, 1.0, v92
	v_rcp_f32_e32 v92, v92
	v_add_f32_e32 v85, v37, v85
	v_add_f32_e32 v84, 1.0, v84
	v_rcp_f32_e32 v126, v84
	v_mul_f32_e32 v84, 0xc1000000, v92
	v_add_f32_e32 v92, v41, v93
	v_mul_f32_e32 v92, 0xbfb8aa3b, v92
	v_exp_f32_e32 v92, v92
	v_mul_f32_e32 v85, 0xbfb8aa3b, v85
	v_exp_f32_e32 v85, v85
	v_mul_f32_e32 v84, v147, v84
	v_add_f32_e32 v92, 1.0, v92
	v_rcp_f32_e32 v92, v92
	v_add_f32_e32 v85, 1.0, v85
	v_rcp_f32_e32 v127, v85
	v_mul_f32_e32 v84, 0x3fb8aa3b, v84
	v_mul_f32_e32 v85, 0xc1000000, v92
	v_mul_f32_e32 v85, v149, v85
	v_mul_f32_e32 v85, 0x3fb8aa3b, v85
	v_exp_f32_e32 v128, v84
	v_exp_f32_e32 v129, v85
	v_add_f32_e32 v94, v42, v94
	v_add_f32_e32 v95, v43, v95
	v_fma_f32 v84, -v128, v128, 1.0
	v_fma_f32 v85, -v129, v129, 1.0
	v_sqrt_f32_e32 v130, v84
	v_mov_b32_e32 v84, 1.0
	v_sqrt_f32_e32 v131, v85
	v_mov_b32_e32 v85, 1.0
	v_mov_b32_dpp v84, v128 row_shr:1 row_mask:0xf bank_mask:0xf
	v_mul_f32_e32 v94, 0xbfb8aa3b, v94
	v_mov_b32_dpp v85, v129 row_shr:1 row_mask:0xf bank_mask:0xf
	v_pk_mul_f32 v[134:135], v[128:129], v[84:85]
	v_mov_b32_e32 v84, 1.0
	v_mov_b32_e32 v85, 1.0
	v_mul_f32_e32 v95, 0xbfb8aa3b, v95
	v_mov_b32_dpp v84, v134 row_shr:2 row_mask:0xf bank_mask:0xf
	v_mov_b32_dpp v85, v135 row_shr:2 row_mask:0xf bank_mask:0xf
	v_pk_mul_f32 v[136:137], v[134:135], v[84:85]
	v_mov_b32_e32 v84, 1.0
	v_mov_b32_e32 v85, 1.0
	v_exp_f32_e32 v94, v94
	v_mov_b32_dpp v84, v136 row_shr:4 row_mask:0xf bank_mask:0xf
	v_mov_b32_dpp v85, v137 row_shr:4 row_mask:0xf bank_mask:0xf
	v_pk_mul_f32 v[138:139], v[136:137], v[84:85]
	v_mov_b32_e32 v84, 1.0
	v_mov_b32_e32 v85, 1.0
	v_exp_f32_e32 v95, v95
	v_mov_b32_dpp v84, v138 row_shr:8 row_mask:0xf bank_mask:0xf
	v_mov_b32_dpp v85, v139 row_shr:8 row_mask:0xf bank_mask:0xf
	v_pk_mul_f32 v[140:141], v[138:139], v[84:85]
	v_add_u32_e32 v85, 0x1080, v145
	ds_read2_b32 v[142:143], v85 offset1:1
	v_add_f32_e32 v86, v38, v86
	v_add_f32_e32 v87, v39, v87
	v_mul_f32_e32 v86, 0xbfb8aa3b, v86
	v_mul_f32_e32 v87, 0xbfb8aa3b, v87
	s_waitcnt lgkmcnt(0)
; __device__ __forceinline__ unsigned pk2(float lo, float hi) { const f32x2_t v = {lo, hi}; const bf16x2_t b = __builtin_convertvector(v, bf16x2_t); return __builtin_bit_cast(unsigned, b); }
; __device__ __forceinline__ float sigmoidf_(float x) { return __builtin_amdgcn_rcpf(1.0f + __expf(-x)); }
; __device__ __forceinline__ float bcast15(float v, int lane) { return bperm_f((lane & 48) | 15, v); }
; __device__ __forceinline__ void w_lru_m1(const Args& a, int l, unsigned char* ws, const bf16_t* proj, bf16_t* y, LAS unsigned char* wl, int b, int ck_, int h, int lane) {
;     ...
;         for (int tb = 0; tb < 4; ++tb) { const int tok = 16 * tb + lo;
;             f32x4 ga = {0.f, 0.f, 0.f, 0.f}, gx = {0.f, 0.f, 0.f, 0.f};
; #pragma unroll
;             for (int kk = 0; kk < 2; ++kk) { ga = __builtin_amdgcn_mfma_f32_16x16x32_bf16(WaF[kk], Xf[tb][kk], ga, 0, 0, 0); gx = __builtin_amdgcn_mfma_f32_16x16x32_bf16(WxF[kk], Xf[tb][kk], gx, 0, 0, 0); }
;             float hv[4], pv[4];
; #pragma unroll
;             for (int r = 0; r < 4; ++r) {
;                 const float rg = sigmoidf_(ga[r] + bav[r]), ig = sigmoidf_(gx[r] + bxv[r]);
;                 const float la = -8.0f * rg * sp[r]; float A = __expf(la);
;                 float U = __builtin_amdgcn_sqrtf(1.0f - A * A) * (ig * xcf[tok * 65 + j0 + r]);
;                 { const float As = dpp_shr1<1>(A), Us = dpp_shr0<1>(U); U = A * Us + U; A = A * As; }
;                 { const float As = dpp_shr1<2>(A), Us = dpp_shr0<2>(U); U = A * Us + U; A = A * As; }
;                 { const float As = dpp_shr1<4>(A), Us = dpp_shr0<4>(U); U = A * Us + U; A = A * As; }
;                 { const float As = dpp_shr1<8>(A), Us = dpp_shr0<8>(U); U = A * Us + U; A = A * As; }
;                 const float hh = U + A * hc[r], PP = A * Pc[r];
;                 hc[r] = bcast15(hh, lane); Pc[r] = bcast15(PP, lane); hv[r] = hh; pv[r] = PP; }
;             *(unsigned long long*)(y + (size_t)(row0 + tok) * DM + 64 * h + j0) = (unsigned long long)pk2(hv[0], hv[1]) | ((unsigned long long)pk2(hv[2], hv[3]) << 32);
;             *(unsigned long long*)((bf16_t*)(ws + WS_P) + (size_t)(row0 + tok) * 512 + 64 * h + j0) = (unsigned long long)pk2(pv[0], pv[1]) | ((unsigned long long)pk2(pv[2], pv[3]) << 32);
;         }
	v_pk_mul_f32 v[126:127], v[142:143], v[126:127]
	v_add_f32_e32 v94, 1.0, v94
	v_pk_mul_f32 v[126:127], v[126:127], v[130:131]
	v_exp_f32_e32 v86, v86
	v_add_f32_e32 v95, 1.0, v95
	v_mov_b32_dpp v130, v126 row_shr:1 row_mask:0xf bank_mask:0xf bound_ctrl:1
	v_mov_b32_dpp v131, v127 row_shr:1 row_mask:0xf bank_mask:0xf bound_ctrl:1
	v_pk_fma_f32 v[126:127], v[128:129], v[130:131], v[126:127]
	v_exp_f32_e32 v87, v87
	v_rcp_f32_e32 v94, v94
	v_mov_b32_dpp v128, v126 row_shr:2 row_mask:0xf bank_mask:0xf bound_ctrl:1
	v_mov_b32_dpp v129, v127 row_shr:2 row_mask:0xf bank_mask:0xf bound_ctrl:1
	v_pk_fma_f32 v[126:127], v[134:135], v[128:129], v[126:127]
	v_rcp_f32_e32 v95, v95
	v_add_f32_e32 v86, 1.0, v86
	v_mov_b32_dpp v128, v126 row_shr:4 row_mask:0xf bank_mask:0xf bound_ctrl:1
	v_mov_b32_dpp v129, v127 row_shr:4 row_mask:0xf bank_mask:0xf bound_ctrl:1
	v_pk_fma_f32 v[126:127], v[136:137], v[128:129], v[126:127]
	v_add_f32_e32 v87, 1.0, v87
	v_pk_mul_f32 v[92:93], v[140:141], v[150:151]
	v_mov_b32_dpp v128, v126 row_shr:8 row_mask:0xf bank_mask:0xf bound_ctrl:1
	v_mov_b32_dpp v129, v127 row_shr:8 row_mask:0xf bank_mask:0xf bound_ctrl:1
	v_pk_fma_f32 v[126:127], v[138:139], v[128:129], v[126:127]
	v_rcp_f32_e32 v128, v86
	v_mul_f32_e32 v86, 0xc1000000, v94
	v_rcp_f32_e32 v129, v87
	v_mul_f32_e32 v87, 0xc1000000, v95
	v_mul_f32_e32 v86, v2, v86
	v_mul_f32_e32 v87, v148, v87
	v_mul_f32_e32 v86, 0x3fb8aa3b, v86
	v_mul_f32_e32 v87, 0x3fb8aa3b, v87
	v_exp_f32_e32 v94, v86
	v_exp_f32_e32 v95, v87
	v_pk_fma_f32 v[126:127], v[140:141], v[124:125], v[126:127]
	ds_bpermute_b32 v84, v1, v92
	v_fma_f32 v86, -v94, v94, 1.0
	v_fma_f32 v87, -v95, v95, 1.0
	v_sqrt_f32_e32 v130, v86
	v_mov_b32_e32 v86, 1.0
	v_sqrt_f32_e32 v131, v87
	v_mov_b32_e32 v87, 1.0
	v_mov_b32_dpp v86, v94 row_shr:1 row_mask:0xf bank_mask:0xf
	ds_bpermute_b32 v124, v1, v126
	v_mov_b32_dpp v87, v95 row_shr:1 row_mask:0xf bank_mask:0xf
	v_pk_mul_f32 v[134:135], v[94:95], v[86:87]
	v_mov_b32_e32 v86, 1.0
	v_mov_b32_e32 v87, 1.0
	ds_bpermute_b32 v125, v1, v127
	v_mov_b32_dpp v86, v134 row_shr:2 row_mask:0xf bank_mask:0xf
	v_mov_b32_dpp v87, v135 row_shr:2 row_mask:0xf bank_mask:0xf
	v_pk_mul_f32 v[136:137], v[134:135], v[86:87]
	v_mov_b32_e32 v86, 1.0
	v_mov_b32_e32 v87, 1.0
	ds_bpermute_b32 v85, v1, v93
	v_mov_b32_dpp v86, v136 row_shr:4 row_mask:0xf bank_mask:0xf
	v_mov_b32_dpp v87, v137 row_shr:4 row_mask:0xf bank_mask:0xf
	v_pk_mul_f32 v[138:139], v[136:137], v[86:87]
	v_mov_b32_e32 v86, 1.0
	v_mov_b32_e32 v87, 1.0
	v_cvt_pk_bf16_f32 v126, v126, v127
	v_mov_b32_dpp v86, v138 row_shr:8 row_mask:0xf bank_mask:0xf
	v_mov_b32_dpp v87, v139 row_shr:8 row_mask:0xf bank_mask:0xf
	v_pk_mul_f32 v[140:141], v[138:139], v[86:87]
	v_add_u32_e32 v87, 0x1088, v145
	ds_read2_b32 v[142:143], v87 offset1:1
	v_pk_mul_f32 v[132:133], v[140:141], v[132:133]
	v_cvt_pk_bf16_f32 v92, v92, v93
	v_cvt_pk_bf16_f32 v93, v132, v133
	ds_bpermute_b32 v86, v1, v132
	s_waitcnt lgkmcnt(0)
	v_pk_mul_f32 v[128:129], v[128:129], v[142:143]
	ds_bpermute_b32 v87, v1, v133
	v_pk_mul_f32 v[128:129], v[130:131], v[128:129]
	s_nop 1
	v_mov_b32_dpp v130, v128 row_shr:1 row_mask:0xf bank_mask:0xf bound_ctrl:1
	v_mov_b32_dpp v131, v129 row_shr:1 row_mask:0xf bank_mask:0xf bound_ctrl:1
	v_pk_fma_f32 v[94:95], v[94:95], v[130:131], v[128:129]
	s_nop 1
	v_mov_b32_dpp v128, v94 row_shr:2 row_mask:0xf bank_mask:0xf bound_ctrl:1
	v_mov_b32_dpp v129, v95 row_shr:2 row_mask:0xf bank_mask:0xf bound_ctrl:1
	v_pk_fma_f32 v[94:95], v[134:135], v[128:129], v[94:95]
	s_nop 1
	v_mov_b32_dpp v128, v94 row_shr:4 row_mask:0xf bank_mask:0xf bound_ctrl:1
	v_mov_b32_dpp v129, v95 row_shr:4 row_mask:0xf bank_mask:0xf bound_ctrl:1
	v_pk_fma_f32 v[94:95], v[136:137], v[128:129], v[94:95]
	s_nop 1
	v_mov_b32_dpp v128, v94 row_shr:8 row_mask:0xf bank_mask:0xf bound_ctrl:1
	v_mov_b32_dpp v129, v95 row_shr:8 row_mask:0xf bank_mask:0xf bound_ctrl:1
	v_pk_fma_f32 v[94:95], v[138:139], v[128:129], v[94:95]
	s_nop 0
	v_pk_fma_f32 v[94:95], v[140:141], v[122:123], v[94:95]
	ds_bpermute_b32 v122, v1, v94
	v_cvt_pk_bf16_f32 v127, v94, v95
	ds_bpermute_b32 v123, v1, v95
	v_mov_b64_e32 v[232:233], v[126:127]
	s_nop 1
	v_permlane16_swap_b32_e32 v230, v232
	v_permlane16_swap_b32_e32 v231, v233
	global_store_dwordx4 v[104:105], v[230:233], off
	v_mov_b64_e32 v[236:237], v[92:93]
	s_nop 1
	v_permlane16_swap_b32_e32 v234, v236
	v_permlane16_swap_b32_e32 v235, v237
	global_store_dwordx4 v[106:107], v[234:237], off
	v_mfma_f32_16x16x32_bf16 v[92:95], v[68:71], v[8:11], 0
	v_mfma_f32_16x16x32_bf16 v[130:133], v[76:79], v[24:27], v[92:95]
	v_mfma_f32_16x16x32_bf16 v[126:129], v[72:75], v[8:11], 0
	v_mfma_f32_16x16x32_bf16 v[134:137], v[80:83], v[24:27], v[126:129]
	s_nop 5
	v_add_f32_e32 v92, v40, v130
	v_mul_f32_e32 v92, 0xbfb8aa3b, v92
	v_exp_f32_e32 v92, v92
	v_mov_b32_e32 v126, 1.0
	v_mfma_f32_16x16x32_bf16 v[68:71], v[68:71], v[4:7], 0
	v_add_f32_e32 v92, 1.0, v92
	v_rcp_f32_e32 v93, v92
	v_add_f32_e32 v92, v36, v134
	v_mul_f32_e32 v92, 0xbfb8aa3b, v92
	v_exp_f32_e32 v92, v92
	v_mul_f32_e32 v93, 0xc1000000, v93
	v_mul_f32_e32 v93, v147, v93
	v_mul_f32_e32 v93, 0x3fb8aa3b, v93
	v_exp_f32_e32 v94, v93
	v_add_f32_e32 v92, 1.0, v92
	v_rcp_f32_e32 v92, v92
	v_fma_f32 v93, -v94, v94, 1.0
	v_sqrt_f32_e32 v130, v93
	v_add_f32_e32 v93, v41, v131
	v_mul_f32_e32 v93, 0xbfb8aa3b, v93
	v_exp_f32_e32 v93, v93
	v_mov_b32_dpp v126, v94 row_shr:1 row_mask:0xf bank_mask:0xf
	v_add_f32_e32 v93, 1.0, v93
	v_rcp_f32_e32 v95, v93
	v_add_f32_e32 v93, v37, v135
	v_mul_f32_e32 v93, 0xbfb8aa3b, v93
	v_exp_f32_e32 v93, v93
	v_mul_f32_e32 v95, 0xc1000000, v95
	v_mul_f32_e32 v95, v149, v95
	v_mul_f32_e32 v95, 0x3fb8aa3b, v95
	v_exp_f32_e32 v95, v95
	v_add_f32_e32 v93, 1.0, v93
	v_rcp_f32_e32 v93, v93
	v_fma_f32 v127, -v95, v95, 1.0
	v_sqrt_f32_e32 v131, v127
	v_mov_b32_e32 v127, 1.0
	s_nop 1
	v_mov_b32_dpp v127, v95 row_shr:1 row_mask:0xf bank_mask:0xf
	v_pk_mul_f32 v[134:135], v[94:95], v[126:127]
	v_mov_b32_e32 v126, 1.0
	v_mov_b32_e32 v127, 1.0
	s_nop 0
	v_mov_b32_dpp v126, v134 row_shr:2 row_mask:0xf bank_mask:0xf
	v_mov_b32_dpp v127, v135 row_shr:2 row_mask:0xf bank_mask:0xf
	v_pk_mul_f32 v[138:139], v[134:135], v[126:127]
	v_mov_b32_e32 v126, 1.0
	v_mov_b32_e32 v127, 1.0
	s_nop 0
	v_mov_b32_dpp v126, v138 row_shr:4 row_mask:0xf bank_mask:0xf
	v_mov_b32_dpp v127, v139 row_shr:4 row_mask:0xf bank_mask:0xf
	v_pk_mul_f32 v[140:141], v[138:139], v[126:127]
	v_mov_b32_e32 v126, 1.0
	v_mov_b32_e32 v127, 1.0
	s_nop 0
	v_mov_b32_dpp v126, v140 row_shr:8 row_mask:0xf bank_mask:0xf
	v_mov_b32_dpp v127, v141 row_shr:8 row_mask:0xf bank_mask:0xf
	v_pk_mul_f32 v[142:143], v[140:141], v[126:127]
	s_nop 0
	v_pk_mul_f32 v[128:129], v[142:143], v[84:85]
	v_add_u32_e32 v84, 0x20c0, v145
	ds_read2_b32 v[84:85], v84 offset1:1
	ds_bpermute_b32 v126, v1, v128
	ds_bpermute_b32 v127, v1, v129
	s_waitcnt lgkmcnt(0)
; __device__ __forceinline__ unsigned pk2(float lo, float hi) { const f32x2_t v = {lo, hi}; const bf16x2_t b = __builtin_convertvector(v, bf16x2_t); return __builtin_bit_cast(unsigned, b); }
; __device__ __forceinline__ float sigmoidf_(float x) { return __builtin_amdgcn_rcpf(1.0f + __expf(-x)); }
; __device__ __forceinline__ float bcast15(float v, int lane) { return bperm_f((lane & 48) | 15, v); }
; __device__ __forceinline__ void w_lru_m1(const Args& a, int l, unsigned char* ws, const bf16_t* proj, bf16_t* y, LAS unsigned char* wl, int b, int ck_, int h, int lane) {
;     ...
;         for (int tb = 0; tb < 4; ++tb) { const int tok = 16 * tb + lo;
;             f32x4 ga = {0.f, 0.f, 0.f, 0.f}, gx = {0.f, 0.f, 0.f, 0.f};
; #pragma unroll
;             for (int kk = 0; kk < 2; ++kk) { ga = __builtin_amdgcn_mfma_f32_16x16x32_bf16(WaF[kk], Xf[tb][kk], ga, 0, 0, 0); gx = __builtin_amdgcn_mfma_f32_16x16x32_bf16(WxF[kk], Xf[tb][kk], gx, 0, 0, 0); }
;             float hv[4], pv[4];
; #pragma unroll
;             for (int r = 0; r < 4; ++r) {
;                 const float rg = sigmoidf_(ga[r] + bav[r]), ig = sigmoidf_(gx[r] + bxv[r]);
;                 const float la = -8.0f * rg * sp[r]; float A = __expf(la);
;                 float U = __builtin_amdgcn_sqrtf(1.0f - A * A) * (ig * xcf[tok * 65 + j0 + r]);
;                 { const float As = dpp_shr1<1>(A), Us = dpp_shr0<1>(U); U = A * Us + U; A = A * As; }
;                 { const float As = dpp_shr1<2>(A), Us = dpp_shr0<2>(U); U = A * Us + U; A = A * As; }
;                 { const float As = dpp_shr1<4>(A), Us = dpp_shr0<4>(U); U = A * Us + U; A = A * As; }
;                 { const float As = dpp_shr1<8>(A), Us = dpp_shr0<8>(U); U = A * Us + U; A = A * As; }
;                 const float hh = U + A * hc[r], PP = A * Pc[r];
;                 hc[r] = bcast15(hh, lane); Pc[r] = bcast15(PP, lane); hv[r] = hh; pv[r] = PP; }
;             *(unsigned long long*)(y + (size_t)(row0 + tok) * DM + 64 * h + j0) = (unsigned long long)pk2(hv[0], hv[1]) | ((unsigned long long)pk2(hv[2], hv[3]) << 32);
;             *(unsigned long long*)((bf16_t*)(ws + WS_P) + (size_t)(row0 + tok) * 512 + 64 * h + j0) = (unsigned long long)pk2(pv[0], pv[1]) | ((unsigned long long)pk2(pv[2], pv[3]) << 32);
;         }
	v_pk_mul_f32 v[84:85], v[84:85], v[92:93]
	s_nop 0
	v_pk_mul_f32 v[84:85], v[84:85], v[130:131]
	s_nop 1
	v_mov_b32_dpp v92, v84 row_shr:1 row_mask:0xf bank_mask:0xf bound_ctrl:1
	v_mov_b32_dpp v93, v85 row_shr:1 row_mask:0xf bank_mask:0xf bound_ctrl:1
	v_pk_fma_f32 v[84:85], v[94:95], v[92:93], v[84:85]
	s_nop 1
	v_mov_b32_dpp v92, v84 row_shr:2 row_mask:0xf bank_mask:0xf bound_ctrl:1
	v_mov_b32_dpp v93, v85 row_shr:2 row_mask:0xf bank_mask:0xf bound_ctrl:1
	v_pk_fma_f32 v[84:85], v[134:135], v[92:93], v[84:85]
	s_nop 1
	v_mov_b32_dpp v92, v84 row_shr:4 row_mask:0xf bank_mask:0xf bound_ctrl:1
	v_mov_b32_dpp v93, v85 row_shr:4 row_mask:0xf bank_mask:0xf bound_ctrl:1
	v_pk_fma_f32 v[84:85], v[138:139], v[92:93], v[84:85]
	s_nop 1
	v_mov_b32_dpp v92, v84 row_shr:8 row_mask:0xf bank_mask:0xf bound_ctrl:1
	v_mov_b32_dpp v93, v85 row_shr:8 row_mask:0xf bank_mask:0xf bound_ctrl:1
	v_pk_fma_f32 v[84:85], v[140:141], v[92:93], v[84:85]
	v_mov_b32_e32 v92, 1.0
	v_pk_fma_f32 v[124:125], v[142:143], v[124:125], v[84:85]
	v_add_f32_e32 v84, v42, v132
	v_mul_f32_e32 v84, 0xbfb8aa3b, v84
	v_exp_f32_e32 v84, v84
	ds_bpermute_b32 v94, v1, v124
	ds_bpermute_b32 v95, v1, v125
	v_cvt_pk_bf16_f32 v124, v124, v125
	v_add_f32_e32 v84, 1.0, v84
	v_rcp_f32_e32 v85, v84
	v_add_f32_e32 v84, v38, v136
	v_mul_f32_e32 v84, 0xbfb8aa3b, v84
	v_exp_f32_e32 v84, v84
	v_mul_f32_e32 v85, 0xc1000000, v85
	v_mul_f32_e32 v85, v2, v85
	v_mul_f32_e32 v85, 0x3fb8aa3b, v85
	v_exp_f32_e32 v130, v85
	v_add_f32_e32 v84, 1.0, v84
	v_rcp_f32_e32 v84, v84
	v_fma_f32 v85, -v130, v130, 1.0
	v_sqrt_f32_e32 v132, v85
	v_add_f32_e32 v85, v43, v133
	v_mul_f32_e32 v85, 0xbfb8aa3b, v85
	v_exp_f32_e32 v85, v85
	v_mov_b32_dpp v92, v130 row_shr:1 row_mask:0xf bank_mask:0xf
	v_add_f32_e32 v85, 1.0, v85
	v_rcp_f32_e32 v93, v85
	v_add_f32_e32 v85, v39, v137
	v_mul_f32_e32 v85, 0xbfb8aa3b, v85
	v_exp_f32_e32 v85, v85
	v_mul_f32_e32 v93, 0xc1000000, v93
	v_mul_f32_e32 v93, v148, v93
	v_mul_f32_e32 v93, 0x3fb8aa3b, v93
	v_exp_f32_e32 v131, v93
	v_add_f32_e32 v85, 1.0, v85
	v_rcp_f32_e32 v85, v85
	v_fma_f32 v93, -v131, v131, 1.0
	v_sqrt_f32_e32 v133, v93
	v_mov_b32_e32 v93, 1.0
	s_nop 1
	v_mov_b32_dpp v93, v131 row_shr:1 row_mask:0xf bank_mask:0xf
	v_pk_mul_f32 v[134:135], v[130:131], v[92:93]
	v_mov_b32_e32 v92, 1.0
	v_mov_b32_e32 v93, 1.0
	s_nop 0
	v_mov_b32_dpp v92, v134 row_shr:2 row_mask:0xf bank_mask:0xf
	v_mov_b32_dpp v93, v135 row_shr:2 row_mask:0xf bank_mask:0xf
	v_pk_mul_f32 v[136:137], v[134:135], v[92:93]
	v_mov_b32_e32 v92, 1.0
	v_mov_b32_e32 v93, 1.0
	s_nop 0
	v_mov_b32_dpp v92, v136 row_shr:4 row_mask:0xf bank_mask:0xf
	v_mov_b32_dpp v93, v137 row_shr:4 row_mask:0xf bank_mask:0xf
	v_pk_mul_f32 v[138:139], v[136:137], v[92:93]
	v_mov_b32_e32 v92, 1.0
	v_mov_b32_e32 v93, 1.0
	s_nop 0
	v_mov_b32_dpp v92, v138 row_shr:8 row_mask:0xf bank_mask:0xf
	v_mov_b32_dpp v93, v139 row_shr:8 row_mask:0xf bank_mask:0xf
	v_pk_mul_f32 v[140:141], v[138:139], v[92:93]
	v_add_u32_e32 v93, 0x20c8, v145
	ds_read2_b32 v[142:143], v93 offset1:1
	v_pk_mul_f32 v[86:87], v[140:141], v[86:87]
	ds_bpermute_b32 v92, v1, v86
	ds_bpermute_b32 v93, v1, v87
	s_waitcnt lgkmcnt(0)
	v_pk_mul_f32 v[84:85], v[84:85], v[142:143]
	s_nop 0
	v_pk_mul_f32 v[84:85], v[132:133], v[84:85]
	s_nop 1
	v_mov_b32_dpp v132, v84 row_shr:1 row_mask:0xf bank_mask:0xf bound_ctrl:1
	v_mov_b32_dpp v133, v85 row_shr:1 row_mask:0xf bank_mask:0xf bound_ctrl:1
	v_pk_fma_f32 v[84:85], v[130:131], v[132:133], v[84:85]
	s_nop 1
	v_mov_b32_dpp v130, v84 row_shr:2 row_mask:0xf bank_mask:0xf bound_ctrl:1
	v_mov_b32_dpp v131, v85 row_shr:2 row_mask:0xf bank_mask:0xf bound_ctrl:1
	v_pk_fma_f32 v[84:85], v[134:135], v[130:131], v[84:85]
	s_nop 1
	v_mov_b32_dpp v130, v84 row_shr:4 row_mask:0xf bank_mask:0xf bound_ctrl:1
	v_mov_b32_dpp v131, v85 row_shr:4 row_mask:0xf bank_mask:0xf bound_ctrl:1
	v_pk_fma_f32 v[84:85], v[136:137], v[130:131], v[84:85]
	s_nop 1
	v_mov_b32_dpp v130, v84 row_shr:8 row_mask:0xf bank_mask:0xf bound_ctrl:1
	v_mov_b32_dpp v131, v85 row_shr:8 row_mask:0xf bank_mask:0xf bound_ctrl:1
	v_pk_fma_f32 v[84:85], v[138:139], v[130:131], v[84:85]
	s_nop 0
	v_pk_fma_f32 v[122:123], v[140:141], v[122:123], v[84:85]
	ds_bpermute_b32 v84, v1, v122
	ds_bpermute_b32 v85, v1, v123
	v_cvt_pk_bf16_f32 v125, v122, v123
	v_cvt_pk_bf16_f32 v122, v128, v129
	v_cvt_pk_bf16_f32 v123, v86, v87
	v_mov_b64_e32 v[240:241], v[124:125]
	s_nop 1
	v_permlane16_swap_b32_e32 v238, v240
	v_permlane16_swap_b32_e32 v239, v241
	global_store_dwordx4 v[96:97], v[238:241], off
	v_mov_b64_e32 v[244:245], v[122:123]
	s_nop 1
	v_permlane16_swap_b32_e32 v242, v244
	v_permlane16_swap_b32_e32 v243, v245
	global_store_dwordx4 v[98:99], v[242:245], off
	v_mfma_f32_16x16x32_bf16 v[122:125], v[72:75], v[4:7], 0
	v_mfma_f32_16x16x32_bf16 v[72:75], v[76:79], v[20:23], v[68:71]
	v_mfma_f32_16x16x32_bf16 v[68:71], v[80:83], v[20:23], v[122:125]
	s_nop 6
	v_add_f32_e32 v40, v40, v72
	v_add_f32_e32 v41, v41, v73
	v_add_f32_e32 v42, v42, v74
	v_mul_f32_e32 v40, 0xbfb8aa3b, v40
	v_mul_f32_e32 v41, 0xbfb8aa3b, v41
	v_mul_f32_e32 v42, 0xbfb8aa3b, v42
	v_exp_f32_e32 v40, v40
	v_exp_f32_e32 v41, v41
	v_exp_f32_e32 v42, v42
	v_add_f32_e32 v36, v36, v68
	v_add_f32_e32 v37, v37, v69
	v_add_f32_e32 v38, v38, v70
	v_mul_f32_e32 v36, 0xbfb8aa3b, v36
	v_mul_f32_e32 v37, 0xbfb8aa3b, v37
	v_mul_f32_e32 v38, 0xbfb8aa3b, v38
	v_add_f32_e32 v40, 1.0, v40
	v_exp_f32_e32 v36, v36
	v_add_f32_e32 v41, 1.0, v41
	v_exp_f32_e32 v37, v37
	v_add_f32_e32 v42, 1.0, v42
	v_exp_f32_e32 v38, v38
	v_rcp_f32_e32 v72, v40
	v_rcp_f32_e32 v68, v41
	v_rcp_f32_e32 v42, v42
	v_add_f32_e32 v36, 1.0, v36
	v_add_f32_e32 v37, 1.0, v37
; __device__ __forceinline__ unsigned pk2(float lo, float hi) { const f32x2_t v = {lo, hi}; const bf16x2_t b = __builtin_convertvector(v, bf16x2_t); return __builtin_bit_cast(unsigned, b); }
; __device__ __forceinline__ float sigmoidf_(float x) { return __builtin_amdgcn_rcpf(1.0f + __expf(-x)); }
; __device__ __forceinline__ void w_lru_m1(const Args& a, int l, unsigned char* ws, const bf16_t* proj, bf16_t* y, LAS unsigned char* wl, int b, int ck_, int h, int lane) {
;     ...
;         for (int tb = 0; tb < 4; ++tb) { const int tok = 16 * tb + lo;
;             f32x4 ga = {0.f, 0.f, 0.f, 0.f}, gx = {0.f, 0.f, 0.f, 0.f};
; #pragma unroll
;             for (int kk = 0; kk < 2; ++kk) { ga = __builtin_amdgcn_mfma_f32_16x16x32_bf16(WaF[kk], Xf[tb][kk], ga, 0, 0, 0); gx = __builtin_amdgcn_mfma_f32_16x16x32_bf16(WxF[kk], Xf[tb][kk], gx, 0, 0, 0); }
;             float hv[4], pv[4];
; #pragma unroll
;             for (int r = 0; r < 4; ++r) {
;                 const float rg = sigmoidf_(ga[r] + bav[r]), ig = sigmoidf_(gx[r] + bxv[r]);
;                 const float la = -8.0f * rg * sp[r]; float A = __expf(la);
;                 float U = __builtin_amdgcn_sqrtf(1.0f - A * A) * (ig * xcf[tok * 65 + j0 + r]);
;                 { const float As = dpp_shr1<1>(A), Us = dpp_shr0<1>(U); U = A * Us + U; A = A * As; }
;                 { const float As = dpp_shr1<2>(A), Us = dpp_shr0<2>(U); U = A * Us + U; A = A * As; }
;                 { const float As = dpp_shr1<4>(A), Us = dpp_shr0<4>(U); U = A * Us + U; A = A * As; }
;                 { const float As = dpp_shr1<8>(A), Us = dpp_shr0<8>(U); U = A * Us + U; A = A * As; }
;                 const float hh = U + A * hc[r], PP = A * Pc[r];
;                 hc[r] = bcast15(hh, lane); Pc[r] = bcast15(PP, lane); hv[r] = hh; pv[r] = PP; }
;             *(unsigned long long*)(y + (size_t)(row0 + tok) * DM + 64 * h + j0) = (unsigned long long)pk2(hv[0], hv[1]) | ((unsigned long long)pk2(hv[2], hv[3]) << 32);
;             *(unsigned long long*)((bf16_t*)(ws + WS_P) + (size_t)(row0 + tok) * 512 + 64 * h + j0) = (unsigned long long)pk2(pv[0], pv[1]) | ((unsigned long long)pk2(pv[2], pv[3]) << 32);
;         }
;         if (lo == 0) { const size_t so = (size_t)(b * NCH + ck_) * 512 + 64 * h + j0;
; #pragma unroll
;             for (int r = 0; r < 4; ++r) { ((float*)(ws + WS_LRUA))[so + r] = Pc[r]; ((float*)(ws + WS_LRUH))[so + r] = hc[r]; } }
	v_add_f32_e32 v38, 1.0, v38
	v_rcp_f32_e32 v40, v36
	v_mul_f32_e32 v36, 0xc1000000, v72
	v_rcp_f32_e32 v41, v37
	v_mul_f32_e32 v37, 0xc1000000, v68
	v_rcp_f32_e32 v70, v38
	v_mul_f32_e32 v38, 0xc1000000, v42
	v_mul_f32_e32 v36, v147, v36
	v_mul_f32_e32 v37, v149, v37
	v_mul_f32_e32 v2, v2, v38
	v_mul_f32_e32 v36, 0x3fb8aa3b, v36
	v_mul_f32_e32 v37, 0x3fb8aa3b, v37
	v_mul_f32_e32 v2, 0x3fb8aa3b, v2
	v_exp_f32_e32 v72, v36
	v_exp_f32_e32 v73, v37
	v_exp_f32_e32 v42, v2
	v_add_f32_e32 v39, v39, v71
	v_fma_f32 v36, -v72, v72, 1.0
	v_fma_f32 v37, -v73, v73, 1.0
	v_fma_f32 v2, -v42, v42, 1.0
	v_sqrt_f32_e32 v76, v36
	v_mov_b32_e32 v36, 1.0
	v_sqrt_f32_e32 v77, v37
	v_mov_b32_e32 v37, 1.0
	v_sqrt_f32_e32 v74, v2
	v_add_f32_e32 v2, v43, v75
	v_mov_b32_dpp v36, v72 row_shr:1 row_mask:0xf bank_mask:0xf
	v_mov_b32_dpp v37, v73 row_shr:1 row_mask:0xf bank_mask:0xf
	v_mul_f32_e32 v2, 0xbfb8aa3b, v2
	v_pk_mul_f32 v[78:79], v[72:73], v[36:37]
	v_mov_b32_e32 v36, 1.0
	v_mov_b32_e32 v37, 1.0
	v_exp_f32_e32 v2, v2
	v_mov_b32_dpp v36, v78 row_shr:2 row_mask:0xf bank_mask:0xf
	v_mov_b32_dpp v37, v79 row_shr:2 row_mask:0xf bank_mask:0xf
	v_pk_mul_f32 v[80:81], v[78:79], v[36:37]
	v_mov_b32_e32 v36, 1.0
	v_mov_b32_e32 v37, 1.0
	v_add_f32_e32 v2, 1.0, v2
	v_mov_b32_dpp v36, v80 row_shr:4 row_mask:0xf bank_mask:0xf
	v_mov_b32_dpp v37, v81 row_shr:4 row_mask:0xf bank_mask:0xf
	v_pk_mul_f32 v[82:83], v[80:81], v[36:37]
	v_mov_b32_e32 v36, 1.0
	v_mov_b32_e32 v37, 1.0
	v_rcp_f32_e32 v2, v2
	v_mov_b32_dpp v36, v82 row_shr:8 row_mask:0xf bank_mask:0xf
	v_mov_b32_dpp v37, v83 row_shr:8 row_mask:0xf bank_mask:0xf
	v_pk_mul_f32 v[86:87], v[82:83], v[36:37]
	v_add_u32_e32 v37, 0x3100, v145
	ds_read2_b32 v[122:123], v37 offset1:1
	v_mul_f32_e32 v39, 0xbfb8aa3b, v39
	v_mul_f32_e32 v2, 0xc1000000, v2
	v_exp_f32_e32 v39, v39
	v_mul_f32_e32 v2, v148, v2
	v_mul_f32_e32 v2, 0x3fb8aa3b, v2
	s_waitcnt lgkmcnt(0)
	v_pk_mul_f32 v[40:41], v[122:123], v[40:41]
	v_exp_f32_e32 v43, v2
	v_pk_mul_f32 v[40:41], v[40:41], v[76:77]
	v_add_f32_e32 v39, 1.0, v39
	v_mov_b32_e32 v38, 1.0
	v_mov_b32_dpp v76, v40 row_shr:1 row_mask:0xf bank_mask:0xf bound_ctrl:1
	v_mov_b32_dpp v77, v41 row_shr:1 row_mask:0xf bank_mask:0xf bound_ctrl:1
	v_pk_fma_f32 v[40:41], v[72:73], v[76:77], v[40:41]
	v_rcp_f32_e32 v71, v39
	v_mov_b32_e32 v39, 1.0
	v_mov_b32_dpp v72, v40 row_shr:2 row_mask:0xf bank_mask:0xf bound_ctrl:1
	v_mov_b32_dpp v73, v41 row_shr:2 row_mask:0xf bank_mask:0xf bound_ctrl:1
	v_mov_b32_dpp v38, v42 row_shr:1 row_mask:0xf bank_mask:0xf
	v_mov_b32_dpp v39, v43 row_shr:1 row_mask:0xf bank_mask:0xf
	v_pk_fma_f32 v[40:41], v[78:79], v[72:73], v[40:41]
	v_pk_mul_f32 v[78:79], v[42:43], v[38:39]
	v_mov_b32_e32 v38, 1.0
	v_mov_b32_e32 v39, 1.0
	v_mov_b32_dpp v72, v40 row_shr:4 row_mask:0xf bank_mask:0xf bound_ctrl:1
	v_mov_b32_dpp v73, v41 row_shr:4 row_mask:0xf bank_mask:0xf bound_ctrl:1
	v_mov_b32_dpp v38, v78 row_shr:2 row_mask:0xf bank_mask:0xf
	v_mov_b32_dpp v39, v79 row_shr:2 row_mask:0xf bank_mask:0xf
	v_pk_fma_f32 v[40:41], v[80:81], v[72:73], v[40:41]
	v_pk_mul_f32 v[80:81], v[78:79], v[38:39]
	v_mov_b32_e32 v38, 1.0
	v_mov_b32_e32 v39, 1.0
	v_mov_b32_dpp v72, v40 row_shr:8 row_mask:0xf bank_mask:0xf bound_ctrl:1
	v_mov_b32_dpp v73, v41 row_shr:8 row_mask:0xf bank_mask:0xf bound_ctrl:1
	v_mov_b32_dpp v38, v80 row_shr:4 row_mask:0xf bank_mask:0xf
	v_mov_b32_dpp v39, v81 row_shr:4 row_mask:0xf bank_mask:0xf
	v_pk_fma_f32 v[40:41], v[82:83], v[72:73], v[40:41]
	v_pk_mul_f32 v[82:83], v[80:81], v[38:39]
	v_mov_b32_e32 v38, 1.0
	v_mov_b32_e32 v39, 1.0
	v_fma_f32 v2, -v43, v43, 1.0
	v_mov_b32_dpp v38, v82 row_shr:8 row_mask:0xf bank_mask:0xf
	v_mov_b32_dpp v39, v83 row_shr:8 row_mask:0xf bank_mask:0xf
	v_pk_mul_f32 v[68:69], v[86:87], v[126:127]
	v_pk_fma_f32 v[72:73], v[86:87], v[94:95], v[40:41]
	v_sqrt_f32_e32 v75, v2
	v_pk_mul_f32 v[86:87], v[82:83], v[38:39]
	v_add_u32_e32 v2, 0x3108, v145
	v_pk_mul_f32 v[76:77], v[86:87], v[92:93]
	ds_read2_b32 v[92:93], v2 offset1:1
	ds_bpermute_b32 v36, v1, v68
	ds_bpermute_b32 v40, v1, v72
	ds_bpermute_b32 v41, v1, v73
	ds_bpermute_b32 v37, v1, v69
	s_waitcnt lgkmcnt(0)
	v_pk_mul_f32 v[70:71], v[70:71], v[92:93]
	ds_bpermute_b32 v38, v1, v76
	v_pk_mul_f32 v[70:71], v[74:75], v[70:71]
	ds_bpermute_b32 v39, v1, v77
	v_cvt_pk_bf16_f32 v72, v72, v73
	v_mov_b32_dpp v74, v70 row_shr:1 row_mask:0xf bank_mask:0xf bound_ctrl:1
	v_mov_b32_dpp v75, v71 row_shr:1 row_mask:0xf bank_mask:0xf bound_ctrl:1
	v_pk_fma_f32 v[42:43], v[42:43], v[74:75], v[70:71]
	v_cvt_pk_bf16_f32 v68, v68, v69
	v_cvt_pk_bf16_f32 v69, v76, v77
	v_mov_b32_dpp v70, v42 row_shr:2 row_mask:0xf bank_mask:0xf bound_ctrl:1
	v_mov_b32_dpp v71, v43 row_shr:2 row_mask:0xf bank_mask:0xf bound_ctrl:1
	v_pk_fma_f32 v[42:43], v[78:79], v[70:71], v[42:43]
	s_nop 1
	v_mov_b32_dpp v70, v42 row_shr:4 row_mask:0xf bank_mask:0xf bound_ctrl:1
	v_mov_b32_dpp v71, v43 row_shr:4 row_mask:0xf bank_mask:0xf bound_ctrl:1
	v_pk_fma_f32 v[42:43], v[80:81], v[70:71], v[42:43]
	s_nop 1
	v_mov_b32_dpp v70, v42 row_shr:8 row_mask:0xf bank_mask:0xf bound_ctrl:1
	v_mov_b32_dpp v71, v43 row_shr:8 row_mask:0xf bank_mask:0xf bound_ctrl:1
	v_pk_fma_f32 v[42:43], v[82:83], v[70:71], v[42:43]
	s_nop 0
	v_pk_fma_f32 v[70:71], v[86:87], v[84:85], v[42:43]
	ds_bpermute_b32 v42, v1, v70
	ds_bpermute_b32 v43, v1, v71
	v_cvt_pk_bf16_f32 v73, v70, v71
	v_mov_b64_e32 v[248:249], v[72:73]
	s_nop 1
	v_permlane16_swap_b32_e32 v246, v248
	v_permlane16_swap_b32_e32 v247, v249
	global_store_dwordx4 v[114:115], v[246:249], off
	v_mov_b64_e32 v[252:253], v[68:69]
	s_nop 1
	v_permlane16_swap_b32_e32 v250, v252
	v_permlane16_swap_b32_e32 v251, v253
	global_store_dwordx4 v[116:117], v[250:253], off
	s_and_saveexec_b64 s[34:35], vcc
	s_cbranch_execz .LBB0_525
	v_add_u32_e32 v68, 16, v0
	v_ashrrev_i32_e32 v69, 31, v68
	v_lshl_add_u64 v[68:69], s[42:43], 0, v[68:69]
	v_lshlrev_b64 v[68:69], 2, v[68:69]
	v_lshl_add_u64 v[70:71], s[84:85], 0, v[68:69]
	v_lshl_add_u64 v[68:69], s[86:87], 0, v[68:69]
	s_waitcnt lgkmcnt(0)
	global_store_dwordx4 v[70:71], v[36:39], off
	global_store_dwordx4 v[68:69], v[40:43], off
; __device__ __forceinline__ float sigmoidf_(float x) { return __builtin_amdgcn_rcpf(1.0f + __expf(-x)); }
; __device__ __forceinline__ void w_lru_m1(const Args& a, int l, unsigned char* ws, const bf16_t* proj, bf16_t* y, LAS unsigned char* wl, int b, int ck_, int h, int lane) {
;     ...
;         if (jb < 3) {
; #pragma unroll
;             for (int kk = 0; kk < 2; ++kk) { nWa[kk] = *(const bf16x8*)(waT + (16 * (jb + 1) + lo) * 64 + 32 * kk + 8 * fq); nWx[kk] = *(const bf16x8*)(wxT + (16 * (jb + 1) + lo) * 64 + 32 * kk + 8 * fq); }
;             nba = *(const f32x4*)(ba + 16 * (jb + 1) + 4 * fq); nbx = *(const f32x4*)(bx + 16 * (jb + 1) + 4 * fq); nlam = *(const f32x4*)(lam + 16 * (jb + 1) + 4 * fq);
;         }
;         const int j0 = 16 * jb + 4 * fq;
;         float bav[4], bxv[4], sp[4], hc[4], Pc[4];
; #pragma unroll
;         for (int r = 0; r < 4; ++r) { bav[r] = pba[r]; bxv[r] = pbx[r]; sp[r] = log1pf(__expf(-plam[r])); hc[r] = 0.f; Pc[r] = 1.f; }
; #pragma unroll
;         for (int tb = 0; tb < 4; ++tb) { const int tok = 16 * tb + lo;
;             f32x4 ga = {0.f, 0.f, 0.f, 0.f}, gx = {0.f, 0.f, 0.f, 0.f};
; #pragma unroll
;             for (int kk = 0; kk < 2; ++kk) { ga = __builtin_amdgcn_mfma_f32_16x16x32_bf16(WaF[kk], Xf[tb][kk], ga, 0, 0, 0); gx = __builtin_amdgcn_mfma_f32_16x16x32_bf16(WxF[kk], Xf[tb][kk], gx, 0, 0, 0); }
;             float hv[4], pv[4];
; #pragma unroll
;             for (int r = 0; r < 4; ++r) {
;                 const float rg = sigmoidf_(ga[r] + bav[r]), ig = sigmoidf_(gx[r] + bxv[r]);
;                 const float la = -8.0f * rg * sp[r]; float A = __expf(la);
;                 float U = __builtin_amdgcn_sqrtf(1.0f - A * A) * (ig * xcf[tok * 65 + j0 + r]);
;                 { const float As = dpp_shr1<1>(A), Us = dpp_shr0<1>(U); U = A * Us + U; A = A * As; }
.LBB0_525:
	s_or_b64 exec, exec, s[34:35]
	v_lshl_or_b32 v2, v146, 1, v210
	v_lshl_add_u64 v[36:37], v[118:119], 0, v[2:3]
	s_waitcnt lgkmcnt(0)
	v_lshl_add_u64 v[38:39], v[120:121], 0, v[2:3]
	s_waitcnt vmcnt(10)
	s_nop 7
	global_load_dwordx4 v[68:71], v[36:37], off
	global_load_dwordx4 v[72:75], v[38:39], off
	global_load_dwordx4 v[76:79], v[36:37], off offset:1024
	global_load_dwordx4 v[80:83], v[38:39], off offset:1024
	global_load_dwordx4 v[40:43], v[108:109], off offset:192
	s_nop 0
	global_load_dwordx4 v[36:39], v[110:111], off offset:192
	global_load_dwordx4 v[84:87], v[112:113], off offset:192
	ds_read2_b32 v[124:125], v145 offset0:32 offset1:33
	ds_read2_b32 v[128:129], v145 offset0:34 offset1:35
	s_nop 7
	s_nop 0
	s_nop 7
	s_nop 0
	s_nop 7
	s_nop 0
	s_nop 7
	s_nop 1
	s_nop 7
	s_nop 1
	s_nop 7
	s_nop 1
	s_nop 7
	v_mov_b32_e32 v2, v88
	s_nop 7
	s_nop 0
	s_nop 7
	s_nop 0
	s_nop 7
	s_nop 0
	s_nop 7
	s_nop 0
	s_nop 7
	s_nop 0
	s_nop 7
	s_nop 0
	s_nop 7
	s_nop 1
	s_nop 7
	s_nop 1
	s_nop 7
	s_nop 1
	s_nop 7
	v_mov_b32_e32 v134, v89
	s_nop 7
	s_nop 0
	s_nop 7
	s_nop 0
	s_nop 7
	s_nop 0
	s_nop 7
	s_nop 0
	s_nop 7
	s_nop 0
	s_nop 7
	s_nop 0
	s_nop 7
	s_nop 1
	s_nop 7
	s_nop 1
	s_nop 7
	s_nop 1
	s_nop 7
	v_mov_b32_e32 v135, v90
	s_nop 7
	s_nop 0
	s_nop 7
	s_nop 0
	s_nop 7
	s_nop 0
	s_nop 7
	s_nop 0
	s_nop 7
	s_nop 0
	s_nop 7
	s_nop 0
	s_nop 7
	v_mfma_f32_16x16x32_bf16 v[92:95], v[60:63], v[16:19], 0
	s_nop 0
	s_nop 7
	v_mfma_f32_16x16x32_bf16 v[110:113], v[52:55], v[32:35], v[92:95]
	s_nop 0
	s_nop 7
	s_nop 1
	s_nop 7
	v_mov_b32_e32 v136, v91
	v_mfma_f32_16x16x32_bf16 v[88:91], v[64:67], v[16:19], 0
	s_nop 0
	v_add_f32_e32 v92, v44, v110
	v_add_f32_e32 v93, v45, v111
	v_mul_f32_e32 v92, 0xbfb8aa3b, v92
	v_mfma_f32_16x16x32_bf16 v[88:91], v[56:59], v[32:35], v[88:91]
	v_mul_f32_e32 v93, 0xbfb8aa3b, v93
	v_exp_f32_e32 v92, v92
	v_exp_f32_e32 v93, v93
	v_add_f32_e32 v92, 1.0, v92
	v_add_f32_e32 v93, 1.0, v93
	s_nop 2
	v_add_f32_e32 v88, v48, v88
	v_add_f32_e32 v89, v49, v89
	v_mul_f32_e32 v88, 0xbfb8aa3b, v88
	v_mul_f32_e32 v89, 0xbfb8aa3b, v89
	v_exp_f32_e32 v88, v88
	v_exp_f32_e32 v89, v89
	v_rcp_f32_e32 v92, v92
	v_rcp_f32_e32 v93, v93
	v_add_f32_e32 v88, 1.0, v88
	v_add_f32_e32 v89, 1.0, v89
	v_rcp_f32_e32 v88, v88
	v_rcp_f32_e32 v89, v89
	s_waitcnt lgkmcnt(0)
	v_pk_mul_f32 v[92:93], v[124:125], v[92:93]
	v_add_f32_e32 v90, v50, v90
	v_mul_f32_e32 v88, 0xc1000000, v88
	v_mul_f32_e32 v89, 0xc1000000, v89
	v_mul_f32_e32 v88, v2, v88
	v_mul_f32_e32 v89, v134, v89
	v_mul_f32_e32 v88, 0x3fb8aa3b, v88
	v_mul_f32_e32 v89, 0x3fb8aa3b, v89
	v_exp_f32_e32 v108, v88
	v_exp_f32_e32 v109, v89
	v_add_f32_e32 v91, v51, v91
	v_mul_f32_e32 v90, 0xbfb8aa3b, v90
	v_fma_f32 v88, -v108, v108, 1.0
	v_fma_f32 v89, -v109, v109, 1.0
	v_sqrt_f32_e32 v110, v88
	v_sqrt_f32_e32 v111, v89
	v_mov_b32_e32 v88, 1.0
	v_mov_b32_e32 v89, 1.0
	v_mul_f32_e32 v91, 0xbfb8aa3b, v91
	v_pk_mul_f32 v[92:93], v[92:93], v[110:111]
	v_mov_b32_dpp v88, v108 row_shr:1 row_mask:0xf bank_mask:0xf
	v_mov_b32_dpp v89, v109 row_shr:1 row_mask:0xf bank_mask:0xf
	v_mov_b32_dpp v110, v92 row_shr:1 row_mask:0xf bank_mask:0xf bound_ctrl:1
	v_mov_b32_dpp v111, v93 row_shr:1 row_mask:0xf bank_mask:0xf bound_ctrl:1
	v_pk_fma_f32 v[92:93], v[108:109], v[110:111], v[92:93]
	v_pk_mul_f32 v[118:119], v[108:109], v[88:89]
	v_mov_b32_e32 v88, 1.0
	v_mov_b32_e32 v89, 1.0
	v_mov_b32_dpp v108, v92 row_shr:2 row_mask:0xf bank_mask:0xf bound_ctrl:1
	v_mov_b32_dpp v109, v93 row_shr:2 row_mask:0xf bank_mask:0xf bound_ctrl:1
	v_exp_f32_e32 v90, v90
	v_exp_f32_e32 v91, v91
	v_mov_b32_dpp v88, v118 row_shr:2 row_mask:0xf bank_mask:0xf
	v_mov_b32_dpp v89, v119 row_shr:2 row_mask:0xf bank_mask:0xf
	v_pk_fma_f32 v[92:93], v[118:119], v[108:109], v[92:93]
	v_pk_mul_f32 v[120:121], v[118:119], v[88:89]
	v_mov_b32_e32 v88, 1.0
	v_mov_b32_e32 v89, 1.0
	v_mov_b32_dpp v108, v92 row_shr:4 row_mask:0xf bank_mask:0xf bound_ctrl:1
	v_mov_b32_dpp v109, v93 row_shr:4 row_mask:0xf bank_mask:0xf bound_ctrl:1
	v_mov_b32_dpp v88, v120 row_shr:4 row_mask:0xf bank_mask:0xf
	v_mov_b32_dpp v89, v121 row_shr:4 row_mask:0xf bank_mask:0xf
	v_pk_fma_f32 v[92:93], v[120:121], v[108:109], v[92:93]
	v_pk_mul_f32 v[122:123], v[120:121], v[88:89]
	v_add_f32_e32 v90, 1.0, v90
	v_mov_b32_dpp v108, v92 row_shr:8 row_mask:0xf bank_mask:0xf bound_ctrl:1
	v_mov_b32_dpp v109, v93 row_shr:8 row_mask:0xf bank_mask:0xf bound_ctrl:1
	v_add_f32_e32 v91, 1.0, v91
	v_pk_fma_f32 v[92:93], v[122:123], v[108:109], v[92:93]
	v_rcp_f32_e32 v90, v90
	v_add_f32_e32 v108, v46, v112
	v_rcp_f32_e32 v91, v91
	v_add_f32_e32 v109, v47, v113
	v_mul_f32_e32 v108, 0xbfb8aa3b, v108
	v_mul_f32_e32 v109, 0xbfb8aa3b, v109
	v_exp_f32_e32 v108, v108
	v_exp_f32_e32 v109, v109
	v_mul_f32_e32 v90, 0xc1000000, v90
	v_mul_f32_e32 v91, 0xc1000000, v91
	v_mul_f32_e32 v90, v135, v90
	v_mul_f32_e32 v91, v136, v91
	v_add_f32_e32 v108, 1.0, v108
	v_mul_f32_e32 v90, 0x3fb8aa3b, v90
	v_add_f32_e32 v109, 1.0, v109
	v_mul_f32_e32 v91, 0x3fb8aa3b, v91
	v_rcp_f32_e32 v112, v108
	v_exp_f32_e32 v108, v90
	v_rcp_f32_e32 v113, v109
	v_exp_f32_e32 v109, v91
	v_mov_b32_e32 v88, 1.0
	v_fma_f32 v90, -v108, v108, 1.0
	v_sqrt_f32_e32 v118, v90
	v_fma_f32 v91, -v109, v109, 1.0
	v_sqrt_f32_e32 v119, v91
	v_pk_mul_f32 v[112:113], v[112:113], v[128:129]
	v_mov_b32_e32 v89, 1.0
	v_mov_b32_e32 v90, 1.0
	v_mov_b32_e32 v91, 1.0
	v_pk_mul_f32 v[112:113], v[118:119], v[112:113]
	v_mov_b32_dpp v88, v122 row_shr:8 row_mask:0xf bank_mask:0xf
	v_mov_b32_dpp v89, v123 row_shr:8 row_mask:0xf bank_mask:0xf
	v_mov_b32_dpp v90, v108 row_shr:1 row_mask:0xf bank_mask:0xf
	v_mov_b32_dpp v91, v109 row_shr:1 row_mask:0xf bank_mask:0xf
; __device__ __forceinline__ float sigmoidf_(float x) { return __builtin_amdgcn_rcpf(1.0f + __expf(-x)); }
; __device__ __forceinline__ float bcast15(float v, int lane) { return bperm_f((lane & 48) | 15, v); }
; __device__ __forceinline__ void w_lru_m1(const Args& a, int l, unsigned char* ws, const bf16_t* proj, bf16_t* y, LAS unsigned char* wl, int b, int ck_, int h, int lane) {
;     ...
;         for (int tb = 0; tb < 4; ++tb) { const int tok = 16 * tb + lo;
;             f32x4 ga = {0.f, 0.f, 0.f, 0.f}, gx = {0.f, 0.f, 0.f, 0.f};
; #pragma unroll
;             for (int kk = 0; kk < 2; ++kk) { ga = __builtin_amdgcn_mfma_f32_16x16x32_bf16(WaF[kk], Xf[tb][kk], ga, 0, 0, 0); gx = __builtin_amdgcn_mfma_f32_16x16x32_bf16(WxF[kk], Xf[tb][kk], gx, 0, 0, 0); }
;             float hv[4], pv[4];
; #pragma unroll
;             for (int r = 0; r < 4; ++r) {
;                 const float rg = sigmoidf_(ga[r] + bav[r]), ig = sigmoidf_(gx[r] + bxv[r]);
;                 const float la = -8.0f * rg * sp[r]; float A = __expf(la);
;                 float U = __builtin_amdgcn_sqrtf(1.0f - A * A) * (ig * xcf[tok * 65 + j0 + r]);
;                 { const float As = dpp_shr1<1>(A), Us = dpp_shr0<1>(U); U = A * Us + U; A = A * As; }
;                 { const float As = dpp_shr1<2>(A), Us = dpp_shr0<2>(U); U = A * Us + U; A = A * As; }
;                 { const float As = dpp_shr1<4>(A), Us = dpp_shr0<4>(U); U = A * Us + U; A = A * As; }
;                 { const float As = dpp_shr1<8>(A), Us = dpp_shr0<8>(U); U = A * Us + U; A = A * As; }
;                 const float hh = U + A * hc[r], PP = A * Pc[r];
;                 hc[r] = bcast15(hh, lane); Pc[r] = bcast15(PP, lane); hv[r] = hh; pv[r] = PP; }
	v_mov_b32_dpp v118, v112 row_shr:1 row_mask:0xf bank_mask:0xf bound_ctrl:1
	v_mov_b32_dpp v119, v113 row_shr:1 row_mask:0xf bank_mask:0xf bound_ctrl:1
	v_pk_mul_f32 v[94:95], v[122:123], v[88:89]
	v_pk_mul_f32 v[122:123], v[108:109], v[90:91]
	v_mov_b32_e32 v90, 1.0
	v_mov_b32_e32 v91, 1.0
	v_pk_fma_f32 v[108:109], v[108:109], v[118:119], v[112:113]
	v_mov_b32_dpp v90, v122 row_shr:2 row_mask:0xf bank_mask:0xf
	v_mov_b32_dpp v91, v123 row_shr:2 row_mask:0xf bank_mask:0xf
	v_mov_b32_dpp v112, v108 row_shr:2 row_mask:0xf bank_mask:0xf bound_ctrl:1
	v_mov_b32_dpp v113, v109 row_shr:2 row_mask:0xf bank_mask:0xf bound_ctrl:1
	v_pk_mul_f32 v[124:125], v[122:123], v[90:91]
	v_mov_b32_e32 v90, 1.0
	v_mov_b32_e32 v91, 1.0
	v_pk_fma_f32 v[108:109], v[122:123], v[112:113], v[108:109]
	v_mov_b32_dpp v90, v124 row_shr:4 row_mask:0xf bank_mask:0xf
	v_mov_b32_dpp v91, v125 row_shr:4 row_mask:0xf bank_mask:0xf
	v_mov_b32_dpp v112, v108 row_shr:4 row_mask:0xf bank_mask:0xf bound_ctrl:1
	v_mov_b32_dpp v113, v109 row_shr:4 row_mask:0xf bank_mask:0xf bound_ctrl:1
	v_pk_mul_f32 v[126:127], v[124:125], v[90:91]
	v_mov_b32_e32 v90, 1.0
	v_mov_b32_e32 v91, 1.0
	v_pk_fma_f32 v[108:109], v[124:125], v[112:113], v[108:109]
	v_mov_b32_dpp v90, v126 row_shr:8 row_mask:0xf bank_mask:0xf
	v_mov_b32_dpp v91, v127 row_shr:8 row_mask:0xf bank_mask:0xf
	v_mov_b32_dpp v112, v108 row_shr:8 row_mask:0xf bank_mask:0xf bound_ctrl:1
	v_mov_b32_dpp v113, v109 row_shr:8 row_mask:0xf bank_mask:0xf bound_ctrl:1
	v_pk_mul_f32 v[120:121], v[126:127], v[90:91]
	v_pk_fma_f32 v[108:109], v[126:127], v[112:113], v[108:109]
	v_pk_fma_f32 v[110:111], v[94:95], 0, v[92:93] op_sel_hi:[1,0,1]
	v_pk_fma_f32 v[112:113], v[120:121], 0, v[108:109] op_sel_hi:[1,0,1]
	ds_bpermute_b32 v92, v1, v110
	ds_bpermute_b32 v93, v1, v111
	v_cvt_pk_bf16_f32 v110, v110, v111
	v_cvt_pk_bf16_f32 v111, v112, v113
	ds_bpermute_b32 v108, v1, v112
	ds_bpermute_b32 v109, v1, v113
	v_mov_b64_e32 v[222:223], v[110:111]
	v_mfma_f32_16x16x32_bf16 v[110:113], v[64:67], v[12:15], 0
	ds_bpermute_b32 v88, v1, v94
	ds_bpermute_b32 v89, v1, v95
	v_cvt_pk_bf16_f32 v94, v94, v95
	v_mfma_f32_16x16x32_bf16 v[122:125], v[56:59], v[28:31], v[110:113]
	v_cvt_pk_bf16_f32 v95, v120, v121
	v_mov_b64_e32 v[226:227], v[94:95]
	ds_bpermute_b32 v90, v1, v120
	ds_bpermute_b32 v91, v1, v121
	v_mfma_f32_16x16x32_bf16 v[118:121], v[60:63], v[12:15], 0
	s_nop 2
	v_add_f32_e32 v94, v48, v122
	v_mul_f32_e32 v94, 0xbfb8aa3b, v94
	v_exp_f32_e32 v94, v94
	v_mfma_f32_16x16x32_bf16 v[118:121], v[52:55], v[28:31], v[118:121]
	v_mov_b32_e32 v112, 1.0
	v_add_f32_e32 v94, 1.0, v94
	v_rcp_f32_e32 v95, v94
	s_nop 0
	v_mul_f32_e32 v95, 0xc1000000, v95
	v_mul_f32_e32 v95, v2, v95
	v_mul_f32_e32 v95, 0x3fb8aa3b, v95
	v_exp_f32_e32 v110, v95
	v_add_f32_e32 v94, v44, v118
	v_mul_f32_e32 v94, 0xbfb8aa3b, v94
	v_exp_f32_e32 v94, v94
	v_fma_f32 v95, -v110, v110, 1.0
	v_sqrt_f32_e32 v118, v95
	v_add_f32_e32 v95, v49, v123
	v_mul_f32_e32 v95, 0xbfb8aa3b, v95
	v_exp_f32_e32 v95, v95
	v_mov_b32_dpp v112, v110 row_shr:1 row_mask:0xf bank_mask:0xf
	v_add_f32_e32 v94, 1.0, v94
	v_rcp_f32_e32 v94, v94
	v_add_f32_e32 v95, 1.0, v95
	v_rcp_f32_e32 v111, v95
	v_add_f32_e32 v95, v45, v119
	v_mul_f32_e32 v95, 0xbfb8aa3b, v95
	v_exp_f32_e32 v95, v95
	v_mul_f32_e32 v111, 0xc1000000, v111
	v_mul_f32_e32 v111, v134, v111
	v_mul_f32_e32 v111, 0x3fb8aa3b, v111
	v_exp_f32_e32 v111, v111
	v_add_f32_e32 v95, 1.0, v95
	v_rcp_f32_e32 v95, v95
	v_fma_f32 v113, -v111, v111, 1.0
	v_sqrt_f32_e32 v119, v113
	v_mov_b32_e32 v113, 1.0
	s_nop 1
	v_mov_b32_dpp v113, v111 row_shr:1 row_mask:0xf bank_mask:0xf
	v_pk_mul_f32 v[122:123], v[110:111], v[112:113]
	v_mov_b32_e32 v112, 1.0
	v_mov_b32_e32 v113, 1.0
	s_nop 0
	v_mov_b32_dpp v112, v122 row_shr:2 row_mask:0xf bank_mask:0xf
	v_mov_b32_dpp v113, v123 row_shr:2 row_mask:0xf bank_mask:0xf
	v_pk_mul_f32 v[126:127], v[122:123], v[112:113]
	v_mov_b32_e32 v112, 1.0
	v_mov_b32_e32 v113, 1.0
	s_nop 0
	v_mov_b32_dpp v112, v126 row_shr:4 row_mask:0xf bank_mask:0xf
	v_mov_b32_dpp v113, v127 row_shr:4 row_mask:0xf bank_mask:0xf
	v_pk_mul_f32 v[128:129], v[126:127], v[112:113]
	v_mov_b32_e32 v112, 1.0
	v_mov_b32_e32 v113, 1.0
	s_nop 0
	v_mov_b32_dpp v112, v128 row_shr:8 row_mask:0xf bank_mask:0xf
	v_mov_b32_dpp v113, v129 row_shr:8 row_mask:0xf bank_mask:0xf
	v_pk_mul_f32 v[130:131], v[128:129], v[112:113]
	v_add_u32_e32 v113, 0x10c0, v145
	ds_read2_b32 v[132:133], v113 offset1:1
	s_waitcnt lgkmcnt(0)
; __device__ __forceinline__ float sigmoidf_(float x) { return __builtin_amdgcn_rcpf(1.0f + __expf(-x)); }
; __device__ __forceinline__ float bcast15(float v, int lane) { return bperm_f((lane & 48) | 15, v); }
; __device__ __forceinline__ void w_lru_m1(const Args& a, int l, unsigned char* ws, const bf16_t* proj, bf16_t* y, LAS unsigned char* wl, int b, int ck_, int h, int lane) {
;     ...
;         for (int tb = 0; tb < 4; ++tb) { const int tok = 16 * tb + lo;
;             f32x4 ga = {0.f, 0.f, 0.f, 0.f}, gx = {0.f, 0.f, 0.f, 0.f};
; #pragma unroll
;             for (int kk = 0; kk < 2; ++kk) { ga = __builtin_amdgcn_mfma_f32_16x16x32_bf16(WaF[kk], Xf[tb][kk], ga, 0, 0, 0); gx = __builtin_amdgcn_mfma_f32_16x16x32_bf16(WxF[kk], Xf[tb][kk], gx, 0, 0, 0); }
;             float hv[4], pv[4];
; #pragma unroll
;             for (int r = 0; r < 4; ++r) {
;                 const float rg = sigmoidf_(ga[r] + bav[r]), ig = sigmoidf_(gx[r] + bxv[r]);
;                 const float la = -8.0f * rg * sp[r]; float A = __expf(la);
;                 float U = __builtin_amdgcn_sqrtf(1.0f - A * A) * (ig * xcf[tok * 65 + j0 + r]);
;                 { const float As = dpp_shr1<1>(A), Us = dpp_shr0<1>(U); U = A * Us + U; A = A * As; }
;                 { const float As = dpp_shr1<2>(A), Us = dpp_shr0<2>(U); U = A * Us + U; A = A * As; }
;                 { const float As = dpp_shr1<4>(A), Us = dpp_shr0<4>(U); U = A * Us + U; A = A * As; }
;                 { const float As = dpp_shr1<8>(A), Us = dpp_shr0<8>(U); U = A * Us + U; A = A * As; }
;                 const float hh = U + A * hc[r], PP = A * Pc[r];
;                 hc[r] = bcast15(hh, lane); Pc[r] = bcast15(PP, lane); hv[r] = hh; pv[r] = PP; }
	v_pk_mul_f32 v[88:89], v[130:131], v[88:89]
	ds_bpermute_b32 v112, v1, v88
	ds_bpermute_b32 v113, v1, v89
	v_cvt_pk_bf16_f32 v88, v88, v89
	v_pk_mul_f32 v[94:95], v[132:133], v[94:95]
	s_nop 0
	v_pk_mul_f32 v[94:95], v[94:95], v[118:119]
	s_nop 1
	v_mov_b32_dpp v118, v94 row_shr:1 row_mask:0xf bank_mask:0xf bound_ctrl:1
	v_mov_b32_dpp v119, v95 row_shr:1 row_mask:0xf bank_mask:0xf bound_ctrl:1
	v_pk_fma_f32 v[94:95], v[110:111], v[118:119], v[94:95]
	s_nop 1
	v_mov_b32_dpp v110, v94 row_shr:2 row_mask:0xf bank_mask:0xf bound_ctrl:1
	v_mov_b32_dpp v111, v95 row_shr:2 row_mask:0xf bank_mask:0xf bound_ctrl:1
	v_pk_fma_f32 v[94:95], v[122:123], v[110:111], v[94:95]
	v_mov_b32_e32 v122, 1.0
	v_mov_b32_e32 v123, 1.0
	v_mov_b32_dpp v110, v94 row_shr:4 row_mask:0xf bank_mask:0xf bound_ctrl:1
	v_mov_b32_dpp v111, v95 row_shr:4 row_mask:0xf bank_mask:0xf bound_ctrl:1
	v_pk_fma_f32 v[94:95], v[126:127], v[110:111], v[94:95]
	s_nop 1
	v_mov_b32_dpp v110, v94 row_shr:8 row_mask:0xf bank_mask:0xf bound_ctrl:1
	v_mov_b32_dpp v111, v95 row_shr:8 row_mask:0xf bank_mask:0xf bound_ctrl:1
	v_pk_fma_f32 v[94:95], v[128:129], v[110:111], v[94:95]
	s_nop 0
	v_pk_fma_f32 v[92:93], v[130:131], v[92:93], v[94:95]
	v_add_f32_e32 v94, v50, v124
	v_mul_f32_e32 v94, 0xbfb8aa3b, v94
	v_exp_f32_e32 v94, v94
	ds_bpermute_b32 v110, v1, v92
	ds_bpermute_b32 v111, v1, v93
	v_cvt_pk_bf16_f32 v92, v92, v93
	v_add_f32_e32 v94, 1.0, v94
	v_rcp_f32_e32 v95, v94
	v_add_f32_e32 v94, v46, v120
	v_mul_f32_e32 v94, 0xbfb8aa3b, v94
	v_exp_f32_e32 v94, v94
	v_mul_f32_e32 v95, 0xc1000000, v95
	v_mul_f32_e32 v95, v135, v95
	v_mul_f32_e32 v95, 0x3fb8aa3b, v95
	v_exp_f32_e32 v118, v95
	v_add_f32_e32 v94, 1.0, v94
	v_rcp_f32_e32 v94, v94
	v_fma_f32 v95, -v118, v118, 1.0
	v_sqrt_f32_e32 v120, v95
	v_add_f32_e32 v95, v51, v125
	v_mul_f32_e32 v95, 0xbfb8aa3b, v95
	v_exp_f32_e32 v95, v95
	v_mov_b32_dpp v122, v118 row_shr:1 row_mask:0xf bank_mask:0xf
	v_add_f32_e32 v95, 1.0, v95
	v_rcp_f32_e32 v119, v95
	v_add_f32_e32 v95, v47, v121
	v_mul_f32_e32 v95, 0xbfb8aa3b, v95
	v_exp_f32_e32 v95, v95
	v_mul_f32_e32 v119, 0xc1000000, v119
	v_mul_f32_e32 v119, v136, v119
	v_mul_f32_e32 v119, 0x3fb8aa3b, v119
	v_exp_f32_e32 v119, v119
	v_add_f32_e32 v95, 1.0, v95
	v_rcp_f32_e32 v95, v95
	v_mov_b32_dpp v123, v119 row_shr:1 row_mask:0xf bank_mask:0xf
	v_pk_mul_f32 v[124:125], v[118:119], v[122:123]
	v_mov_b32_e32 v122, 1.0
	v_mov_b32_e32 v123, 1.0
	v_fma_f32 v121, -v119, v119, 1.0
	v_mov_b32_dpp v122, v124 row_shr:2 row_mask:0xf bank_mask:0xf
	v_mov_b32_dpp v123, v125 row_shr:2 row_mask:0xf bank_mask:0xf
	v_pk_mul_f32 v[126:127], v[124:125], v[122:123]
	v_mov_b32_e32 v122, 1.0
	v_mov_b32_e32 v123, 1.0
	v_sqrt_f32_e32 v121, v121
	v_mov_b32_dpp v122, v126 row_shr:4 row_mask:0xf bank_mask:0xf
	v_mov_b32_dpp v123, v127 row_shr:4 row_mask:0xf bank_mask:0xf
	v_pk_mul_f32 v[128:129], v[126:127], v[122:123]
	v_mov_b32_e32 v122, 1.0
	v_mov_b32_e32 v123, 1.0
	s_nop 0
	v_mov_b32_dpp v122, v128 row_shr:8 row_mask:0xf bank_mask:0xf
	v_mov_b32_dpp v123, v129 row_shr:8 row_mask:0xf bank_mask:0xf
	v_pk_mul_f32 v[130:131], v[128:129], v[122:123]
	v_add_u32_e32 v123, 0x10c8, v145
	ds_read2_b32 v[132:133], v123 offset1:1
	v_pk_mul_f32 v[90:91], v[130:131], v[90:91]
	ds_bpermute_b32 v122, v1, v90
	v_cvt_pk_bf16_f32 v89, v90, v91
	ds_bpermute_b32 v123, v1, v91
	s_waitcnt lgkmcnt(0)
	v_pk_mul_f32 v[94:95], v[94:95], v[132:133]
	s_nop 0
	v_pk_mul_f32 v[94:95], v[120:121], v[94:95]
	s_nop 1
	v_mov_b32_dpp v120, v94 row_shr:1 row_mask:0xf bank_mask:0xf bound_ctrl:1
	v_mov_b32_dpp v121, v95 row_shr:1 row_mask:0xf bank_mask:0xf bound_ctrl:1
	v_pk_fma_f32 v[94:95], v[118:119], v[120:121], v[94:95]
	s_nop 1
	v_mov_b32_dpp v118, v94 row_shr:2 row_mask:0xf bank_mask:0xf bound_ctrl:1
	v_mov_b32_dpp v119, v95 row_shr:2 row_mask:0xf bank_mask:0xf bound_ctrl:1
	v_pk_fma_f32 v[94:95], v[124:125], v[118:119], v[94:95]
	s_nop 1
	v_mov_b32_dpp v118, v94 row_shr:4 row_mask:0xf bank_mask:0xf bound_ctrl:1
	v_mov_b32_dpp v119, v95 row_shr:4 row_mask:0xf bank_mask:0xf bound_ctrl:1
	v_pk_fma_f32 v[94:95], v[126:127], v[118:119], v[94:95]
	s_nop 1
	v_mov_b32_dpp v118, v94 row_shr:8 row_mask:0xf bank_mask:0xf bound_ctrl:1
	v_mov_b32_dpp v119, v95 row_shr:8 row_mask:0xf bank_mask:0xf bound_ctrl:1
	v_pk_fma_f32 v[94:95], v[128:129], v[118:119], v[94:95]
	v_mfma_f32_16x16x32_bf16 v[118:121], v[60:63], v[8:11], 0
	v_fma_f32 v94, v130, v108, v94
	v_fma_f32 v95, v131, v109, v95
	ds_bpermute_b32 v108, v1, v94
	v_cvt_pk_bf16_f32 v93, v94, v95
	v_mov_b64_e32 v[230:231], v[92:93]
	v_mov_b64_e32 v[234:235], v[88:89]
	v_mfma_f32_16x16x32_bf16 v[88:91], v[64:67], v[8:11], 0
	ds_bpermute_b32 v109, v1, v95
	v_mfma_f32_16x16x32_bf16 v[92:95], v[56:59], v[24:27], v[88:91]
	v_mfma_f32_16x16x32_bf16 v[88:91], v[52:55], v[24:27], v[118:121]
	v_mfma_f32_16x16x32_bf16 v[64:67], v[64:67], v[4:7], 0
	s_nop 5
	v_add_f32_e32 v92, v48, v92
	v_mul_f32_e32 v92, 0xbfb8aa3b, v92
	v_exp_f32_e32 v92, v92
	v_add_f32_e32 v88, v44, v88
	v_mul_f32_e32 v88, 0xbfb8aa3b, v88
	v_exp_f32_e32 v88, v88
	v_add_f32_e32 v92, 1.0, v92
	v_rcp_f32_e32 v92, v92
	v_add_f32_e32 v89, v45, v89
	v_add_f32_e32 v88, 1.0, v88
	v_rcp_f32_e32 v118, v88
	v_mul_f32_e32 v88, 0xc1000000, v92
	v_add_f32_e32 v92, v49, v93
	v_mul_f32_e32 v92, 0xbfb8aa3b, v92
	v_exp_f32_e32 v92, v92
	v_mul_f32_e32 v89, 0xbfb8aa3b, v89
	v_exp_f32_e32 v89, v89
	v_mul_f32_e32 v88, v2, v88
	v_add_f32_e32 v92, 1.0, v92
	v_rcp_f32_e32 v92, v92
	v_add_f32_e32 v89, 1.0, v89
	v_rcp_f32_e32 v119, v89
	v_mul_f32_e32 v88, 0x3fb8aa3b, v88
	v_mul_f32_e32 v89, 0xc1000000, v92
	v_mul_f32_e32 v89, v134, v89
	v_mul_f32_e32 v89, 0x3fb8aa3b, v89
; __device__ __forceinline__ float sigmoidf_(float x) { return __builtin_amdgcn_rcpf(1.0f + __expf(-x)); }
; __device__ __forceinline__ void w_lru_m1(const Args& a, int l, unsigned char* ws, const bf16_t* proj, bf16_t* y, LAS unsigned char* wl, int b, int ck_, int h, int lane) {
;     ...
;             for (int r = 0; r < 4; ++r) {
;                 const float rg = sigmoidf_(ga[r] + bav[r]), ig = sigmoidf_(gx[r] + bxv[r]);
;                 const float la = -8.0f * rg * sp[r]; float A = __expf(la);
;                 float U = __builtin_amdgcn_sqrtf(1.0f - A * A) * (ig * xcf[tok * 65 + j0 + r]);
;                 { const float As = dpp_shr1<1>(A), Us = dpp_shr0<1>(U); U = A * Us + U; A = A * As; }
;                 { const float As = dpp_shr1<2>(A), Us = dpp_shr0<2>(U); U = A * Us + U; A = A * As; }
;                 { const float As = dpp_shr1<4>(A), Us = dpp_shr0<4>(U); U = A * Us + U; A = A * As; }
;                 { const float As = dpp_shr1<8>(A), Us = dpp_shr0<8>(U); U = A * Us + U; A = A * As; }
;                 const float hh = U + A * hc[r], PP = A * Pc[r];
	v_exp_f32_e32 v120, v88
	v_exp_f32_e32 v121, v89
	v_mfma_f32_16x16x32_bf16 v[60:63], v[60:63], v[4:7], 0
	v_add_f32_e32 v94, v50, v94
	v_fma_f32 v88, -v120, v120, 1.0
	v_fma_f32 v89, -v121, v121, 1.0
	v_sqrt_f32_e32 v124, v88
	v_mov_b32_e32 v88, 1.0
	v_sqrt_f32_e32 v125, v89
	v_mov_b32_e32 v89, 1.0
	v_mov_b32_dpp v88, v120 row_shr:1 row_mask:0xf bank_mask:0xf
	v_mfma_f32_16x16x32_bf16 v[56:59], v[56:59], v[20:23], v[64:67]
	v_mov_b32_dpp v89, v121 row_shr:1 row_mask:0xf bank_mask:0xf
	v_pk_mul_f32 v[126:127], v[120:121], v[88:89]
	v_mov_b32_e32 v88, 1.0
	v_mov_b32_e32 v89, 1.0
	v_add_f32_e32 v95, v51, v95
	v_mov_b32_dpp v88, v126 row_shr:2 row_mask:0xf bank_mask:0xf
	v_mov_b32_dpp v89, v127 row_shr:2 row_mask:0xf bank_mask:0xf
	v_pk_mul_f32 v[128:129], v[126:127], v[88:89]
	v_mov_b32_e32 v88, 1.0
	v_mov_b32_e32 v89, 1.0
	v_mul_f32_e32 v94, 0xbfb8aa3b, v94
	v_mov_b32_dpp v88, v128 row_shr:4 row_mask:0xf bank_mask:0xf
	v_mov_b32_dpp v89, v129 row_shr:4 row_mask:0xf bank_mask:0xf
	v_pk_mul_f32 v[130:131], v[128:129], v[88:89]
	v_mov_b32_e32 v88, 1.0
	v_mov_b32_e32 v89, 1.0
	v_mul_f32_e32 v95, 0xbfb8aa3b, v95
	v_mov_b32_dpp v88, v130 row_shr:8 row_mask:0xf bank_mask:0xf
	v_mov_b32_dpp v89, v131 row_shr:8 row_mask:0xf bank_mask:0xf
	v_pk_mul_f32 v[132:133], v[130:131], v[88:89]
	v_add_u32_e32 v89, 0x2100, v145
	v_pk_mul_f32 v[92:93], v[132:133], v[112:113]
	ds_read2_b32 v[112:113], v89 offset1:1
	v_mfma_f32_16x16x32_bf16 v[60:63], v[52:55], v[20:23], v[60:63]
	v_add_f32_e32 v48, v48, v56
	v_exp_f32_e32 v94, v94
	v_exp_f32_e32 v95, v95
	s_waitcnt lgkmcnt(0)
	v_pk_mul_f32 v[112:113], v[112:113], v[118:119]
	v_mul_f32_e32 v48, 0xbfb8aa3b, v48
	v_pk_mul_f32 v[112:113], v[112:113], v[124:125]
	v_exp_f32_e32 v48, v48
	v_add_f32_e32 v90, v46, v90
	v_mov_b32_dpp v118, v112 row_shr:1 row_mask:0xf bank_mask:0xf bound_ctrl:1
	v_mov_b32_dpp v119, v113 row_shr:1 row_mask:0xf bank_mask:0xf bound_ctrl:1
	v_add_f32_e32 v91, v47, v91
	v_pk_fma_f32 v[112:113], v[120:121], v[118:119], v[112:113]
	v_mul_f32_e32 v90, 0xbfb8aa3b, v90
	v_mul_f32_e32 v91, 0xbfb8aa3b, v91
	v_add_f32_e32 v44, v44, v60
	v_mov_b32_dpp v118, v112 row_shr:2 row_mask:0xf bank_mask:0xf bound_ctrl:1
	v_mov_b32_dpp v119, v113 row_shr:2 row_mask:0xf bank_mask:0xf bound_ctrl:1
	v_add_f32_e32 v94, 1.0, v94
	v_exp_f32_e32 v90, v90
	v_add_f32_e32 v95, 1.0, v95
	v_exp_f32_e32 v91, v91
	v_mul_f32_e32 v44, 0xbfb8aa3b, v44
	v_pk_fma_f32 v[112:113], v[126:127], v[118:119], v[112:113]
	v_rcp_f32_e32 v94, v94
	v_rcp_f32_e32 v95, v95
	v_add_f32_e32 v48, 1.0, v48
	v_exp_f32_e32 v44, v44
	v_mov_b32_dpp v118, v112 row_shr:4 row_mask:0xf bank_mask:0xf bound_ctrl:1
	v_mov_b32_dpp v119, v113 row_shr:4 row_mask:0xf bank_mask:0xf bound_ctrl:1
	v_rcp_f32_e32 v52, v48
	v_pk_fma_f32 v[112:113], v[128:129], v[118:119], v[112:113]
	v_add_f32_e32 v90, 1.0, v90
	v_add_f32_e32 v91, 1.0, v91
	v_mov_b32_dpp v118, v112 row_shr:8 row_mask:0xf bank_mask:0xf bound_ctrl:1
	v_mov_b32_dpp v119, v113 row_shr:8 row_mask:0xf bank_mask:0xf bound_ctrl:1
	v_pk_fma_f32 v[112:113], v[130:131], v[118:119], v[112:113]
	v_rcp_f32_e32 v118, v90
	v_mul_f32_e32 v90, 0xc1000000, v94
	v_rcp_f32_e32 v119, v91
	v_mul_f32_e32 v91, 0xc1000000, v95
	v_add_f32_e32 v44, 1.0, v44
	v_mul_f32_e32 v90, v135, v90
	v_mul_f32_e32 v91, v136, v91
	v_rcp_f32_e32 v48, v44
	v_mul_f32_e32 v44, 0xc1000000, v52
	v_mul_f32_e32 v90, 0x3fb8aa3b, v90
	v_mul_f32_e32 v91, 0x3fb8aa3b, v91
	v_mul_f32_e32 v2, v2, v44
	v_exp_f32_e32 v94, v90
	v_exp_f32_e32 v95, v91
	v_mul_f32_e32 v2, 0x3fb8aa3b, v2
	v_exp_f32_e32 v54, v2
	v_fma_f32 v90, -v94, v94, 1.0
	v_fma_f32 v91, -v95, v95, 1.0
	v_sqrt_f32_e32 v120, v90
	v_mov_b32_e32 v90, 1.0
	v_sqrt_f32_e32 v121, v91
	v_mov_b32_e32 v91, 1.0
	v_fma_f32 v2, -v54, v54, 1.0
	v_mov_b32_dpp v90, v94 row_shr:1 row_mask:0xf bank_mask:0xf
	v_mov_b32_dpp v91, v95 row_shr:1 row_mask:0xf bank_mask:0xf
	v_sqrt_f32_e32 v56, v2
	v_add_f32_e32 v2, v49, v57
	v_pk_mul_f32 v[124:125], v[94:95], v[90:91]
	v_mov_b32_e32 v90, 1.0
	v_mov_b32_e32 v91, 1.0
	v_mul_f32_e32 v2, 0xbfb8aa3b, v2
	v_mov_b32_dpp v90, v124 row_shr:2 row_mask:0xf bank_mask:0xf
	v_mov_b32_dpp v91, v125 row_shr:2 row_mask:0xf bank_mask:0xf
	v_exp_f32_e32 v2, v2
	v_pk_mul_f32 v[126:127], v[124:125], v[90:91]
	v_mov_b32_e32 v90, 1.0
	v_mov_b32_e32 v91, 1.0
	v_add_f32_e32 v2, 1.0, v2
	v_mov_b32_dpp v90, v126 row_shr:4 row_mask:0xf bank_mask:0xf
	v_mov_b32_dpp v91, v127 row_shr:4 row_mask:0xf bank_mask:0xf
	v_pk_mul_f32 v[128:129], v[126:127], v[90:91]
	v_mov_b32_e32 v90, 1.0
	v_mov_b32_e32 v91, 1.0
	v_rcp_f32_e32 v2, v2
	v_mov_b32_dpp v90, v128 row_shr:8 row_mask:0xf bank_mask:0xf
	v_mov_b32_dpp v91, v129 row_shr:8 row_mask:0xf bank_mask:0xf
	v_pk_mul_f32 v[130:131], v[128:129], v[90:91]
	v_add_u32_e32 v91, 0x2108, v145
	v_pk_fma_f32 v[112:113], v[132:133], v[110:111], v[112:113]
	ds_read2_b32 v[132:133], v91 offset1:1
	v_add_f32_e32 v45, v45, v61
	v_mul_f32_e32 v45, 0xbfb8aa3b, v45
	v_mul_f32_e32 v2, 0xc1000000, v2
	v_exp_f32_e32 v45, v45
	v_mul_f32_e32 v2, v134, v2
	s_waitcnt lgkmcnt(0)
; __device__ __forceinline__ unsigned pk2(float lo, float hi) { const f32x2_t v = {lo, hi}; const bf16x2_t b = __builtin_convertvector(v, bf16x2_t); return __builtin_bit_cast(unsigned, b); }
; __device__ __forceinline__ float sigmoidf_(float x) { return __builtin_amdgcn_rcpf(1.0f + __expf(-x)); }
; __device__ __forceinline__ float bcast15(float v, int lane) { return bperm_f((lane & 48) | 15, v); }
; __device__ __forceinline__ void w_lru_m1(const Args& a, int l, unsigned char* ws, const bf16_t* proj, bf16_t* y, LAS unsigned char* wl, int b, int ck_, int h, int lane) {
;     ...
;             for (int r = 0; r < 4; ++r) {
;                 const float rg = sigmoidf_(ga[r] + bav[r]), ig = sigmoidf_(gx[r] + bxv[r]);
;                 const float la = -8.0f * rg * sp[r]; float A = __expf(la);
;                 float U = __builtin_amdgcn_sqrtf(1.0f - A * A) * (ig * xcf[tok * 65 + j0 + r]);
;                 { const float As = dpp_shr1<1>(A), Us = dpp_shr0<1>(U); U = A * Us + U; A = A * As; }
;                 { const float As = dpp_shr1<2>(A), Us = dpp_shr0<2>(U); U = A * Us + U; A = A * As; }
;                 { const float As = dpp_shr1<4>(A), Us = dpp_shr0<4>(U); U = A * Us + U; A = A * As; }
;                 { const float As = dpp_shr1<8>(A), Us = dpp_shr0<8>(U); U = A * Us + U; A = A * As; }
;                 const float hh = U + A * hc[r], PP = A * Pc[r];
;                 hc[r] = bcast15(hh, lane); Pc[r] = bcast15(PP, lane); hv[r] = hh; pv[r] = PP; }
;             *(unsigned long long*)(y + (size_t)(row0 + tok) * DM + 64 * h + j0) = (unsigned long long)pk2(hv[0], hv[1]) | ((unsigned long long)pk2(hv[2], hv[3]) << 32);
;             *(unsigned long long*)((bf16_t*)(ws + WS_P) + (size_t)(row0 + tok) * 512 + 64 * h + j0) = (unsigned long long)pk2(pv[0], pv[1]) | ((unsigned long long)pk2(pv[2], pv[3]) << 32);
;         }
;         if (lo == 0) { const size_t so = (size_t)(b * NCH + ck_) * 512 + 64 * h + j0;
	v_pk_mul_f32 v[118:119], v[118:119], v[132:133]
	v_mul_f32_e32 v2, 0x3fb8aa3b, v2
	v_pk_mul_f32 v[118:119], v[120:121], v[118:119]
	v_exp_f32_e32 v55, v2
	v_add_f32_e32 v45, 1.0, v45
	v_mov_b32_dpp v120, v118 row_shr:1 row_mask:0xf bank_mask:0xf bound_ctrl:1
	v_mov_b32_dpp v121, v119 row_shr:1 row_mask:0xf bank_mask:0xf bound_ctrl:1
	v_pk_fma_f32 v[94:95], v[94:95], v[120:121], v[118:119]
	v_mov_b32_e32 v44, 1.0
	v_rcp_f32_e32 v49, v45
	v_mov_b32_dpp v118, v94 row_shr:2 row_mask:0xf bank_mask:0xf bound_ctrl:1
	v_mov_b32_dpp v119, v95 row_shr:2 row_mask:0xf bank_mask:0xf bound_ctrl:1
	v_mov_b32_e32 v45, 1.0
	v_pk_fma_f32 v[94:95], v[124:125], v[118:119], v[94:95]
	v_mov_b32_dpp v44, v54 row_shr:1 row_mask:0xf bank_mask:0xf
	v_mov_b32_dpp v45, v55 row_shr:1 row_mask:0xf bank_mask:0xf
	v_mov_b32_dpp v118, v94 row_shr:4 row_mask:0xf bank_mask:0xf bound_ctrl:1
	v_mov_b32_dpp v119, v95 row_shr:4 row_mask:0xf bank_mask:0xf bound_ctrl:1
	v_pk_mul_f32 v[60:61], v[54:55], v[44:45]
	v_mov_b32_e32 v44, 1.0
	v_mov_b32_e32 v45, 1.0
	v_pk_fma_f32 v[94:95], v[126:127], v[118:119], v[94:95]
	v_mov_b32_dpp v44, v60 row_shr:2 row_mask:0xf bank_mask:0xf
	v_mov_b32_dpp v45, v61 row_shr:2 row_mask:0xf bank_mask:0xf
	ds_bpermute_b32 v88, v1, v92
	ds_bpermute_b32 v89, v1, v93
	v_mov_b32_dpp v118, v94 row_shr:8 row_mask:0xf bank_mask:0xf bound_ctrl:1
	v_mov_b32_dpp v119, v95 row_shr:8 row_mask:0xf bank_mask:0xf bound_ctrl:1
	v_pk_mul_f32 v[64:65], v[60:61], v[44:45]
	v_mov_b32_e32 v44, 1.0
	v_mov_b32_e32 v45, 1.0
	v_pk_fma_f32 v[94:95], v[128:129], v[118:119], v[94:95]
	v_mov_b32_dpp v44, v64 row_shr:4 row_mask:0xf bank_mask:0xf
	v_mov_b32_dpp v45, v65 row_shr:4 row_mask:0xf bank_mask:0xf
	v_pk_mul_f32 v[122:123], v[130:131], v[122:123]
	v_pk_fma_f32 v[108:109], v[130:131], v[108:109], v[94:95]
	v_pk_mul_f32 v[66:67], v[64:65], v[44:45]
	v_mov_b32_e32 v44, 1.0
	v_mov_b32_e32 v45, 1.0
	ds_bpermute_b32 v110, v1, v112
	ds_bpermute_b32 v111, v1, v113
	v_cvt_pk_bf16_f32 v112, v112, v113
	v_cvt_pk_bf16_f32 v113, v108, v109
	v_cvt_pk_bf16_f32 v92, v92, v93
	v_cvt_pk_bf16_f32 v93, v122, v123
	v_fma_f32 v2, -v55, v55, 1.0
	v_mov_b32_dpp v44, v66 row_shr:8 row_mask:0xf bank_mask:0xf
	v_mov_b32_dpp v45, v67 row_shr:8 row_mask:0xf bank_mask:0xf
	v_mov_b64_e32 v[238:239], v[112:113]
	v_mov_b64_e32 v[242:243], v[92:93]
	v_sqrt_f32_e32 v57, v2
	v_pk_mul_f32 v[92:93], v[66:67], v[44:45]
	v_add_u32_e32 v2, 0x3140, v145
	s_waitcnt lgkmcnt(0)
	v_pk_mul_f32 v[52:53], v[92:93], v[88:89]
	ds_read2_b32 v[88:89], v2 offset1:1
	v_add_f32_e32 v2, v50, v58
	v_mul_f32_e32 v2, 0xbfb8aa3b, v2
	v_exp_f32_e32 v2, v2
	v_add_f32_e32 v46, v46, v62
	v_add_f32_e32 v47, v47, v63
	v_mul_f32_e32 v46, 0xbfb8aa3b, v46
	v_add_f32_e32 v2, 1.0, v2
	v_rcp_f32_e32 v2, v2
	v_mul_f32_e32 v47, 0xbfb8aa3b, v47
	v_exp_f32_e32 v46, v46
	v_exp_f32_e32 v47, v47
	v_mul_f32_e32 v2, 0xc1000000, v2
	v_mul_f32_e32 v2, v135, v2
	v_mul_f32_e32 v2, 0x3fb8aa3b, v2
	v_exp_f32_e32 v50, v2
	s_waitcnt lgkmcnt(0)
	v_pk_mul_f32 v[48:49], v[88:89], v[48:49]
	v_add_f32_e32 v46, 1.0, v46
	v_pk_mul_f32 v[48:49], v[48:49], v[56:57]
	v_fma_f32 v2, -v50, v50, 1.0
	v_sqrt_f32_e32 v58, v2
	v_add_f32_e32 v2, v51, v59
	v_mul_f32_e32 v2, 0xbfb8aa3b, v2
	v_exp_f32_e32 v2, v2
	v_mov_b32_dpp v56, v48 row_shr:1 row_mask:0xf bank_mask:0xf bound_ctrl:1
	v_mov_b32_dpp v57, v49 row_shr:1 row_mask:0xf bank_mask:0xf bound_ctrl:1
	v_add_f32_e32 v47, 1.0, v47
	v_add_f32_e32 v2, 1.0, v2
	v_rcp_f32_e32 v2, v2
	v_pk_fma_f32 v[48:49], v[54:55], v[56:57], v[48:49]
	v_rcp_f32_e32 v56, v46
	v_mov_b32_e32 v46, 1.0
	v_mul_f32_e32 v2, 0xc1000000, v2
	v_mul_f32_e32 v2, v136, v2
	v_mul_f32_e32 v2, 0x3fb8aa3b, v2
	v_exp_f32_e32 v51, v2
	v_rcp_f32_e32 v57, v47
	v_mov_b32_e32 v47, 1.0
	v_mov_b32_dpp v54, v48 row_shr:2 row_mask:0xf bank_mask:0xf bound_ctrl:1
	v_mov_b32_dpp v55, v49 row_shr:2 row_mask:0xf bank_mask:0xf bound_ctrl:1
	v_mov_b32_dpp v46, v50 row_shr:1 row_mask:0xf bank_mask:0xf
	v_mov_b32_dpp v47, v51 row_shr:1 row_mask:0xf bank_mask:0xf
	v_pk_fma_f32 v[48:49], v[60:61], v[54:55], v[48:49]
	v_pk_mul_f32 v[62:63], v[50:51], v[46:47]
	v_mov_b32_e32 v46, 1.0
	v_mov_b32_e32 v47, 1.0
	v_mov_b32_dpp v54, v48 row_shr:4 row_mask:0xf bank_mask:0xf bound_ctrl:1
	v_mov_b32_dpp v55, v49 row_shr:4 row_mask:0xf bank_mask:0xf bound_ctrl:1
	v_mov_b32_dpp v46, v62 row_shr:2 row_mask:0xf bank_mask:0xf
	v_mov_b32_dpp v47, v63 row_shr:2 row_mask:0xf bank_mask:0xf
	ds_bpermute_b32 v90, v1, v122
	ds_bpermute_b32 v91, v1, v123
	v_pk_fma_f32 v[48:49], v[64:65], v[54:55], v[48:49]
	v_pk_mul_f32 v[64:65], v[62:63], v[46:47]
	v_mov_b32_e32 v46, 1.0
	v_mov_b32_e32 v47, 1.0
	v_mov_b32_dpp v54, v48 row_shr:8 row_mask:0xf bank_mask:0xf bound_ctrl:1
	v_mov_b32_dpp v55, v49 row_shr:8 row_mask:0xf bank_mask:0xf bound_ctrl:1
	v_mov_b32_dpp v46, v64 row_shr:4 row_mask:0xf bank_mask:0xf
	v_mov_b32_dpp v47, v65 row_shr:4 row_mask:0xf bank_mask:0xf
	v_pk_fma_f32 v[48:49], v[66:67], v[54:55], v[48:49]
	v_pk_mul_f32 v[66:67], v[64:65], v[46:47]
	v_mov_b32_e32 v46, 1.0
	v_mov_b32_e32 v47, 1.0
	v_fma_f32 v2, -v51, v51, 1.0
	v_mov_b32_dpp v46, v66 row_shr:8 row_mask:0xf bank_mask:0xf
	v_mov_b32_dpp v47, v67 row_shr:8 row_mask:0xf bank_mask:0xf
	v_sqrt_f32_e32 v59, v2
	v_pk_mul_f32 v[88:89], v[66:67], v[46:47]
	v_add_u32_e32 v2, 0x3148, v145
	s_waitcnt lgkmcnt(0)
	v_pk_mul_f32 v[60:61], v[88:89], v[90:91]
	ds_read2_b32 v[90:91], v2 offset1:1
	ds_bpermute_b32 v94, v1, v108
	ds_bpermute_b32 v95, v1, v109
	v_pk_fma_f32 v[54:55], v[92:93], v[110:111], v[48:49]
	ds_bpermute_b32 v44, v1, v52
	s_waitcnt lgkmcnt(0)
	v_pk_mul_f32 v[56:57], v[56:57], v[90:91]
	ds_bpermute_b32 v48, v1, v54
	v_pk_mul_f32 v[56:57], v[58:59], v[56:57]
	ds_bpermute_b32 v49, v1, v55
	ds_bpermute_b32 v45, v1, v53
	v_mov_b32_dpp v58, v56 row_shr:1 row_mask:0xf bank_mask:0xf bound_ctrl:1
	v_mov_b32_dpp v59, v57 row_shr:1 row_mask:0xf bank_mask:0xf bound_ctrl:1
	v_pk_fma_f32 v[50:51], v[50:51], v[58:59], v[56:57]
	ds_bpermute_b32 v46, v1, v60
	ds_bpermute_b32 v47, v1, v61
	v_mov_b32_dpp v56, v50 row_shr:2 row_mask:0xf bank_mask:0xf bound_ctrl:1
	v_mov_b32_dpp v57, v51 row_shr:2 row_mask:0xf bank_mask:0xf bound_ctrl:1
	v_pk_fma_f32 v[50:51], v[62:63], v[56:57], v[50:51]
	v_cvt_pk_bf16_f32 v54, v54, v55
	v_cvt_pk_bf16_f32 v52, v52, v53
	v_mov_b32_dpp v56, v50 row_shr:4 row_mask:0xf bank_mask:0xf bound_ctrl:1
	v_mov_b32_dpp v57, v51 row_shr:4 row_mask:0xf bank_mask:0xf bound_ctrl:1
	v_pk_fma_f32 v[50:51], v[64:65], v[56:57], v[50:51]
	v_cvt_pk_bf16_f32 v53, v60, v61
	s_nop 0
	v_mov_b32_dpp v56, v50 row_shr:8 row_mask:0xf bank_mask:0xf bound_ctrl:1
	v_mov_b32_dpp v57, v51 row_shr:8 row_mask:0xf bank_mask:0xf bound_ctrl:1
	v_pk_fma_f32 v[50:51], v[66:67], v[56:57], v[50:51]
	s_nop 0
	v_pk_fma_f32 v[56:57], v[88:89], v[94:95], v[50:51]
	ds_bpermute_b32 v50, v1, v56
	ds_bpermute_b32 v51, v1, v57
	v_cvt_pk_bf16_f32 v55, v56, v57
	v_mov_b64_e32 v[246:247], v[54:55]
	v_mov_b64_e32 v[250:251], v[52:53]
	s_and_saveexec_b64 s[34:35], vcc
	s_cbranch_execz .LBB0_527
; __device__ __forceinline__ void w_lru_m1(const Args& a, int l, unsigned char* ws, const bf16_t* proj, bf16_t* y, LAS unsigned char* wl, int b, int ck_, int h, int lane) {
;     ...
;         if (lo == 0) { const size_t so = (size_t)(b * NCH + ck_) * 512 + 64 * h + j0;
; #pragma unroll
;             for (int r = 0; r < 4; ++r) { ((float*)(ws + WS_LRUA))[so + r] = Pc[r]; ((float*)(ws + WS_LRUH))[so + r] = hc[r]; } }
	v_add_u32_e32 v52, 32, v0
	v_ashrrev_i32_e32 v53, 31, v52
	v_lshl_add_u64 v[52:53], s[42:43], 0, v[52:53]
	v_lshlrev_b64 v[52:53], 2, v[52:53]
	v_lshl_add_u64 v[54:55], s[84:85], 0, v[52:53]
	v_lshl_add_u64 v[52:53], s[86:87], 0, v[52:53]
	s_waitcnt lgkmcnt(0)
	global_store_dwordx4 v[54:55], v[44:47], off
	global_store_dwordx4 v[52:53], v[48:51], off

; __device__ __forceinline__ unsigned f2bf(float f) { return pk2(f, f) & 0xffffu; }
; __device__ __forceinline__ void p0_prologue(const Args& a, unsigned char* ws, LAS unsigned char* lds, const int tid) {
;     ...
;         for (int idx = gt; idx < 2 * 2 * 8 * 4096; idx += NT) { const int i = idx & 63, jj = (idx >> 6) & 63, h = (idx >> 12) & 7, ax = (idx >> 15) & 1, l = idx >> 16;
;             const float* src = (ax ? wx_ : wa_) + (size_t)l * 8 * 4096 + h * 4096 + i * 64 + jj; gw_[idx] = (bf16_t)f2bf(*src); }
.LBB0_878:
	v_ashrrev_i32_e32 v12, 16, v4
	v_and_b32_e32 v11, 0x8000, v5
	v_and_b32_e32 v13, 0x8000, v4
	v_ashrrev_i32_e32 v10, 16, v5
	v_mov_b32_e32 v15, s21
	v_mov_b32_e32 v16, s5
	v_mov_b32_e32 v17, s11
	v_mov_b32_e32 v20, s9
	v_mov_b32_e32 v21, s10
	v_mov_b32_e32 v22, s8
	v_cmp_eq_u32_e32 vcc, 0, v11
	v_cmp_eq_u32_e64 s[38:39], 0, v13
	v_ashrrev_i32_e32 v13, 31, v12
	v_lshrrev_b32_e32 v2, 6, v4
	v_and_b32_e32 v14, 0x7000, v4
	v_mov_b32_e32 v18, s20
	v_mov_b32_e32 v19, s3
	v_cndmask_b32_e32 v15, v15, v16, vcc
	v_cndmask_b32_e64 v17, v17, v20, s[38:39]
	v_ashrrev_i32_e32 v11, 31, v10
	v_cndmask_b32_e64 v16, v21, v22, s[38:39]
	v_lshlrev_b64 v[12:13], 17, v[12:13]
	v_and_b32_e32 v9, 0x7000, v5
	v_lshlrev_b32_e32 v23, 6, v5
	v_lshlrev_b32_e32 v24, 6, v4
	v_and_b32_e32 v25, 63, v2
	v_lshlrev_b32_e32 v2, 2, v14
	v_cndmask_b32_e32 v14, v18, v19, vcc
	v_lshlrev_b64 v[10:11], 17, v[10:11]
	v_lshl_add_u64 v[12:13], v[16:17], 0, v[12:13]
	v_and_b32_e32 v20, 0xfc0, v23
	v_and_b32_e32 v23, 0xfc0, v24
	v_lshl_add_u64 v[10:11], v[14:15], 0, v[10:11]
	v_lshl_add_u64 v[12:13], v[12:13], 0, v[2:3]
	v_lshlrev_b32_e32 v2, 2, v9
	v_lshl_add_u64 v[10:11], v[10:11], 0, v[2:3]
	v_lshlrev_b32_e32 v2, 2, v23
	v_lshrrev_b32_e32 v1, 6, v5
	v_lshl_add_u64 v[12:13], v[12:13], 0, v[2:3]
	v_lshlrev_b32_e32 v2, 2, v20
	v_and_b32_e32 v1, 63, v1
	v_lshl_add_u64 v[10:11], v[10:11], 0, v[2:3]
	v_lshlrev_b32_e32 v2, 2, v25
	v_lshl_add_u64 v[12:13], v[12:13], 0, v[2:3]
	v_lshlrev_b32_e32 v2, 2, v1
	v_lshl_add_u64 v[10:11], v[10:11], 0, v[2:3]
	global_load_dword v1, v[12:13], off
	global_load_dword v2, v[10:11], off
	v_add_u32_e32 v8, -2, v8
	v_ashrrev_i32_e32 v13, 31, v4
	v_and_b32_e32 v12, 0xfffffc07, v4
	v_bfe_u32 v151, v4, 5, 1
	v_lshl_or_b32 v12, v151, 9, v12
	v_bfe_u32 v151, v4, 3, 2
	v_lshl_or_b32 v12, v151, 7, v12
	v_bfe_u32 v151, v4, 6, 4
	v_lshl_or_b32 v12, v151, 3, v12
	v_cmp_eq_u32_e32 vcc, 0, v8
	v_ashrrev_i32_e32 v11, 31, v5
	v_and_b32_e32 v10, 0xfffffc07, v5
	v_bfe_u32 v151, v5, 5, 1
	v_lshl_or_b32 v10, v151, 9, v10
	v_bfe_u32 v151, v5, 3, 2
	v_lshl_or_b32 v10, v151, 7, v10
	v_bfe_u32 v151, v5, 6, 4
	v_lshl_or_b32 v10, v151, 3, v10
	v_add_u32_e32 v5, s27, v5
	v_add_u32_e32 v4, s24, v4
	v_lshl_add_u64 v[12:13], v[12:13], 1, s[14:15]
	s_or_b64 s[34:35], vcc, s[34:35]
	v_lshl_add_u64 v[10:11], v[10:11], 1, s[14:15]
	s_waitcnt vmcnt(0)
	v_cvt_pk_bf16_f32 v1, v1, v2
	flat_store_short v[12:13], v1
	flat_store_short_d16_hi v[10:11], v1
	s_andn2_b64 exec, exec, s[34:35]
	s_cbranch_execnz .LBB0_878
	s_or_b64 exec, exec, s[34:35]
	v_cmp_ne_u32_e32 vcc, v6, v7
	v_mad_u64_u32 v[0:1], s[20:21], v7, s4, v[0:1]
	s_orn2_b64 s[34:35], vcc, exec

; __device__ __forceinline__ unsigned f2bf(float f) { return pk2(f, f) & 0xffffu; }
; __device__ __forceinline__ void p0_prologue(const Args& a, unsigned char* ws, LAS unsigned char* lds, const int tid) {
;     ...
;         for (int idx = gt; idx < 2 * 2 * 8 * 4096; idx += NT) { const int i = idx & 63, jj = (idx >> 6) & 63, h = (idx >> 12) & 7, ax = (idx >> 15) & 1, l = idx >> 16;
;             const float* src = (ax ? wx_ : wa_) + (size_t)l * 8 * 4096 + h * 4096 + i * 64 + jj; gw_[idx] = (bf16_t)f2bf(*src); }
.LBB0_882:
	v_ashrrev_i32_e32 v6, 16, v0
	v_and_b32_e32 v7, 0x8000, v0
	s_waitcnt lgkmcnt(0)
	v_mov_b32_e32 v8, s11
	v_mov_b32_e32 v9, s9
	v_mov_b32_e32 v10, s10
	v_mov_b32_e32 v11, s8
	v_cmp_eq_u32_e32 vcc, 0, v7
	v_ashrrev_i32_e32 v7, 31, v6
	v_and_b32_e32 v2, 0x7000, v0
	v_cndmask_b32_e32 v9, v8, v9, vcc
	v_cndmask_b32_e32 v8, v10, v11, vcc
	v_lshlrev_b64 v[6:7], 17, v[6:7]
	v_and_b32_e32 v12, 0xfc0, v1
	v_lshlrev_b32_e32 v2, 2, v2
	v_lshl_add_u64 v[6:7], v[8:9], 0, v[6:7]
	v_lshrrev_b32_e32 v13, 4, v0
	v_lshl_add_u64 v[6:7], v[6:7], 0, v[2:3]
	v_lshlrev_b32_e32 v2, 2, v12
	v_lshl_add_u64 v[6:7], v[6:7], 0, v[2:3]
	v_and_b32_e32 v2, 0xfc, v13
	v_lshl_add_u64 v[6:7], v[6:7], 0, v[2:3]
	global_load_dword v2, v[6:7], off
	v_and_b32_e32 v150, 0xfffffc07, v0
	v_bfe_u32 v151, v0, 5, 1
	v_lshl_or_b32 v150, v151, 9, v150
	v_bfe_u32 v151, v0, 3, 2
	v_lshl_or_b32 v150, v151, 7, v150
	v_bfe_u32 v151, v0, 6, 4
	v_lshl_or_b32 v150, v151, 3, v150
	v_sub_u32_e32 v150, v150, v0
	v_ashrrev_i32_e32 v151, 31, v150
	v_lshl_add_u64 v[150:151], v[150:151], 1, v[4:5]
	v_add_u32_e32 v0, s4, v0
	s_mov_b32 s3, 0x1ffff
	v_cmp_lt_i32_e32 vcc, s3, v0
	v_add_u32_e32 v1, s2, v1
	s_or_b64 s[18:19], vcc, s[18:19]
	s_waitcnt vmcnt(0)
	v_cvt_pk_bf16_f32 v2, v2, s0
	flat_store_short v[150:151], v2
	v_lshl_add_u64 v[4:5], v[4:5], 0, s[14:15]
	s_andn2_b64 exec, exec, s[18:19]
	s_cbranch_execnz .LBB0_882
